# in_proj K-loop LDS read software pipelining; s5 gemm ks batching; E task reorder; ssd_p1 load batching; W_out transpose de-serialized
# speedup vs baseline: 1.1037x; 1.0244x over previous
.LBB0_174:
	s_sub_i32 s98, s20, s19
	s_cmp_lt_i32 s98, 0
	s_cbranch_scc1 .Lremap_e_done
	s_movk_i32 s99, 0x880
	s_cmpk_lt_i32 s98, 0x220
	s_cselect_b32 s99, s99, 0xfffffde0
	s_add_i32 s20, s20, s99

.LBB0_325:
	v_lshl_add_u64 v[158:159], v[78:79], 0, s[4:5]
	v_add_co_u32_e32 v130, vcc, s7, v158
	v_lshl_add_u64 v[162:163], v[80:81], 0, s[4:5]
	s_nop 0
	v_addc_co_u32_e32 v134, vcc, 0, v159, vcc
	v_add_co_u32_e32 v137, vcc, s7, v162
	s_cmp_lt_u32 s3, 8
	s_nop 0
	v_addc_co_u32_e32 v158, vcc, 0, v163, vcc
	v_lshl_add_u64 v[162:163], v[82:83], 0, s[4:5]
	v_add_co_u32_e32 v159, vcc, s7, v162
	v_lshl_add_u64 v[164:165], v[86:87], 0, s[4:5]
	s_nop 0
	v_addc_co_u32_e32 v160, vcc, 0, v163, vcc
	v_lshl_add_u64 v[162:163], v[84:85], 0, s[4:5]
	v_add_co_u32_e32 v166, vcc, s7, v162
	s_nop 1
	v_addc_co_u32_e32 v168, vcc, 0, v163, vcc
	v_lshl_add_u64 v[162:163], v[76:77], 0, s[4:5]
	s_cselect_b64 vcc, -1, 0
	v_lshl_add_u64 v[170:171], v[74:75], 0, s[4:5]
	v_lshl_add_u64 v[174:175], v[88:89], 0, s[4:5]
	v_lshl_add_u64 v[176:177], v[72:73], 0, s[4:5]
	v_lshl_add_u64 v[180:181], v[90:91], 0, s[4:5]
	v_lshl_add_u64 v[182:183], v[70:71], 0, s[4:5]
	v_lshl_add_u64 v[184:185], v[92:93], 0, s[4:5]
	v_lshl_add_u64 v[186:187], v[162:163], 0, s[10:11]
	v_lshl_add_u64 v[162:163], v[164:165], 0, s[16:17]
	v_lshl_add_u64 v[164:165], v[184:185], 0, s[16:17]
	v_cndmask_b32_e32 v169, v163, v187, vcc
	v_cndmask_b32_e32 v172, v162, v186, vcc
	v_mov_b32_e32 v162, v130
	v_mov_b32_e32 v163, v134
	global_load_dwordx4 v[184:187], v[162:163], off offset:320
	v_mov_b32_e32 v162, v137
	v_mov_b32_e32 v163, v158
	global_load_dwordx4 v[188:191], v[162:163], off offset:320
	v_mov_b32_e32 v162, v159
	v_mov_b32_e32 v163, v160
	global_load_dwordx4 v[192:195], v[162:163], off offset:320
	v_mov_b32_e32 v158, v166
	v_mov_b32_e32 v159, v168
	global_load_dwordx4 v[212:215], v[158:159], off offset:320
	v_lshl_add_u64 v[158:159], v[170:171], 0, s[10:11]
	v_lshl_add_u64 v[162:163], v[174:175], 0, s[16:17]
	v_lshl_add_u64 v[170:171], v[176:177], 0, s[10:11]
	v_lshl_add_u64 v[174:175], v[180:181], 0, s[16:17]
	v_lshl_add_u64 v[176:177], v[182:183], 0, s[10:11]
	v_cndmask_b32_e32 v130, v163, v159, vcc
	v_cndmask_b32_e32 v134, v162, v158, vcc
	v_cndmask_b32_e32 v137, v175, v171, vcc
	v_cndmask_b32_e32 v158, v174, v170, vcc
	v_cndmask_b32_e32 v159, v165, v177, vcc
	v_cndmask_b32_e32 v160, v164, v176, vcc
	v_mov_b32_e32 v162, v172
	v_mov_b32_e32 v163, v169
	global_load_dwordx4 v[174:177], v[162:163], off
	v_mov_b32_e32 v162, v134
	v_mov_b32_e32 v163, v130
	global_load_dwordx4 v[168:171], v[162:163], off
	v_mov_b32_e32 v162, v158
	v_mov_b32_e32 v163, v137
	global_load_dwordx4 v[180:183], v[162:163], off
	v_mov_b32_e32 v162, v160
	v_mov_b32_e32 v163, v159
	global_load_dwordx4 v[218:221], v[162:163], off
	v_lshl_add_u64 v[66:67], v[78:79], 0, s[4:5]
	v_add_co_u32_e32 v116, vcc, s7, v66
	v_lshl_add_u64 v[94:95], v[80:81], 0, s[4:5]
	s_nop 0
	v_addc_co_u32_e32 v117, vcc, 0, v67, vcc
	v_add_co_u32_e32 v114, vcc, s7, v94
	s_cmp_lt_u32 s3, 8
	s_nop 0
	v_addc_co_u32_e32 v115, vcc, 0, v95, vcc
	v_lshl_add_u64 v[94:95], v[82:83], 0, s[4:5]
	v_add_co_u32_e32 v98, vcc, s7, v94
	v_lshl_add_u64 v[96:97], v[86:87], 0, s[4:5]
	s_nop 0
	v_addc_co_u32_e32 v99, vcc, 0, v95, vcc
	v_lshl_add_u64 v[94:95], v[84:85], 0, s[4:5]
	v_add_co_u32_e32 v102, vcc, s7, v94
	v_lshl_add_u64 v[104:105], v[96:97], 0, s[8:9]
	s_nop 0
	v_addc_co_u32_e32 v103, vcc, 0, v95, vcc
	v_lshl_add_u64 v[94:95], v[76:77], 0, s[4:5]
	s_cselect_b64 vcc, -1, 0
	v_lshl_add_u64 v[100:101], v[94:95], 0, s[0:1]
	v_cndmask_b32_e32 v101, v105, v101, vcc
	v_cndmask_b32_e32 v100, v104, v100, vcc
	global_load_dwordx4 v[142:145], v[100:101], off
	v_lshl_add_u64 v[100:101], v[74:75], 0, s[4:5]
	v_lshl_add_u64 v[104:105], v[88:89], 0, s[4:5]
	v_lshl_add_u64 v[106:107], v[100:101], 0, s[0:1]
	v_lshl_add_u64 v[108:109], v[104:105], 0, s[8:9]
	v_cndmask_b32_e32 v107, v109, v107, vcc
	v_cndmask_b32_e32 v106, v108, v106, vcc
	global_load_dwordx4 v[146:149], v[106:107], off
	v_lshl_add_u64 v[106:107], v[72:73], 0, s[4:5]
	v_lshl_add_u64 v[110:111], v[90:91], 0, s[4:5]
	v_lshl_add_u64 v[108:109], v[106:107], 0, s[0:1]
	v_lshl_add_u64 v[112:113], v[110:111], 0, s[8:9]
	global_load_dwordx4 v[66:69], v[116:117], off offset:256
	global_load_dwordx4 v[120:123], v[114:115], off offset:256
	global_load_dwordx4 v[124:127], v[98:99], off offset:256
	v_cndmask_b32_e32 v109, v113, v109, vcc
	v_cndmask_b32_e32 v108, v112, v108, vcc
	global_load_dwordx4 v[150:153], v[108:109], off
	v_lshl_add_u64 v[112:113], v[70:71], 0, s[4:5]
	v_lshl_add_u64 v[108:109], v[92:93], 0, s[4:5]
	v_lshl_add_u64 v[128:129], v[112:113], 0, s[0:1]
	v_lshl_add_u64 v[154:155], v[108:109], 0, s[8:9]
	v_cndmask_b32_e32 v129, v155, v129, vcc
	v_cndmask_b32_e32 v128, v154, v128, vcc
	global_load_dwordx4 v[154:157], v[128:129], off
	global_load_dwordx4 v[138:141], v[102:103], off offset:256
	v_lshl_add_u64 v[94:95], v[94:95], 0, s[10:11]
	v_lshl_add_u64 v[96:97], v[96:97], 0, s[16:17]
	v_lshl_add_u64 v[108:109], v[108:109], 0, s[16:17]
	v_cndmask_b32_e32 v95, v97, v95, vcc
	v_cndmask_b32_e32 v94, v96, v94, vcc
	s_add_i32 s3, s3, 2
	s_add_u32 s4, s4, 0x80
	s_addc_u32 s5, s5, 0
	s_cmpk_lg_i32 s4, 0x400
	s_waitcnt vmcnt(5)
	v_mfma_f32_16x16x32_bf16 v[62:65], v[66:69], v[142:145], v[62:65]
	v_mfma_f32_16x16x32_bf16 v[58:61], v[66:69], v[146:149], v[58:61]
	s_waitcnt vmcnt(2)
	v_mfma_f32_16x16x32_bf16 v[54:57], v[66:69], v[150:153], v[54:57]
	s_waitcnt vmcnt(1)
	v_mfma_f32_16x16x32_bf16 v[50:53], v[66:69], v[154:157], v[50:53]
	v_mfma_f32_16x16x32_bf16 v[46:49], v[120:123], v[142:145], v[46:49]
	v_mfma_f32_16x16x32_bf16 v[42:45], v[120:123], v[146:149], v[42:45]
	v_mfma_f32_16x16x32_bf16 v[38:41], v[120:123], v[150:153], v[38:41]
	v_mfma_f32_16x16x32_bf16 v[34:37], v[120:123], v[154:157], v[34:37]
	v_mfma_f32_16x16x32_bf16 v[30:33], v[124:127], v[142:145], v[30:33]
	v_mfma_f32_16x16x32_bf16 v[26:29], v[124:127], v[146:149], v[26:29]
	v_mfma_f32_16x16x32_bf16 v[22:25], v[124:127], v[150:153], v[22:25]
	v_mfma_f32_16x16x32_bf16 v[18:21], v[124:127], v[154:157], v[18:21]
	s_nop 0
	s_nop 0
	v_lshl_add_u64 v[98:99], v[100:101], 0, s[10:11]
	v_lshl_add_u64 v[100:101], v[104:105], 0, s[16:17]
	v_lshl_add_u64 v[102:103], v[106:107], 0, s[10:11]
	v_lshl_add_u64 v[104:105], v[110:111], 0, s[16:17]
	v_lshl_add_u64 v[106:107], v[112:113], 0, s[10:11]
	v_cndmask_b32_e32 v99, v101, v99, vcc
	v_cndmask_b32_e32 v98, v100, v98, vcc
	v_cndmask_b32_e32 v103, v105, v103, vcc
	v_cndmask_b32_e32 v102, v104, v102, vcc
	v_cndmask_b32_e32 v107, v109, v107, vcc
	v_cndmask_b32_e32 v106, v108, v106, vcc
	s_waitcnt vmcnt(0)
	v_mfma_f32_16x16x32_bf16 v[14:17], v[138:141], v[142:145], v[14:17]
	s_nop 0
	v_mfma_f32_16x16x32_bf16 v[10:13], v[138:141], v[146:149], v[10:13]
	v_mfma_f32_16x16x32_bf16 v[6:9], v[138:141], v[150:153], v[6:9]
	v_mfma_f32_16x16x32_bf16 v[2:5], v[138:141], v[154:157], v[2:5]
	v_mfma_f32_16x16x32_bf16 v[62:65], v[184:187], v[174:177], v[62:65]
	v_mfma_f32_16x16x32_bf16 v[58:61], v[184:187], v[168:171], v[58:61]
	v_mfma_f32_16x16x32_bf16 v[54:57], v[184:187], v[180:183], v[54:57]
	v_mfma_f32_16x16x32_bf16 v[50:53], v[184:187], v[218:221], v[50:53]
	v_mfma_f32_16x16x32_bf16 v[46:49], v[188:191], v[174:177], v[46:49]
	v_mfma_f32_16x16x32_bf16 v[42:45], v[188:191], v[168:171], v[42:45]
	v_mfma_f32_16x16x32_bf16 v[38:41], v[188:191], v[180:183], v[38:41]
	v_mfma_f32_16x16x32_bf16 v[34:37], v[188:191], v[218:221], v[34:37]
	v_mfma_f32_16x16x32_bf16 v[30:33], v[192:195], v[174:177], v[30:33]
	v_mfma_f32_16x16x32_bf16 v[26:29], v[192:195], v[168:171], v[26:29]
	v_mfma_f32_16x16x32_bf16 v[22:25], v[192:195], v[180:183], v[22:25]
	v_mfma_f32_16x16x32_bf16 v[18:21], v[192:195], v[218:221], v[18:21]
	v_mfma_f32_16x16x32_bf16 v[14:17], v[212:215], v[174:177], v[14:17]
	v_mfma_f32_16x16x32_bf16 v[10:13], v[212:215], v[168:171], v[10:13]
	v_mfma_f32_16x16x32_bf16 v[6:9], v[212:215], v[180:183], v[6:9]
	v_mfma_f32_16x16x32_bf16 v[2:5], v[212:215], v[218:221], v[2:5]
	s_cbranch_scc1 .LBB0_325
	v_ashrrev_i32_e32 v1, 4, v1
	v_and_b32_e32 v68, -4, v1
	s_mov_b32 s3, s89
	v_ashrrev_i32_e32 v69, 31, v68
	v_lshl_add_u64 v[70:71], s[2:3], 0, v[68:69]
	v_mul_f32_e32 v69, 0x3d372713, v62
	v_mul_f32_e32 v69, v62, v69
	v_fma_f32 v69, v62, v69, v62
	v_mul_f32_e32 v69, 0x3f4c422a, v69
	v_mul_f32_e32 v69, -2.0, v69
	v_mul_f32_e32 v69, 0x3fb8aa3b, v69
	v_exp_f32_e32 v72, v69
	v_mul_f32_e32 v69, 0x3d372713, v63
	v_mul_f32_e32 v69, v63, v69
	v_fma_f32 v69, v63, v69, v63
	v_mul_f32_e32 v69, 0x3f4c422a, v69
	v_mul_f32_e32 v69, -2.0, v69
	v_mul_f32_e32 v69, 0x3fb8aa3b, v69
	v_exp_f32_e32 v73, v69
	v_lshlrev_b32_e32 v66, 3, v119
	v_readlane_b32 s0, v253, 57
	v_and_b32_e32 v130, 24, v66
	v_pk_add_f32 v[72:73], v[72:73], 1.0 op_sel_hi:[1,0]
	v_readlane_b32 s1, v253, 58
	v_div_scale_f32 v69, s[4:5], v73, v73, v63
	v_rcp_f32_e32 v74, v69
	v_lshl_add_u64 v[66:67], s[0:1], 0, v[130:131]
	v_or_b32_e32 v130, s6, v118
	v_fma_f32 v75, -v69, v74, 1.0
	v_fmac_f32_e32 v74, v75, v74
	v_div_scale_f32 v75, vcc, v63, v73, v63
	v_mul_f32_e32 v76, v75, v74
	v_fma_f32 v77, -v69, v76, v75
	v_fmac_f32_e32 v76, v77, v74
	v_fma_f32 v69, -v69, v76, v75
	v_div_fmas_f32 v69, v69, v74, v76
	v_div_fixup_f32 v63, v69, v73, v63
	v_div_scale_f32 v69, s[4:5], v72, v72, v62
	v_rcp_f32_e32 v73, v69
	s_barrier
	v_fma_f32 v74, -v69, v73, 1.0
	v_fmac_f32_e32 v73, v74, v73
	v_div_scale_f32 v74, vcc, v62, v72, v62
	v_mul_f32_e32 v75, v74, v73
	v_fma_f32 v76, -v69, v75, v74
	v_fmac_f32_e32 v75, v76, v73
	v_fma_f32 v69, -v69, v75, v74
	v_div_fmas_f32 v69, v69, v73, v75
	v_div_fixup_f32 v62, v69, v72, v62
	v_cvt_pk_bf16_f32 v62, v62, v63
	v_mul_f32_e32 v63, 0x3d372713, v64
	v_mul_f32_e32 v63, v64, v63
	v_fma_f32 v63, v64, v63, v64
	v_mul_f32_e32 v63, 0x3f4c422a, v63
	v_mul_f32_e32 v63, -2.0, v63
	v_mul_f32_e32 v63, 0x3fb8aa3b, v63
	v_exp_f32_e32 v72, v63
	v_mul_f32_e32 v63, 0x3d372713, v65
	v_mul_f32_e32 v63, v65, v63
	v_fma_f32 v63, v65, v63, v65
	v_mul_f32_e32 v63, 0x3f4c422a, v63
	v_mul_f32_e32 v63, -2.0, v63
	v_mul_f32_e32 v63, 0x3fb8aa3b, v63
	v_exp_f32_e32 v73, v63
	s_nop 0
	v_pk_add_f32 v[72:73], v[72:73], 1.0 op_sel_hi:[1,0]
	s_nop 0
	v_div_scale_f32 v63, s[4:5], v73, v73, v65
	v_rcp_f32_e32 v69, v63
	s_nop 0
	v_fma_f32 v74, -v63, v69, 1.0
	v_fmac_f32_e32 v69, v74, v69
	v_div_scale_f32 v74, vcc, v65, v73, v65
	v_mul_f32_e32 v75, v74, v69
	v_fma_f32 v76, -v63, v75, v74
	v_fmac_f32_e32 v75, v76, v69
	v_fma_f32 v63, -v63, v75, v74
	v_div_fmas_f32 v63, v63, v69, v75
	v_div_fixup_f32 v63, v63, v73, v65
	v_div_scale_f32 v65, s[4:5], v72, v72, v64
	v_rcp_f32_e32 v69, v65
	s_nop 0
	v_fma_f32 v73, -v65, v69, 1.0
	v_fmac_f32_e32 v69, v73, v69
	v_div_scale_f32 v73, vcc, v64, v72, v64
	v_mul_f32_e32 v74, v73, v69
	v_fma_f32 v75, -v65, v74, v73
	v_fmac_f32_e32 v74, v75, v69
	v_fma_f32 v65, -v65, v74, v73
	v_div_fmas_f32 v65, v65, v69, v74
	v_div_fixup_f32 v64, v65, v72, v64
	v_cvt_pk_bf16_f32 v63, v64, v63
	v_lshl_add_u64 v[64:65], v[70:71], 0, v[130:131]
	v_lshlrev_b64 v[64:65], 5, v[64:65]
	v_lshl_add_u64 v[64:65], v[66:67], 0, v[64:65]
	global_store_dwordx2 v[64:65], v[62:63], off
	v_mul_f32_e32 v62, 0x3d372713, v58
	v_mul_f32_e32 v63, 0x3d372713, v59
	v_mul_f32_e32 v62, v58, v62
	v_mul_f32_e32 v63, v59, v63
	v_fma_f32 v62, v58, v62, v58
	v_fma_f32 v63, v59, v63, v59
	v_mul_f32_e32 v62, 0x3f4c422a, v62
	v_mul_f32_e32 v63, 0x3f4c422a, v63
	v_mul_f32_e32 v62, -2.0, v62
	v_mul_f32_e32 v63, -2.0, v63
	v_mul_f32_e32 v62, 0x3fb8aa3b, v62
	v_mul_f32_e32 v63, 0x3fb8aa3b, v63
	v_exp_f32_e32 v62, v62
	v_exp_f32_e32 v63, v63
	s_nop 0
	v_pk_add_f32 v[62:63], v[62:63], 1.0 op_sel_hi:[1,0]
	s_nop 0
	v_div_scale_f32 v64, s[4:5], v63, v63, v59
	v_rcp_f32_e32 v65, v64
	s_nop 0
	v_fma_f32 v69, -v64, v65, 1.0
	v_fmac_f32_e32 v65, v69, v65
	v_div_scale_f32 v69, vcc, v59, v63, v59
	v_mul_f32_e32 v72, v69, v65
	v_fma_f32 v73, -v64, v72, v69
	v_fmac_f32_e32 v72, v73, v65
	v_fma_f32 v64, -v64, v72, v69
	v_div_fmas_f32 v64, v64, v65, v72
	v_div_fixup_f32 v59, v64, v63, v59
	v_div_scale_f32 v63, s[4:5], v62, v62, v58
	v_rcp_f32_e32 v64, v63
	s_nop 0
	v_fma_f32 v65, -v63, v64, 1.0
	v_fmac_f32_e32 v64, v65, v64
	v_div_scale_f32 v65, vcc, v58, v62, v58
	v_mul_f32_e32 v69, v65, v64
	v_fma_f32 v72, -v63, v69, v65
	v_fmac_f32_e32 v69, v72, v64
	v_fma_f32 v63, -v63, v69, v65
	v_div_fmas_f32 v63, v63, v64, v69
	v_div_fixup_f32 v58, v63, v62, v58
	v_cvt_pk_bf16_f32 v62, v58, v59
	v_mul_f32_e32 v58, 0x3d372713, v60
	v_mul_f32_e32 v59, 0x3d372713, v61
	v_mul_f32_e32 v58, v60, v58
	v_mul_f32_e32 v59, v61, v59
	v_fma_f32 v58, v60, v58, v60
	v_fma_f32 v59, v61, v59, v61
	v_mul_f32_e32 v58, 0x3f4c422a, v58
	v_mul_f32_e32 v59, 0x3f4c422a, v59
	v_mul_f32_e32 v58, -2.0, v58
	v_mul_f32_e32 v59, -2.0, v59
	v_mul_f32_e32 v58, 0x3fb8aa3b, v58
	v_mul_f32_e32 v59, 0x3fb8aa3b, v59
	v_exp_f32_e32 v58, v58
	v_exp_f32_e32 v59, v59
	s_nop 0
	v_pk_add_f32 v[58:59], v[58:59], 1.0 op_sel_hi:[1,0]
	s_nop 0
	v_div_scale_f32 v63, s[4:5], v59, v59, v61
	v_rcp_f32_e32 v64, v63
	s_nop 0
	v_fma_f32 v65, -v63, v64, 1.0
	v_fmac_f32_e32 v64, v65, v64
	v_div_scale_f32 v65, vcc, v61, v59, v61
	v_mul_f32_e32 v69, v65, v64
	v_fma_f32 v72, -v63, v69, v65
	v_fmac_f32_e32 v69, v72, v64
	v_fma_f32 v63, -v63, v69, v65
	v_div_fmas_f32 v63, v63, v64, v69
	v_div_fixup_f32 v59, v63, v59, v61
	v_div_scale_f32 v61, s[4:5], v58, v58, v60
	v_rcp_f32_e32 v63, v61
	s_nop 0
	v_fma_f32 v64, -v61, v63, 1.0
	v_fmac_f32_e32 v63, v64, v63
	v_div_scale_f32 v64, vcc, v60, v58, v60
	v_mul_f32_e32 v65, v64, v63
	v_fma_f32 v69, -v61, v65, v64
	v_fmac_f32_e32 v65, v69, v63
	v_fma_f32 v61, -v61, v65, v64
	v_div_fmas_f32 v61, v61, v63, v65
	v_div_fixup_f32 v58, v61, v58, v60
	v_cvt_pk_bf16_f32 v63, v58, v59
	v_or_b32_e32 v58, 0x100, v130
	v_mov_b32_e32 v59, v131
	v_lshl_add_u64 v[60:61], v[70:71], 0, v[58:59]
	v_lshlrev_b64 v[60:61], 5, v[60:61]
	v_lshl_add_u64 v[60:61], v[66:67], 0, v[60:61]
	global_store_dwordx2 v[60:61], v[62:63], off
	v_mul_f32_e32 v60, 0x3d372713, v54
	v_mul_f32_e32 v61, 0x3d372713, v55
	v_mul_f32_e32 v60, v54, v60
	v_mul_f32_e32 v61, v55, v61
	v_fma_f32 v60, v54, v60, v54
	v_fma_f32 v61, v55, v61, v55
	v_mul_f32_e32 v60, 0x3f4c422a, v60
	v_mul_f32_e32 v61, 0x3f4c422a, v61
	v_mul_f32_e32 v60, -2.0, v60
	v_mul_f32_e32 v61, -2.0, v61
	v_mul_f32_e32 v60, 0x3fb8aa3b, v60
	v_mul_f32_e32 v61, 0x3fb8aa3b, v61
	v_exp_f32_e32 v60, v60
	v_exp_f32_e32 v61, v61
	s_nop 0
	v_pk_add_f32 v[60:61], v[60:61], 1.0 op_sel_hi:[1,0]
	s_nop 0
	v_div_scale_f32 v62, s[4:5], v61, v61, v55
	v_rcp_f32_e32 v63, v62
	s_nop 0
	v_fma_f32 v64, -v62, v63, 1.0
	v_fmac_f32_e32 v63, v64, v63
	v_div_scale_f32 v64, vcc, v55, v61, v55
	v_mul_f32_e32 v65, v64, v63
	v_fma_f32 v69, -v62, v65, v64
	v_fmac_f32_e32 v65, v69, v63
	v_fma_f32 v62, -v62, v65, v64
	v_div_fmas_f32 v62, v62, v63, v65
	v_div_fixup_f32 v55, v62, v61, v55
	v_div_scale_f32 v61, s[4:5], v60, v60, v54
	v_rcp_f32_e32 v62, v61
	s_nop 0
	v_fma_f32 v63, -v61, v62, 1.0
	v_fmac_f32_e32 v62, v63, v62
	v_div_scale_f32 v63, vcc, v54, v60, v54
	v_mul_f32_e32 v64, v63, v62
	v_fma_f32 v65, -v61, v64, v63
	v_fmac_f32_e32 v64, v65, v62
	v_fma_f32 v61, -v61, v64, v63
	v_div_fmas_f32 v61, v61, v62, v64
	v_div_fixup_f32 v54, v61, v60, v54
	v_cvt_pk_bf16_f32 v60, v54, v55
	v_mul_f32_e32 v54, 0x3d372713, v56
	v_mul_f32_e32 v55, 0x3d372713, v57
	v_mul_f32_e32 v54, v56, v54
	v_mul_f32_e32 v55, v57, v55
	v_fma_f32 v54, v56, v54, v56
	v_fma_f32 v55, v57, v55, v57
	v_mul_f32_e32 v54, 0x3f4c422a, v54
	v_mul_f32_e32 v55, 0x3f4c422a, v55
	v_mul_f32_e32 v54, -2.0, v54
	v_mul_f32_e32 v55, -2.0, v55
	v_mul_f32_e32 v54, 0x3fb8aa3b, v54
	v_mul_f32_e32 v55, 0x3fb8aa3b, v55
	v_exp_f32_e32 v54, v54
	v_exp_f32_e32 v55, v55
	s_nop 0
	v_pk_add_f32 v[54:55], v[54:55], 1.0 op_sel_hi:[1,0]
	s_nop 0
	v_div_scale_f32 v61, s[4:5], v55, v55, v57
	v_rcp_f32_e32 v62, v61
	s_nop 0
	v_fma_f32 v63, -v61, v62, 1.0
	v_fmac_f32_e32 v62, v63, v62
	v_div_scale_f32 v63, vcc, v57, v55, v57
	v_mul_f32_e32 v64, v63, v62
	v_fma_f32 v65, -v61, v64, v63
	v_fmac_f32_e32 v64, v65, v62
	v_fma_f32 v61, -v61, v64, v63
	v_div_fmas_f32 v61, v61, v62, v64
	v_div_fixup_f32 v55, v61, v55, v57
	v_div_scale_f32 v57, s[4:5], v54, v54, v56
	v_rcp_f32_e32 v61, v57
	s_nop 0
	v_fma_f32 v62, -v57, v61, 1.0
	v_fmac_f32_e32 v61, v62, v61
	v_div_scale_f32 v62, vcc, v56, v54, v56
	v_mul_f32_e32 v63, v62, v61
	v_fma_f32 v64, -v57, v63, v62
	v_fmac_f32_e32 v63, v64, v61
	v_fma_f32 v57, -v57, v63, v62
	v_div_fmas_f32 v57, v57, v61, v63
	v_div_fixup_f32 v54, v57, v54, v56
	v_cvt_pk_bf16_f32 v61, v54, v55
	v_or_b32_e32 v54, 0x200, v130
	v_mov_b32_e32 v55, v131
	v_lshl_add_u64 v[56:57], v[70:71], 0, v[54:55]
	v_lshlrev_b64 v[56:57], 5, v[56:57]
	v_lshl_add_u64 v[56:57], v[66:67], 0, v[56:57]
	global_store_dwordx2 v[56:57], v[60:61], off
	v_mul_f32_e32 v56, 0x3d372713, v50
	v_mul_f32_e32 v57, 0x3d372713, v51
	v_mul_f32_e32 v56, v50, v56
	v_mul_f32_e32 v57, v51, v57
	v_fma_f32 v56, v50, v56, v50
	v_fma_f32 v57, v51, v57, v51
	v_mul_f32_e32 v56, 0x3f4c422a, v56
	v_mul_f32_e32 v57, 0x3f4c422a, v57
	v_mul_f32_e32 v56, -2.0, v56
	v_mul_f32_e32 v57, -2.0, v57
	v_mul_f32_e32 v56, 0x3fb8aa3b, v56
	v_mul_f32_e32 v57, 0x3fb8aa3b, v57
	v_exp_f32_e32 v56, v56
	v_exp_f32_e32 v57, v57
	s_nop 0
	v_pk_add_f32 v[56:57], v[56:57], 1.0 op_sel_hi:[1,0]
	s_nop 0
	v_div_scale_f32 v60, s[4:5], v57, v57, v51
	v_rcp_f32_e32 v61, v60
	s_nop 0
	v_fma_f32 v62, -v60, v61, 1.0
	v_fmac_f32_e32 v61, v62, v61
	v_div_scale_f32 v62, vcc, v51, v57, v51
	v_mul_f32_e32 v63, v62, v61
	v_fma_f32 v64, -v60, v63, v62
	v_fmac_f32_e32 v63, v64, v61
	v_fma_f32 v60, -v60, v63, v62
	v_div_fmas_f32 v60, v60, v61, v63
	v_div_fixup_f32 v51, v60, v57, v51
	v_div_scale_f32 v57, s[4:5], v56, v56, v50
	v_rcp_f32_e32 v60, v57
	s_nop 0
	v_fma_f32 v61, -v57, v60, 1.0
	v_fmac_f32_e32 v60, v61, v60
	v_div_scale_f32 v61, vcc, v50, v56, v50
	v_mul_f32_e32 v62, v61, v60
	v_fma_f32 v63, -v57, v62, v61
	v_fmac_f32_e32 v62, v63, v60
	v_fma_f32 v57, -v57, v62, v61
	v_div_fmas_f32 v57, v57, v60, v62
	v_div_fixup_f32 v50, v57, v56, v50
	v_cvt_pk_bf16_f32 v56, v50, v51
	v_mul_f32_e32 v50, 0x3d372713, v52
	v_mul_f32_e32 v51, 0x3d372713, v53
	v_mul_f32_e32 v50, v52, v50
	v_mul_f32_e32 v51, v53, v51
	v_fma_f32 v50, v52, v50, v52
	v_fma_f32 v51, v53, v51, v53
	v_mul_f32_e32 v50, 0x3f4c422a, v50
	v_mul_f32_e32 v51, 0x3f4c422a, v51
	v_mul_f32_e32 v50, -2.0, v50
	v_mul_f32_e32 v51, -2.0, v51
	v_mul_f32_e32 v50, 0x3fb8aa3b, v50
	v_mul_f32_e32 v51, 0x3fb8aa3b, v51
	v_exp_f32_e32 v50, v50
	v_exp_f32_e32 v51, v51
	s_nop 0
	v_pk_add_f32 v[50:51], v[50:51], 1.0 op_sel_hi:[1,0]
	s_nop 0
	v_div_scale_f32 v57, s[4:5], v51, v51, v53
	v_rcp_f32_e32 v60, v57
	s_nop 0
	v_fma_f32 v61, -v57, v60, 1.0
	v_fmac_f32_e32 v60, v61, v60
	v_div_scale_f32 v61, vcc, v53, v51, v53
	v_mul_f32_e32 v62, v61, v60
	v_fma_f32 v63, -v57, v62, v61
	v_fmac_f32_e32 v62, v63, v60
	v_fma_f32 v57, -v57, v62, v61
	v_div_fmas_f32 v57, v57, v60, v62
	v_div_fixup_f32 v51, v57, v51, v53
	v_div_scale_f32 v53, s[4:5], v50, v50, v52
	v_rcp_f32_e32 v57, v53
	s_nop 0
	v_fma_f32 v60, -v53, v57, 1.0
	v_fmac_f32_e32 v57, v60, v57
	v_div_scale_f32 v60, vcc, v52, v50, v52
	v_mul_f32_e32 v61, v60, v57
	v_fma_f32 v62, -v53, v61, v60
	v_fmac_f32_e32 v61, v62, v57
	v_fma_f32 v53, -v53, v61, v60
	v_div_fmas_f32 v53, v53, v57, v61
	v_div_fixup_f32 v50, v53, v50, v52
	v_cvt_pk_bf16_f32 v57, v50, v51
	v_or_b32_e32 v50, 0x300, v130
	v_mov_b32_e32 v51, v131
	v_lshl_add_u64 v[52:53], v[70:71], 0, v[50:51]
	v_lshlrev_b64 v[52:53], 5, v[52:53]
	v_lshl_add_u64 v[52:53], v[66:67], 0, v[52:53]
	global_store_dwordx2 v[52:53], v[56:57], off
	v_mul_f32_e32 v56, 0x3d372713, v46
	v_mul_f32_e32 v57, 0x3d372713, v47
	v_mul_f32_e32 v56, v46, v56
	v_mul_f32_e32 v57, v47, v57
	v_fma_f32 v56, v46, v56, v46
	v_fma_f32 v57, v47, v57, v47
	v_mul_f32_e32 v56, 0x3f4c422a, v56
	v_mul_f32_e32 v57, 0x3f4c422a, v57
	v_mul_f32_e32 v56, -2.0, v56
	v_mul_f32_e32 v57, -2.0, v57
	v_mul_f32_e32 v56, 0x3fb8aa3b, v56
	v_mul_f32_e32 v57, 0x3fb8aa3b, v57
	v_exp_f32_e32 v56, v56
	v_exp_f32_e32 v57, v57
	v_or_b32_e32 v52, 1, v68
	v_ashrrev_i32_e32 v53, 31, v52
	v_lshl_add_u64 v[52:53], s[2:3], 0, v[52:53]
	v_pk_add_f32 v[56:57], v[56:57], 1.0 op_sel_hi:[1,0]
	s_nop 0
	v_div_scale_f32 v60, s[4:5], v57, v57, v47
	v_rcp_f32_e32 v61, v60
	s_nop 0
	v_fma_f32 v62, -v60, v61, 1.0
	v_fmac_f32_e32 v61, v62, v61
	v_div_scale_f32 v62, vcc, v47, v57, v47
	v_mul_f32_e32 v63, v62, v61
	v_fma_f32 v64, -v60, v63, v62
	v_fmac_f32_e32 v63, v64, v61
	v_fma_f32 v60, -v60, v63, v62
	v_div_fmas_f32 v60, v60, v61, v63
	v_div_fixup_f32 v47, v60, v57, v47
	v_div_scale_f32 v57, s[4:5], v56, v56, v46
	v_rcp_f32_e32 v60, v57
	s_nop 0
	v_fma_f32 v61, -v57, v60, 1.0
	v_fmac_f32_e32 v60, v61, v60
	v_div_scale_f32 v61, vcc, v46, v56, v46
	v_mul_f32_e32 v62, v61, v60
	v_fma_f32 v63, -v57, v62, v61
	v_fmac_f32_e32 v62, v63, v60
	v_fma_f32 v57, -v57, v62, v61
	v_div_fmas_f32 v57, v57, v60, v62
	v_div_fixup_f32 v46, v57, v56, v46
	v_cvt_pk_bf16_f32 v46, v46, v47
	v_mul_f32_e32 v47, 0x3d372713, v48
	v_mul_f32_e32 v47, v48, v47
	v_fma_f32 v47, v48, v47, v48
	v_mul_f32_e32 v47, 0x3f4c422a, v47
	v_mul_f32_e32 v47, -2.0, v47
	v_mul_f32_e32 v47, 0x3fb8aa3b, v47
	v_exp_f32_e32 v56, v47
	v_mul_f32_e32 v47, 0x3d372713, v49
	v_mul_f32_e32 v47, v49, v47
	v_fma_f32 v47, v49, v47, v49
	v_mul_f32_e32 v47, 0x3f4c422a, v47
	v_mul_f32_e32 v47, -2.0, v47
	v_mul_f32_e32 v47, 0x3fb8aa3b, v47
	v_exp_f32_e32 v57, v47
	s_nop 0
	v_pk_add_f32 v[56:57], v[56:57], 1.0 op_sel_hi:[1,0]
	s_nop 0
	v_div_scale_f32 v47, s[4:5], v57, v57, v49
	v_rcp_f32_e32 v60, v47
	s_nop 0
	v_fma_f32 v61, -v47, v60, 1.0
	v_fmac_f32_e32 v60, v61, v60
	v_div_scale_f32 v61, vcc, v49, v57, v49
	v_mul_f32_e32 v62, v61, v60
	v_fma_f32 v63, -v47, v62, v61
	v_fmac_f32_e32 v62, v63, v60
	v_fma_f32 v47, -v47, v62, v61
	v_div_fmas_f32 v47, v47, v60, v62
	v_div_fixup_f32 v47, v47, v57, v49
	v_div_scale_f32 v49, s[4:5], v56, v56, v48
	v_rcp_f32_e32 v57, v49
	s_nop 0
	v_fma_f32 v60, -v49, v57, 1.0
	v_fmac_f32_e32 v57, v60, v57
	v_div_scale_f32 v60, vcc, v48, v56, v48
	v_mul_f32_e32 v61, v60, v57
	v_fma_f32 v62, -v49, v61, v60
	v_fmac_f32_e32 v61, v62, v57
	v_fma_f32 v49, -v49, v61, v60
	v_div_fmas_f32 v49, v49, v57, v61
	v_div_fixup_f32 v48, v49, v56, v48
	v_cvt_pk_bf16_f32 v47, v48, v47
	v_lshl_add_u64 v[48:49], v[52:53], 0, v[130:131]
	v_lshlrev_b64 v[48:49], 5, v[48:49]
	v_lshl_add_u64 v[48:49], v[66:67], 0, v[48:49]
	global_store_dwordx2 v[48:49], v[46:47], off
	v_mul_f32_e32 v46, 0x3d372713, v42
	v_mul_f32_e32 v47, 0x3d372713, v43
	v_mul_f32_e32 v46, v42, v46
	v_mul_f32_e32 v47, v43, v47
	v_fma_f32 v46, v42, v46, v42
	v_fma_f32 v47, v43, v47, v43
	v_mul_f32_e32 v46, 0x3f4c422a, v46
	v_mul_f32_e32 v47, 0x3f4c422a, v47
	v_mul_f32_e32 v46, -2.0, v46
	v_mul_f32_e32 v47, -2.0, v47
	v_mul_f32_e32 v46, 0x3fb8aa3b, v46
	v_mul_f32_e32 v47, 0x3fb8aa3b, v47
	v_exp_f32_e32 v46, v46
	v_exp_f32_e32 v47, v47
	s_nop 0
	v_pk_add_f32 v[46:47], v[46:47], 1.0 op_sel_hi:[1,0]
	s_nop 0
	v_div_scale_f32 v48, s[4:5], v47, v47, v43
	v_rcp_f32_e32 v49, v48
	s_nop 0
	v_fma_f32 v56, -v48, v49, 1.0
	v_fmac_f32_e32 v49, v56, v49
	v_div_scale_f32 v56, vcc, v43, v47, v43
	v_mul_f32_e32 v57, v56, v49
	v_fma_f32 v60, -v48, v57, v56
	v_fmac_f32_e32 v57, v60, v49
	v_fma_f32 v48, -v48, v57, v56
	v_div_fmas_f32 v48, v48, v49, v57
	v_div_fixup_f32 v43, v48, v47, v43
	v_div_scale_f32 v47, s[4:5], v46, v46, v42
	v_rcp_f32_e32 v48, v47
	s_nop 0
	v_fma_f32 v49, -v47, v48, 1.0
	v_fmac_f32_e32 v48, v49, v48
	v_div_scale_f32 v49, vcc, v42, v46, v42
	v_mul_f32_e32 v56, v49, v48
	v_fma_f32 v57, -v47, v56, v49
	v_fmac_f32_e32 v56, v57, v48
	v_fma_f32 v47, -v47, v56, v49
	v_div_fmas_f32 v47, v47, v48, v56
	v_div_fixup_f32 v42, v47, v46, v42
	v_cvt_pk_bf16_f32 v42, v42, v43
	v_mul_f32_e32 v43, 0x3d372713, v44
	v_mul_f32_e32 v43, v44, v43
	v_fma_f32 v43, v44, v43, v44
	v_mul_f32_e32 v43, 0x3f4c422a, v43
	v_mul_f32_e32 v43, -2.0, v43
	v_mul_f32_e32 v43, 0x3fb8aa3b, v43
	v_exp_f32_e32 v46, v43
	v_mul_f32_e32 v43, 0x3d372713, v45
	v_mul_f32_e32 v43, v45, v43
	v_fma_f32 v43, v45, v43, v45
	v_mul_f32_e32 v43, 0x3f4c422a, v43
	v_mul_f32_e32 v43, -2.0, v43
	v_mul_f32_e32 v43, 0x3fb8aa3b, v43
	v_exp_f32_e32 v47, v43
	s_nop 0
	v_pk_add_f32 v[46:47], v[46:47], 1.0 op_sel_hi:[1,0]
	s_nop 0
	v_div_scale_f32 v43, s[4:5], v47, v47, v45
	v_rcp_f32_e32 v48, v43
	s_nop 0
	v_fma_f32 v49, -v43, v48, 1.0
	v_fmac_f32_e32 v48, v49, v48
	v_div_scale_f32 v49, vcc, v45, v47, v45
	v_mul_f32_e32 v56, v49, v48
	v_fma_f32 v57, -v43, v56, v49
	v_fmac_f32_e32 v56, v57, v48
	v_fma_f32 v43, -v43, v56, v49
	v_div_fmas_f32 v43, v43, v48, v56
	v_div_fixup_f32 v43, v43, v47, v45
	v_div_scale_f32 v45, s[4:5], v46, v46, v44
	v_rcp_f32_e32 v47, v45
	s_nop 0
	v_fma_f32 v48, -v45, v47, 1.0
	v_fmac_f32_e32 v47, v48, v47
	v_div_scale_f32 v48, vcc, v44, v46, v44
	v_mul_f32_e32 v49, v48, v47
	v_fma_f32 v56, -v45, v49, v48
	v_fmac_f32_e32 v49, v56, v47
	v_fma_f32 v45, -v45, v49, v48
	v_div_fmas_f32 v45, v45, v47, v49
	v_div_fixup_f32 v44, v45, v46, v44
	v_cvt_pk_bf16_f32 v43, v44, v43
	v_lshl_add_u64 v[44:45], v[52:53], 0, v[58:59]
	v_lshlrev_b64 v[44:45], 5, v[44:45]
	v_lshl_add_u64 v[44:45], v[66:67], 0, v[44:45]
	global_store_dwordx2 v[44:45], v[42:43], off
	v_mul_f32_e32 v42, 0x3d372713, v38
	v_mul_f32_e32 v43, 0x3d372713, v39
	v_mul_f32_e32 v42, v38, v42
	v_mul_f32_e32 v43, v39, v43
	v_fma_f32 v42, v38, v42, v38
	v_fma_f32 v43, v39, v43, v39
	v_mul_f32_e32 v42, 0x3f4c422a, v42
	v_mul_f32_e32 v43, 0x3f4c422a, v43
	v_mul_f32_e32 v42, -2.0, v42
	v_mul_f32_e32 v43, -2.0, v43
	v_mul_f32_e32 v42, 0x3fb8aa3b, v42
	v_mul_f32_e32 v43, 0x3fb8aa3b, v43
	v_exp_f32_e32 v42, v42
	v_exp_f32_e32 v43, v43
	s_nop 0
	v_pk_add_f32 v[42:43], v[42:43], 1.0 op_sel_hi:[1,0]
	s_nop 0
	v_div_scale_f32 v44, s[4:5], v43, v43, v39
	v_rcp_f32_e32 v45, v44
	s_nop 0
	v_fma_f32 v46, -v44, v45, 1.0
	v_fmac_f32_e32 v45, v46, v45
	v_div_scale_f32 v46, vcc, v39, v43, v39
	v_mul_f32_e32 v47, v46, v45
	v_fma_f32 v48, -v44, v47, v46
	v_fmac_f32_e32 v47, v48, v45
	v_fma_f32 v44, -v44, v47, v46
	v_div_fmas_f32 v44, v44, v45, v47
	v_div_fixup_f32 v39, v44, v43, v39
	v_div_scale_f32 v43, s[4:5], v42, v42, v38
	v_rcp_f32_e32 v44, v43
	s_nop 0
	v_fma_f32 v45, -v43, v44, 1.0
	v_fmac_f32_e32 v44, v45, v44
	v_div_scale_f32 v45, vcc, v38, v42, v38
	v_mul_f32_e32 v46, v45, v44
	v_fma_f32 v47, -v43, v46, v45
	v_fmac_f32_e32 v46, v47, v44
	v_fma_f32 v43, -v43, v46, v45
	v_div_fmas_f32 v43, v43, v44, v46
	v_div_fixup_f32 v38, v43, v42, v38
	v_cvt_pk_bf16_f32 v38, v38, v39
	v_mul_f32_e32 v39, 0x3d372713, v40
	v_mul_f32_e32 v39, v40, v39
	v_fma_f32 v39, v40, v39, v40
	v_mul_f32_e32 v39, 0x3f4c422a, v39
	v_mul_f32_e32 v39, -2.0, v39
	v_mul_f32_e32 v39, 0x3fb8aa3b, v39
	v_exp_f32_e32 v42, v39
	v_mul_f32_e32 v39, 0x3d372713, v41
	v_mul_f32_e32 v39, v41, v39
	v_fma_f32 v39, v41, v39, v41
	v_mul_f32_e32 v39, 0x3f4c422a, v39
	v_mul_f32_e32 v39, -2.0, v39
	v_mul_f32_e32 v39, 0x3fb8aa3b, v39
	v_exp_f32_e32 v43, v39
	s_nop 0
	v_pk_add_f32 v[42:43], v[42:43], 1.0 op_sel_hi:[1,0]
	s_nop 0
	v_div_scale_f32 v39, s[4:5], v43, v43, v41
	v_rcp_f32_e32 v44, v39
	s_nop 0
	v_fma_f32 v45, -v39, v44, 1.0
	v_fmac_f32_e32 v44, v45, v44
	v_div_scale_f32 v45, vcc, v41, v43, v41
	v_mul_f32_e32 v46, v45, v44
	v_fma_f32 v47, -v39, v46, v45
	v_fmac_f32_e32 v46, v47, v44
	v_fma_f32 v39, -v39, v46, v45
	v_div_fmas_f32 v39, v39, v44, v46
	v_div_fixup_f32 v39, v39, v43, v41
	v_div_scale_f32 v41, s[4:5], v42, v42, v40
	v_rcp_f32_e32 v43, v41
	s_nop 0
	v_fma_f32 v44, -v41, v43, 1.0
	v_fmac_f32_e32 v43, v44, v43
	v_div_scale_f32 v44, vcc, v40, v42, v40
	v_mul_f32_e32 v45, v44, v43
	v_fma_f32 v46, -v41, v45, v44
	v_fmac_f32_e32 v45, v46, v43
	v_fma_f32 v41, -v41, v45, v44
	v_div_fmas_f32 v41, v41, v43, v45
	v_div_fixup_f32 v40, v41, v42, v40
	v_cvt_pk_bf16_f32 v39, v40, v39
	v_lshl_add_u64 v[40:41], v[52:53], 0, v[54:55]
	v_lshlrev_b64 v[40:41], 5, v[40:41]
	v_lshl_add_u64 v[40:41], v[66:67], 0, v[40:41]
	global_store_dwordx2 v[40:41], v[38:39], off
	v_mul_f32_e32 v38, 0x3d372713, v34
	v_mul_f32_e32 v39, 0x3d372713, v35
	v_mul_f32_e32 v38, v34, v38
	v_mul_f32_e32 v39, v35, v39
	v_fma_f32 v38, v34, v38, v34
	v_fma_f32 v39, v35, v39, v35
	v_mul_f32_e32 v38, 0x3f4c422a, v38
	v_mul_f32_e32 v39, 0x3f4c422a, v39
	v_mul_f32_e32 v38, -2.0, v38
	v_mul_f32_e32 v39, -2.0, v39
	v_mul_f32_e32 v38, 0x3fb8aa3b, v38
	v_mul_f32_e32 v39, 0x3fb8aa3b, v39
	v_exp_f32_e32 v38, v38
	v_exp_f32_e32 v39, v39
	s_nop 0
	v_pk_add_f32 v[38:39], v[38:39], 1.0 op_sel_hi:[1,0]
	s_nop 0
	v_div_scale_f32 v40, s[4:5], v39, v39, v35
	v_rcp_f32_e32 v41, v40
	s_nop 0
	v_fma_f32 v42, -v40, v41, 1.0
	v_fmac_f32_e32 v41, v42, v41
	v_div_scale_f32 v42, vcc, v35, v39, v35
	v_mul_f32_e32 v43, v42, v41
	v_fma_f32 v44, -v40, v43, v42
	v_fmac_f32_e32 v43, v44, v41
	v_fma_f32 v40, -v40, v43, v42
	v_div_fmas_f32 v40, v40, v41, v43
	v_div_fixup_f32 v35, v40, v39, v35
	v_div_scale_f32 v39, s[4:5], v38, v38, v34
	v_rcp_f32_e32 v40, v39
	s_nop 0
	v_fma_f32 v41, -v39, v40, 1.0
	v_fmac_f32_e32 v40, v41, v40
	v_div_scale_f32 v41, vcc, v34, v38, v34
	v_mul_f32_e32 v42, v41, v40
	v_fma_f32 v43, -v39, v42, v41
	v_fmac_f32_e32 v42, v43, v40
	v_fma_f32 v39, -v39, v42, v41
	v_div_fmas_f32 v39, v39, v40, v42
	v_div_fixup_f32 v34, v39, v38, v34
	v_cvt_pk_bf16_f32 v34, v34, v35
	v_mul_f32_e32 v35, 0x3d372713, v36
	v_mul_f32_e32 v35, v36, v35
	v_fma_f32 v35, v36, v35, v36
	v_mul_f32_e32 v35, 0x3f4c422a, v35
	v_mul_f32_e32 v35, -2.0, v35
	v_mul_f32_e32 v35, 0x3fb8aa3b, v35
	v_exp_f32_e32 v38, v35
	v_mul_f32_e32 v35, 0x3d372713, v37
	v_mul_f32_e32 v35, v37, v35
	v_fma_f32 v35, v37, v35, v37
	v_mul_f32_e32 v35, 0x3f4c422a, v35
	v_mul_f32_e32 v35, -2.0, v35
	v_mul_f32_e32 v35, 0x3fb8aa3b, v35
	v_exp_f32_e32 v39, v35
	s_nop 0
	v_pk_add_f32 v[38:39], v[38:39], 1.0 op_sel_hi:[1,0]
	s_nop 0
	v_div_scale_f32 v35, s[4:5], v39, v39, v37
	v_rcp_f32_e32 v40, v35
	s_nop 0
	v_fma_f32 v41, -v35, v40, 1.0
	v_fmac_f32_e32 v40, v41, v40
	v_div_scale_f32 v41, vcc, v37, v39, v37
	v_mul_f32_e32 v42, v41, v40
	v_fma_f32 v43, -v35, v42, v41
	v_fmac_f32_e32 v42, v43, v40
	v_fma_f32 v35, -v35, v42, v41
	v_div_fmas_f32 v35, v35, v40, v42
	v_div_fixup_f32 v35, v35, v39, v37
	v_div_scale_f32 v37, s[4:5], v38, v38, v36
	v_rcp_f32_e32 v39, v37
	s_nop 0
	v_fma_f32 v40, -v37, v39, 1.0
	v_fmac_f32_e32 v39, v40, v39
	v_div_scale_f32 v40, vcc, v36, v38, v36
	v_mul_f32_e32 v41, v40, v39
	v_fma_f32 v42, -v37, v41, v40
	v_fmac_f32_e32 v41, v42, v39
	v_fma_f32 v37, -v37, v41, v40
	v_div_fmas_f32 v37, v37, v39, v41
	v_div_fixup_f32 v36, v37, v38, v36
	v_cvt_pk_bf16_f32 v35, v36, v35
	v_lshl_add_u64 v[36:37], v[52:53], 0, v[50:51]
	v_lshlrev_b64 v[36:37], 5, v[36:37]
	v_lshl_add_u64 v[36:37], v[66:67], 0, v[36:37]
	global_store_dwordx2 v[36:37], v[34:35], off
	v_mul_f32_e32 v36, 0x3d372713, v30
	v_mul_f32_e32 v37, 0x3d372713, v31
	v_mul_f32_e32 v36, v30, v36
	v_mul_f32_e32 v37, v31, v37
	v_fma_f32 v36, v30, v36, v30
	v_fma_f32 v37, v31, v37, v31
	v_mul_f32_e32 v36, 0x3f4c422a, v36
	v_mul_f32_e32 v37, 0x3f4c422a, v37
	v_mul_f32_e32 v36, -2.0, v36
	v_mul_f32_e32 v37, -2.0, v37
	v_mul_f32_e32 v36, 0x3fb8aa3b, v36
	v_mul_f32_e32 v37, 0x3fb8aa3b, v37
	v_exp_f32_e32 v36, v36
	v_exp_f32_e32 v37, v37
	v_or_b32_e32 v34, 2, v68
	v_ashrrev_i32_e32 v35, 31, v34
	v_lshl_add_u64 v[34:35], s[2:3], 0, v[34:35]
	v_pk_add_f32 v[36:37], v[36:37], 1.0 op_sel_hi:[1,0]
	s_nop 0
	v_div_scale_f32 v38, s[4:5], v37, v37, v31
	v_rcp_f32_e32 v39, v38
	s_nop 0
	v_fma_f32 v40, -v38, v39, 1.0
	v_fmac_f32_e32 v39, v40, v39
	v_div_scale_f32 v40, vcc, v31, v37, v31
	v_mul_f32_e32 v41, v40, v39
	v_fma_f32 v42, -v38, v41, v40
	v_fmac_f32_e32 v41, v42, v39
	v_fma_f32 v38, -v38, v41, v40
	v_div_fmas_f32 v38, v38, v39, v41
	v_div_fixup_f32 v31, v38, v37, v31
	v_div_scale_f32 v37, s[4:5], v36, v36, v30
	v_rcp_f32_e32 v38, v37
	s_nop 0
	v_fma_f32 v39, -v37, v38, 1.0
	v_fmac_f32_e32 v38, v39, v38
	v_div_scale_f32 v39, vcc, v30, v36, v30
	v_mul_f32_e32 v40, v39, v38
	v_fma_f32 v41, -v37, v40, v39
	v_fmac_f32_e32 v40, v41, v38
	v_fma_f32 v37, -v37, v40, v39
	v_div_fmas_f32 v37, v37, v38, v40
	v_div_fixup_f32 v30, v37, v36, v30
	v_cvt_pk_bf16_f32 v30, v30, v31
	v_mul_f32_e32 v31, 0x3d372713, v32
	v_mul_f32_e32 v31, v32, v31
	v_fma_f32 v31, v32, v31, v32
	v_mul_f32_e32 v31, 0x3f4c422a, v31
	v_mul_f32_e32 v31, -2.0, v31
	v_mul_f32_e32 v31, 0x3fb8aa3b, v31
	v_exp_f32_e32 v36, v31
	v_mul_f32_e32 v31, 0x3d372713, v33
	v_mul_f32_e32 v31, v33, v31
	v_fma_f32 v31, v33, v31, v33
	v_mul_f32_e32 v31, 0x3f4c422a, v31
	v_mul_f32_e32 v31, -2.0, v31
	v_mul_f32_e32 v31, 0x3fb8aa3b, v31
	v_exp_f32_e32 v37, v31
	s_nop 0
	v_pk_add_f32 v[36:37], v[36:37], 1.0 op_sel_hi:[1,0]
	s_nop 0
	v_div_scale_f32 v31, s[4:5], v37, v37, v33
	v_rcp_f32_e32 v38, v31
	s_nop 0
	v_fma_f32 v39, -v31, v38, 1.0
	v_fmac_f32_e32 v38, v39, v38
	v_div_scale_f32 v39, vcc, v33, v37, v33
	v_mul_f32_e32 v40, v39, v38
	v_fma_f32 v41, -v31, v40, v39
	v_fmac_f32_e32 v40, v41, v38
	v_fma_f32 v31, -v31, v40, v39
	v_div_fmas_f32 v31, v31, v38, v40
	v_div_fixup_f32 v31, v31, v37, v33
	v_div_scale_f32 v33, s[4:5], v36, v36, v32
	v_rcp_f32_e32 v37, v33
	s_nop 0
	v_fma_f32 v38, -v33, v37, 1.0
	v_fmac_f32_e32 v37, v38, v37
	v_div_scale_f32 v38, vcc, v32, v36, v32
	v_mul_f32_e32 v39, v38, v37
	v_fma_f32 v40, -v33, v39, v38
	v_fmac_f32_e32 v39, v40, v37
	v_fma_f32 v33, -v33, v39, v38
	v_div_fmas_f32 v33, v33, v37, v39
	v_div_fixup_f32 v32, v33, v36, v32
	v_cvt_pk_bf16_f32 v31, v32, v31
	v_lshl_add_u64 v[32:33], v[34:35], 0, v[130:131]
	v_lshlrev_b64 v[32:33], 5, v[32:33]
	v_lshl_add_u64 v[32:33], v[66:67], 0, v[32:33]
	global_store_dwordx2 v[32:33], v[30:31], off
	v_mul_f32_e32 v30, 0x3d372713, v26
	v_mul_f32_e32 v31, 0x3d372713, v27
	v_mul_f32_e32 v30, v26, v30
	v_mul_f32_e32 v31, v27, v31
	v_fma_f32 v30, v26, v30, v26
	v_fma_f32 v31, v27, v31, v27
	v_mul_f32_e32 v30, 0x3f4c422a, v30
	v_mul_f32_e32 v31, 0x3f4c422a, v31
	v_mul_f32_e32 v30, -2.0, v30
	v_mul_f32_e32 v31, -2.0, v31
	v_mul_f32_e32 v30, 0x3fb8aa3b, v30
	v_mul_f32_e32 v31, 0x3fb8aa3b, v31
	v_exp_f32_e32 v30, v30
	v_exp_f32_e32 v31, v31
	s_nop 0
	v_pk_add_f32 v[30:31], v[30:31], 1.0 op_sel_hi:[1,0]
	s_nop 0
	v_div_scale_f32 v32, s[4:5], v31, v31, v27
	v_rcp_f32_e32 v33, v32
	s_nop 0
	v_fma_f32 v36, -v32, v33, 1.0
	v_fmac_f32_e32 v33, v36, v33
	v_div_scale_f32 v36, vcc, v27, v31, v27
	v_mul_f32_e32 v37, v36, v33
	v_fma_f32 v38, -v32, v37, v36
	v_fmac_f32_e32 v37, v38, v33
	v_fma_f32 v32, -v32, v37, v36
	v_div_fmas_f32 v32, v32, v33, v37
	v_div_fixup_f32 v27, v32, v31, v27
	v_div_scale_f32 v31, s[4:5], v30, v30, v26
	v_rcp_f32_e32 v32, v31
	s_nop 0
	v_fma_f32 v33, -v31, v32, 1.0
	v_fmac_f32_e32 v32, v33, v32
	v_div_scale_f32 v33, vcc, v26, v30, v26
	v_mul_f32_e32 v36, v33, v32
	v_fma_f32 v37, -v31, v36, v33
	v_fmac_f32_e32 v36, v37, v32
	v_fma_f32 v31, -v31, v36, v33
	v_div_fmas_f32 v31, v31, v32, v36
	v_div_fixup_f32 v26, v31, v30, v26
	v_cvt_pk_bf16_f32 v26, v26, v27
	v_mul_f32_e32 v27, 0x3d372713, v28
	v_mul_f32_e32 v27, v28, v27
	v_fma_f32 v27, v28, v27, v28
	v_mul_f32_e32 v27, 0x3f4c422a, v27
	v_mul_f32_e32 v27, -2.0, v27
	v_mul_f32_e32 v27, 0x3fb8aa3b, v27
	v_exp_f32_e32 v30, v27
	v_mul_f32_e32 v27, 0x3d372713, v29
	v_mul_f32_e32 v27, v29, v27
	v_fma_f32 v27, v29, v27, v29
	v_mul_f32_e32 v27, 0x3f4c422a, v27
	v_mul_f32_e32 v27, -2.0, v27
	v_mul_f32_e32 v27, 0x3fb8aa3b, v27
	v_exp_f32_e32 v31, v27
	s_nop 0
	v_pk_add_f32 v[30:31], v[30:31], 1.0 op_sel_hi:[1,0]
	s_nop 0
	v_div_scale_f32 v27, s[4:5], v31, v31, v29
	v_rcp_f32_e32 v32, v27
	s_nop 0
	v_fma_f32 v33, -v27, v32, 1.0
	v_fmac_f32_e32 v32, v33, v32
	v_div_scale_f32 v33, vcc, v29, v31, v29
	v_mul_f32_e32 v36, v33, v32
	v_fma_f32 v37, -v27, v36, v33
	v_fmac_f32_e32 v36, v37, v32
	v_fma_f32 v27, -v27, v36, v33
	v_div_fmas_f32 v27, v27, v32, v36
	v_div_fixup_f32 v27, v27, v31, v29
	v_div_scale_f32 v29, s[4:5], v30, v30, v28
	v_rcp_f32_e32 v31, v29
	s_nop 0
	v_fma_f32 v32, -v29, v31, 1.0
	v_fmac_f32_e32 v31, v32, v31
	v_div_scale_f32 v32, vcc, v28, v30, v28
	v_mul_f32_e32 v33, v32, v31
	v_fma_f32 v36, -v29, v33, v32
	v_fmac_f32_e32 v33, v36, v31
	v_fma_f32 v29, -v29, v33, v32
	v_div_fmas_f32 v29, v29, v31, v33
	v_div_fixup_f32 v28, v29, v30, v28
	v_cvt_pk_bf16_f32 v27, v28, v27
	v_lshl_add_u64 v[28:29], v[34:35], 0, v[58:59]
	v_lshlrev_b64 v[28:29], 5, v[28:29]
	v_lshl_add_u64 v[28:29], v[66:67], 0, v[28:29]
	global_store_dwordx2 v[28:29], v[26:27], off
	v_mul_f32_e32 v26, 0x3d372713, v22
	v_mul_f32_e32 v27, 0x3d372713, v23
	v_mul_f32_e32 v26, v22, v26
	v_mul_f32_e32 v27, v23, v27
	v_fma_f32 v26, v22, v26, v22
	v_fma_f32 v27, v23, v27, v23
	v_mul_f32_e32 v26, 0x3f4c422a, v26
	v_mul_f32_e32 v27, 0x3f4c422a, v27
	v_mul_f32_e32 v26, -2.0, v26
	v_mul_f32_e32 v27, -2.0, v27
	v_mul_f32_e32 v26, 0x3fb8aa3b, v26
	v_mul_f32_e32 v27, 0x3fb8aa3b, v27
	v_exp_f32_e32 v26, v26
	v_exp_f32_e32 v27, v27
	s_nop 0
	v_pk_add_f32 v[26:27], v[26:27], 1.0 op_sel_hi:[1,0]
	s_nop 0
	v_div_scale_f32 v28, s[4:5], v27, v27, v23
	v_rcp_f32_e32 v29, v28
	s_nop 0
	v_fma_f32 v30, -v28, v29, 1.0
	v_fmac_f32_e32 v29, v30, v29
	v_div_scale_f32 v30, vcc, v23, v27, v23
	v_mul_f32_e32 v31, v30, v29
	v_fma_f32 v32, -v28, v31, v30
	v_fmac_f32_e32 v31, v32, v29
	v_fma_f32 v28, -v28, v31, v30
	v_div_fmas_f32 v28, v28, v29, v31
	v_div_fixup_f32 v23, v28, v27, v23
	v_div_scale_f32 v27, s[4:5], v26, v26, v22
	v_rcp_f32_e32 v28, v27
	s_nop 0
	v_fma_f32 v29, -v27, v28, 1.0
	v_fmac_f32_e32 v28, v29, v28
	v_div_scale_f32 v29, vcc, v22, v26, v22
	v_mul_f32_e32 v30, v29, v28
	v_fma_f32 v31, -v27, v30, v29
	v_fmac_f32_e32 v30, v31, v28
	v_fma_f32 v27, -v27, v30, v29
	v_div_fmas_f32 v27, v27, v28, v30
	v_div_fixup_f32 v22, v27, v26, v22
	v_cvt_pk_bf16_f32 v22, v22, v23
	v_mul_f32_e32 v23, 0x3d372713, v24
	v_mul_f32_e32 v23, v24, v23
	v_fma_f32 v23, v24, v23, v24
	v_mul_f32_e32 v23, 0x3f4c422a, v23
	v_mul_f32_e32 v23, -2.0, v23
	v_mul_f32_e32 v23, 0x3fb8aa3b, v23
	v_exp_f32_e32 v26, v23
	v_mul_f32_e32 v23, 0x3d372713, v25
	v_mul_f32_e32 v23, v25, v23
	v_fma_f32 v23, v25, v23, v25
	v_mul_f32_e32 v23, 0x3f4c422a, v23
	v_mul_f32_e32 v23, -2.0, v23
	v_mul_f32_e32 v23, 0x3fb8aa3b, v23
	v_exp_f32_e32 v27, v23
	s_nop 0
	v_pk_add_f32 v[26:27], v[26:27], 1.0 op_sel_hi:[1,0]
	s_nop 0
	v_div_scale_f32 v23, s[4:5], v27, v27, v25
	v_rcp_f32_e32 v28, v23
	s_nop 0
	v_fma_f32 v29, -v23, v28, 1.0
	v_fmac_f32_e32 v28, v29, v28
	v_div_scale_f32 v29, vcc, v25, v27, v25
	v_mul_f32_e32 v30, v29, v28
	v_fma_f32 v31, -v23, v30, v29
	v_fmac_f32_e32 v30, v31, v28
	v_fma_f32 v23, -v23, v30, v29
	v_div_fmas_f32 v23, v23, v28, v30
	v_div_fixup_f32 v23, v23, v27, v25
	v_div_scale_f32 v25, s[4:5], v26, v26, v24
	v_rcp_f32_e32 v27, v25
	s_nop 0
	v_fma_f32 v28, -v25, v27, 1.0
	v_fmac_f32_e32 v27, v28, v27
	v_div_scale_f32 v28, vcc, v24, v26, v24
	v_mul_f32_e32 v29, v28, v27
	v_fma_f32 v30, -v25, v29, v28
	v_fmac_f32_e32 v29, v30, v27
	v_fma_f32 v25, -v25, v29, v28
	v_div_fmas_f32 v25, v25, v27, v29
	v_div_fixup_f32 v24, v25, v26, v24
	v_cvt_pk_bf16_f32 v23, v24, v23
	v_lshl_add_u64 v[24:25], v[34:35], 0, v[54:55]
	v_lshlrev_b64 v[24:25], 5, v[24:25]
	v_lshl_add_u64 v[24:25], v[66:67], 0, v[24:25]
	global_store_dwordx2 v[24:25], v[22:23], off
	v_mul_f32_e32 v22, 0x3d372713, v18
	v_mul_f32_e32 v23, 0x3d372713, v19
	v_mul_f32_e32 v22, v18, v22
	v_mul_f32_e32 v23, v19, v23
	v_fma_f32 v22, v18, v22, v18
	v_fma_f32 v23, v19, v23, v19
	v_mul_f32_e32 v22, 0x3f4c422a, v22
	v_mul_f32_e32 v23, 0x3f4c422a, v23
	v_mul_f32_e32 v22, -2.0, v22
	v_mul_f32_e32 v23, -2.0, v23
	v_mul_f32_e32 v22, 0x3fb8aa3b, v22
	v_mul_f32_e32 v23, 0x3fb8aa3b, v23
	v_exp_f32_e32 v22, v22
	v_exp_f32_e32 v23, v23
	s_nop 0
	v_pk_add_f32 v[22:23], v[22:23], 1.0 op_sel_hi:[1,0]
	s_nop 0
	v_div_scale_f32 v24, s[4:5], v23, v23, v19
	v_rcp_f32_e32 v25, v24
	s_nop 0
	v_fma_f32 v26, -v24, v25, 1.0
	v_fmac_f32_e32 v25, v26, v25
	v_div_scale_f32 v26, vcc, v19, v23, v19
	v_mul_f32_e32 v27, v26, v25
	v_fma_f32 v28, -v24, v27, v26
	v_fmac_f32_e32 v27, v28, v25
	v_fma_f32 v24, -v24, v27, v26
	v_div_fmas_f32 v24, v24, v25, v27
	v_div_fixup_f32 v19, v24, v23, v19
	v_div_scale_f32 v23, s[4:5], v22, v22, v18
	v_rcp_f32_e32 v24, v23
	s_nop 0
	v_fma_f32 v25, -v23, v24, 1.0
	v_fmac_f32_e32 v24, v25, v24
	v_div_scale_f32 v25, vcc, v18, v22, v18
	v_mul_f32_e32 v26, v25, v24
	v_fma_f32 v27, -v23, v26, v25
	v_fmac_f32_e32 v26, v27, v24
	v_fma_f32 v23, -v23, v26, v25
	v_div_fmas_f32 v23, v23, v24, v26
	v_div_fixup_f32 v18, v23, v22, v18
	v_cvt_pk_bf16_f32 v18, v18, v19
	v_mul_f32_e32 v19, 0x3d372713, v20
	v_mul_f32_e32 v19, v20, v19
	v_fma_f32 v19, v20, v19, v20
	v_mul_f32_e32 v19, 0x3f4c422a, v19
	v_mul_f32_e32 v19, -2.0, v19
	v_mul_f32_e32 v19, 0x3fb8aa3b, v19
	v_exp_f32_e32 v22, v19
	v_mul_f32_e32 v19, 0x3d372713, v21
	v_mul_f32_e32 v19, v21, v19
	v_fma_f32 v19, v21, v19, v21
	v_mul_f32_e32 v19, 0x3f4c422a, v19
	v_mul_f32_e32 v19, -2.0, v19
	v_mul_f32_e32 v19, 0x3fb8aa3b, v19
	v_exp_f32_e32 v23, v19
	s_nop 0
	v_pk_add_f32 v[22:23], v[22:23], 1.0 op_sel_hi:[1,0]
	s_nop 0
	v_div_scale_f32 v19, s[4:5], v23, v23, v21
	v_rcp_f32_e32 v24, v19
	s_nop 0
	v_fma_f32 v25, -v19, v24, 1.0
	v_fmac_f32_e32 v24, v25, v24
	v_div_scale_f32 v25, vcc, v21, v23, v21
	v_mul_f32_e32 v26, v25, v24
	v_fma_f32 v27, -v19, v26, v25
	v_fmac_f32_e32 v26, v27, v24
	v_fma_f32 v19, -v19, v26, v25
	v_div_fmas_f32 v19, v19, v24, v26
	v_div_fixup_f32 v19, v19, v23, v21
	v_div_scale_f32 v21, s[4:5], v22, v22, v20
	v_rcp_f32_e32 v23, v21
	s_nop 0
	v_fma_f32 v24, -v21, v23, 1.0
	v_fmac_f32_e32 v23, v24, v23
	v_div_scale_f32 v24, vcc, v20, v22, v20
	v_mul_f32_e32 v25, v24, v23
	v_fma_f32 v26, -v21, v25, v24
	v_fmac_f32_e32 v25, v26, v23
	v_fma_f32 v21, -v21, v25, v24
	v_div_fmas_f32 v21, v21, v23, v25
	v_div_fixup_f32 v20, v21, v22, v20
	v_cvt_pk_bf16_f32 v19, v20, v19
	v_lshl_add_u64 v[20:21], v[34:35], 0, v[50:51]
	v_lshlrev_b64 v[20:21], 5, v[20:21]
	v_lshl_add_u64 v[20:21], v[66:67], 0, v[20:21]
	global_store_dwordx2 v[20:21], v[18:19], off
	v_or_b32_e32 v18, 3, v1
	v_mul_f32_e32 v1, 0x3d372713, v14
	v_mul_f32_e32 v1, v14, v1
	v_fma_f32 v1, v14, v1, v14
	v_mul_f32_e32 v1, 0x3f4c422a, v1
	v_mul_f32_e32 v1, -2.0, v1
	v_mul_f32_e32 v1, 0x3fb8aa3b, v1
	v_exp_f32_e32 v20, v1
	v_mul_f32_e32 v1, 0x3d372713, v15
	v_mul_f32_e32 v1, v15, v1
	v_fma_f32 v1, v15, v1, v15
	v_mul_f32_e32 v1, 0x3f4c422a, v1
	v_mul_f32_e32 v1, -2.0, v1
	v_mul_f32_e32 v1, 0x3fb8aa3b, v1
	v_exp_f32_e32 v21, v1
	v_ashrrev_i32_e32 v19, 31, v18
	v_lshl_add_u64 v[18:19], s[2:3], 0, v[18:19]
	v_pk_add_f32 v[20:21], v[20:21], 1.0 op_sel_hi:[1,0]
	s_nop 0
	v_div_scale_f32 v1, s[2:3], v21, v21, v15
	v_rcp_f32_e32 v22, v1
	s_nop 0
	v_fma_f32 v23, -v1, v22, 1.0
	v_fmac_f32_e32 v22, v23, v22
	v_div_scale_f32 v23, vcc, v15, v21, v15
	v_mul_f32_e32 v24, v23, v22
	v_fma_f32 v25, -v1, v24, v23
	v_fmac_f32_e32 v24, v25, v22
	v_fma_f32 v1, -v1, v24, v23
	v_div_fmas_f32 v1, v1, v22, v24
	v_div_fixup_f32 v1, v1, v21, v15
	v_div_scale_f32 v15, s[2:3], v20, v20, v14
	v_rcp_f32_e32 v21, v15
	s_nop 0
	v_fma_f32 v22, -v15, v21, 1.0
	v_fmac_f32_e32 v21, v22, v21
	v_div_scale_f32 v22, vcc, v14, v20, v14
	v_mul_f32_e32 v23, v22, v21
	v_fma_f32 v24, -v15, v23, v22
	v_fmac_f32_e32 v23, v24, v21
	v_fma_f32 v15, -v15, v23, v22
	v_div_fmas_f32 v15, v15, v21, v23
	v_div_fixup_f32 v14, v15, v20, v14
	v_cvt_pk_bf16_f32 v14, v14, v1
	v_mul_f32_e32 v1, 0x3d372713, v16
	v_mul_f32_e32 v1, v16, v1
	v_fma_f32 v1, v16, v1, v16
	v_mul_f32_e32 v1, 0x3f4c422a, v1
	v_mul_f32_e32 v1, -2.0, v1
	v_mul_f32_e32 v1, 0x3fb8aa3b, v1
	v_exp_f32_e32 v20, v1
	v_mul_f32_e32 v1, 0x3d372713, v17
	v_mul_f32_e32 v1, v17, v1
	v_fma_f32 v1, v17, v1, v17
	v_mul_f32_e32 v1, 0x3f4c422a, v1
	v_mul_f32_e32 v1, -2.0, v1
	v_mul_f32_e32 v1, 0x3fb8aa3b, v1
	v_exp_f32_e32 v21, v1
	s_nop 0
	v_pk_add_f32 v[20:21], v[20:21], 1.0 op_sel_hi:[1,0]
	s_nop 0
	v_div_scale_f32 v1, s[2:3], v21, v21, v17
	v_rcp_f32_e32 v15, v1
	s_nop 0
	v_fma_f32 v22, -v1, v15, 1.0
	v_fmac_f32_e32 v15, v22, v15
	v_div_scale_f32 v22, vcc, v17, v21, v17
	v_mul_f32_e32 v23, v22, v15
	v_fma_f32 v24, -v1, v23, v22
	v_fmac_f32_e32 v23, v24, v15
	v_fma_f32 v1, -v1, v23, v22
	v_div_fmas_f32 v1, v1, v15, v23
	v_div_scale_f32 v15, s[2:3], v20, v20, v16
	v_div_fixup_f32 v1, v1, v21, v17
	v_rcp_f32_e32 v17, v15
	s_nop 0
	v_fma_f32 v21, -v15, v17, 1.0
	v_fmac_f32_e32 v17, v21, v17
	v_div_scale_f32 v21, vcc, v16, v20, v16
	v_mul_f32_e32 v22, v21, v17
	v_fma_f32 v23, -v15, v22, v21
	v_fmac_f32_e32 v22, v23, v17
	v_fma_f32 v15, -v15, v22, v21
	v_div_fmas_f32 v15, v15, v17, v22
	v_div_fixup_f32 v15, v15, v20, v16
	v_cvt_pk_bf16_f32 v15, v15, v1
	v_mul_f32_e32 v1, 0x3d372713, v10
	v_mul_f32_e32 v1, v10, v1
	v_fma_f32 v1, v10, v1, v10
	v_lshl_add_u64 v[16:17], v[18:19], 0, v[130:131]
	v_mul_f32_e32 v1, 0x3f4c422a, v1
	v_lshlrev_b64 v[16:17], 5, v[16:17]
	v_mul_f32_e32 v1, -2.0, v1
	v_lshl_add_u64 v[16:17], v[66:67], 0, v[16:17]
	v_mul_f32_e32 v1, 0x3fb8aa3b, v1
	global_store_dwordx2 v[16:17], v[14:15], off
	v_exp_f32_e32 v14, v1
	v_mul_f32_e32 v1, 0x3d372713, v11
	v_mul_f32_e32 v1, v11, v1
	v_fma_f32 v1, v11, v1, v11
	v_mul_f32_e32 v1, 0x3f4c422a, v1
	v_mul_f32_e32 v1, -2.0, v1
	v_mul_f32_e32 v1, 0x3fb8aa3b, v1
	v_exp_f32_e32 v15, v1
	s_nop 0
	v_pk_add_f32 v[14:15], v[14:15], 1.0 op_sel_hi:[1,0]
	s_nop 0
	v_div_scale_f32 v1, s[2:3], v15, v15, v11
	v_rcp_f32_e32 v16, v1
	s_nop 0
	v_fma_f32 v17, -v1, v16, 1.0
	v_fmac_f32_e32 v16, v17, v16
	v_div_scale_f32 v17, vcc, v11, v15, v11
	v_mul_f32_e32 v20, v17, v16
	v_fma_f32 v21, -v1, v20, v17
	v_fmac_f32_e32 v20, v21, v16
	v_fma_f32 v1, -v1, v20, v17
	v_div_fmas_f32 v1, v1, v16, v20
	v_div_fixup_f32 v1, v1, v15, v11
	v_div_scale_f32 v11, s[2:3], v14, v14, v10
	v_rcp_f32_e32 v15, v11
	s_nop 0
	v_fma_f32 v16, -v11, v15, 1.0
	v_fmac_f32_e32 v15, v16, v15
	v_div_scale_f32 v16, vcc, v10, v14, v10
	v_mul_f32_e32 v17, v16, v15
	v_fma_f32 v20, -v11, v17, v16
	v_fmac_f32_e32 v17, v20, v15
	v_fma_f32 v11, -v11, v17, v16
	v_div_fmas_f32 v11, v11, v15, v17
	v_div_fixup_f32 v10, v11, v14, v10
	v_cvt_pk_bf16_f32 v10, v10, v1
	v_mul_f32_e32 v1, 0x3d372713, v12
	v_mul_f32_e32 v1, v12, v1
	v_fma_f32 v1, v12, v1, v12
	v_mul_f32_e32 v1, 0x3f4c422a, v1
	v_mul_f32_e32 v1, -2.0, v1
	v_mul_f32_e32 v1, 0x3fb8aa3b, v1
	v_exp_f32_e32 v14, v1
	v_mul_f32_e32 v1, 0x3d372713, v13
	v_mul_f32_e32 v1, v13, v1
	v_fma_f32 v1, v13, v1, v13
	v_mul_f32_e32 v1, 0x3f4c422a, v1
	v_mul_f32_e32 v1, -2.0, v1
	v_mul_f32_e32 v1, 0x3fb8aa3b, v1
	v_exp_f32_e32 v15, v1
	s_nop 0
	v_pk_add_f32 v[14:15], v[14:15], 1.0 op_sel_hi:[1,0]
	s_nop 0
	v_div_scale_f32 v1, s[2:3], v15, v15, v13
	v_rcp_f32_e32 v11, v1
	s_nop 0
	v_fma_f32 v16, -v1, v11, 1.0
	v_fmac_f32_e32 v11, v16, v11
	v_div_scale_f32 v16, vcc, v13, v15, v13
	v_mul_f32_e32 v17, v16, v11
	v_fma_f32 v20, -v1, v17, v16
	v_fmac_f32_e32 v17, v20, v11
	v_fma_f32 v1, -v1, v17, v16
	v_div_fmas_f32 v1, v1, v11, v17
	v_div_scale_f32 v11, s[2:3], v14, v14, v12
	v_div_fixup_f32 v1, v1, v15, v13
	v_rcp_f32_e32 v13, v11
	s_nop 0
	v_fma_f32 v15, -v11, v13, 1.0
	v_fmac_f32_e32 v13, v15, v13
	v_div_scale_f32 v15, vcc, v12, v14, v12
	v_mul_f32_e32 v16, v15, v13
	v_fma_f32 v17, -v11, v16, v15
	v_fmac_f32_e32 v16, v17, v13
	v_fma_f32 v11, -v11, v16, v15
	v_div_fmas_f32 v11, v11, v13, v16
	v_div_fixup_f32 v11, v11, v14, v12
	v_cvt_pk_bf16_f32 v11, v11, v1
	v_mul_f32_e32 v1, 0x3d372713, v6
	v_mul_f32_e32 v1, v6, v1
	v_fma_f32 v1, v6, v1, v6
	v_lshl_add_u64 v[12:13], v[18:19], 0, v[58:59]
	v_mul_f32_e32 v1, 0x3f4c422a, v1
	v_lshlrev_b64 v[12:13], 5, v[12:13]
	v_mul_f32_e32 v1, -2.0, v1
	v_lshl_add_u64 v[12:13], v[66:67], 0, v[12:13]
	v_mul_f32_e32 v1, 0x3fb8aa3b, v1
	global_store_dwordx2 v[12:13], v[10:11], off
	v_exp_f32_e32 v10, v1
	v_mul_f32_e32 v1, 0x3d372713, v7
	v_mul_f32_e32 v1, v7, v1
	v_fma_f32 v1, v7, v1, v7
	v_mul_f32_e32 v1, 0x3f4c422a, v1
	v_mul_f32_e32 v1, -2.0, v1
	v_mul_f32_e32 v1, 0x3fb8aa3b, v1
	v_exp_f32_e32 v11, v1
	s_nop 0
	v_pk_add_f32 v[10:11], v[10:11], 1.0 op_sel_hi:[1,0]
	s_nop 0
	v_div_scale_f32 v1, s[2:3], v11, v11, v7
	v_rcp_f32_e32 v12, v1
	s_nop 0
	v_fma_f32 v13, -v1, v12, 1.0
	v_fmac_f32_e32 v12, v13, v12
	v_div_scale_f32 v13, vcc, v7, v11, v7
	v_mul_f32_e32 v14, v13, v12
	v_fma_f32 v15, -v1, v14, v13
	v_fmac_f32_e32 v14, v15, v12
	v_fma_f32 v1, -v1, v14, v13
	v_div_fmas_f32 v1, v1, v12, v14
	v_div_fixup_f32 v1, v1, v11, v7
	v_div_scale_f32 v7, s[2:3], v10, v10, v6
	v_rcp_f32_e32 v11, v7
	s_nop 0
	v_fma_f32 v12, -v7, v11, 1.0
	v_fmac_f32_e32 v11, v12, v11
	v_div_scale_f32 v12, vcc, v6, v10, v6
	v_mul_f32_e32 v13, v12, v11
	v_fma_f32 v14, -v7, v13, v12
	v_fmac_f32_e32 v13, v14, v11
	v_fma_f32 v7, -v7, v13, v12
	v_div_fmas_f32 v7, v7, v11, v13
	v_div_fixup_f32 v6, v7, v10, v6
	v_cvt_pk_bf16_f32 v6, v6, v1
	v_mul_f32_e32 v1, 0x3d372713, v8
	v_mul_f32_e32 v1, v8, v1
	v_fma_f32 v1, v8, v1, v8
	v_mul_f32_e32 v1, 0x3f4c422a, v1
	v_mul_f32_e32 v1, -2.0, v1
	v_mul_f32_e32 v1, 0x3fb8aa3b, v1
	v_exp_f32_e32 v10, v1
	v_mul_f32_e32 v1, 0x3d372713, v9
	v_mul_f32_e32 v1, v9, v1
	v_fma_f32 v1, v9, v1, v9
	v_mul_f32_e32 v1, 0x3f4c422a, v1
	v_mul_f32_e32 v1, -2.0, v1
	v_mul_f32_e32 v1, 0x3fb8aa3b, v1
	v_exp_f32_e32 v11, v1
	s_nop 0
	v_pk_add_f32 v[10:11], v[10:11], 1.0 op_sel_hi:[1,0]
	s_nop 0
	v_div_scale_f32 v1, s[2:3], v11, v11, v9
	v_rcp_f32_e32 v7, v1
	s_nop 0
	v_fma_f32 v12, -v1, v7, 1.0
	v_fmac_f32_e32 v7, v12, v7
	v_div_scale_f32 v12, vcc, v9, v11, v9
	v_mul_f32_e32 v13, v12, v7
	v_fma_f32 v14, -v1, v13, v12
	v_fmac_f32_e32 v13, v14, v7
	v_fma_f32 v1, -v1, v13, v12
	v_div_fmas_f32 v1, v1, v7, v13
	v_div_scale_f32 v7, s[2:3], v10, v10, v8
	v_div_fixup_f32 v1, v1, v11, v9
	v_rcp_f32_e32 v9, v7
	s_nop 0
	v_fma_f32 v11, -v7, v9, 1.0
	v_fmac_f32_e32 v9, v11, v9
	v_div_scale_f32 v11, vcc, v8, v10, v8
	v_mul_f32_e32 v12, v11, v9
	v_fma_f32 v13, -v7, v12, v11
	v_fmac_f32_e32 v12, v13, v9
	v_fma_f32 v7, -v7, v12, v11
	v_div_fmas_f32 v7, v7, v9, v12
	v_div_fixup_f32 v7, v7, v10, v8
	v_cvt_pk_bf16_f32 v7, v7, v1
	v_mul_f32_e32 v1, 0x3d372713, v2
	v_mul_f32_e32 v1, v2, v1
	v_fma_f32 v1, v2, v1, v2
	v_lshl_add_u64 v[8:9], v[18:19], 0, v[54:55]
	v_mul_f32_e32 v1, 0x3f4c422a, v1
	v_lshlrev_b64 v[8:9], 5, v[8:9]
	v_mul_f32_e32 v1, -2.0, v1
	v_lshl_add_u64 v[8:9], v[66:67], 0, v[8:9]
	v_mul_f32_e32 v1, 0x3fb8aa3b, v1
	global_store_dwordx2 v[8:9], v[6:7], off
	v_exp_f32_e32 v6, v1
	v_mul_f32_e32 v1, 0x3d372713, v3
	v_mul_f32_e32 v1, v3, v1
	v_fma_f32 v1, v3, v1, v3
	v_mul_f32_e32 v1, 0x3f4c422a, v1
	v_mul_f32_e32 v1, -2.0, v1
	v_mul_f32_e32 v1, 0x3fb8aa3b, v1
	v_exp_f32_e32 v7, v1
	s_nop 0
	v_pk_add_f32 v[6:7], v[6:7], 1.0 op_sel_hi:[1,0]
	s_nop 0
	v_div_scale_f32 v1, s[2:3], v7, v7, v3
	v_rcp_f32_e32 v8, v1
	s_nop 0
	v_fma_f32 v9, -v1, v8, 1.0
	v_fmac_f32_e32 v8, v9, v8
	v_div_scale_f32 v9, vcc, v3, v7, v3
	v_mul_f32_e32 v10, v9, v8
	v_fma_f32 v11, -v1, v10, v9
	v_fmac_f32_e32 v10, v11, v8
	v_fma_f32 v1, -v1, v10, v9
	v_div_fmas_f32 v1, v1, v8, v10
	v_div_fixup_f32 v1, v1, v7, v3
	v_div_scale_f32 v3, s[2:3], v6, v6, v2
	v_rcp_f32_e32 v7, v3
	s_nop 0
	v_fma_f32 v8, -v3, v7, 1.0
	v_fmac_f32_e32 v7, v8, v7
	v_div_scale_f32 v8, vcc, v2, v6, v2
	v_mul_f32_e32 v9, v8, v7
	v_fma_f32 v10, -v3, v9, v8
	v_fmac_f32_e32 v9, v10, v7
	v_fma_f32 v3, -v3, v9, v8
	v_div_fmas_f32 v3, v3, v7, v9
	v_div_fixup_f32 v2, v3, v6, v2
	v_cvt_pk_bf16_f32 v2, v2, v1
	v_mul_f32_e32 v1, 0x3d372713, v4
	v_mul_f32_e32 v1, v4, v1
	v_fma_f32 v1, v4, v1, v4
	v_mul_f32_e32 v1, 0x3f4c422a, v1
	v_mul_f32_e32 v1, -2.0, v1
	v_mul_f32_e32 v1, 0x3fb8aa3b, v1
	v_exp_f32_e32 v6, v1
	v_mul_f32_e32 v1, 0x3d372713, v5
	v_mul_f32_e32 v1, v5, v1
	v_fma_f32 v1, v5, v1, v5
	v_mul_f32_e32 v1, 0x3f4c422a, v1
	v_mul_f32_e32 v1, -2.0, v1
	v_mul_f32_e32 v1, 0x3fb8aa3b, v1
	v_exp_f32_e32 v7, v1
	s_nop 0
	v_pk_add_f32 v[6:7], v[6:7], 1.0 op_sel_hi:[1,0]
	s_nop 0
	v_div_scale_f32 v1, s[2:3], v7, v7, v5
	v_rcp_f32_e32 v3, v1
	s_nop 0
	v_fma_f32 v8, -v1, v3, 1.0
	v_fmac_f32_e32 v3, v8, v3
	v_div_scale_f32 v8, vcc, v5, v7, v5
	v_mul_f32_e32 v9, v8, v3
	v_fma_f32 v10, -v1, v9, v8
	v_fmac_f32_e32 v9, v10, v3
	v_fma_f32 v1, -v1, v9, v8
	v_div_fmas_f32 v1, v1, v3, v9
	v_div_scale_f32 v3, s[2:3], v6, v6, v4
	v_div_fixup_f32 v1, v1, v7, v5
	v_rcp_f32_e32 v5, v3
	s_nop 0
	v_fma_f32 v7, -v3, v5, 1.0
	v_fmac_f32_e32 v5, v7, v5
	v_div_scale_f32 v7, vcc, v4, v6, v4
	v_mul_f32_e32 v8, v7, v5
	v_fma_f32 v9, -v3, v8, v7
	v_fmac_f32_e32 v8, v9, v5
	v_fma_f32 v3, -v3, v8, v7
	v_div_fmas_f32 v3, v3, v5, v8
	v_div_fixup_f32 v3, v3, v6, v4
	v_lshl_add_u64 v[4:5], v[18:19], 0, v[50:51]
	v_lshlrev_b64 v[4:5], 5, v[4:5]
	v_cvt_pk_bf16_f32 v3, v3, v1
	v_lshl_add_u64 v[4:5], v[66:67], 0, v[4:5]
	global_store_dwordx2 v[4:5], v[2:3], off
	s_barrier

.LBB0_430:
	s_or_b64 exec, exec, s[0:1]
	s_lshl_b32 s7, s3, 5
	s_and_b32 s18, s7, 0x100
	v_readlane_b32 s7, v253, 61
	v_ashrrev_i32_e32 v98, 4, v6
	v_and_b32_e32 v99, 15, v6
	s_add_u32 s19, s7, s18
	v_readlane_b32 s7, v253, 62
	v_add_u32_e32 v100, s4, v98
	s_addc_u32 s18, s7, 0
	v_lshlrev_b32_e32 v98, 4, v99
	v_ashrrev_i32_e32 v101, 31, v100
	s_mov_b32 s62, s19
	s_mov_b32 s63, s18
	v_mov_b32_e32 v102, v98
	v_mov_b32_e32 v103, v131
	v_lshl_add_u64 v[104:105], s[62:63], 0, v[102:103]
	v_lshlrev_b64 v[102:103], 9, v[100:101]
	v_lshl_add_u64 v[100:101], v[104:105], 0, v[102:103]
	global_load_dwordx4 v[106:109], v[100:101], off
	v_add_u32_e32 v98, 0x100, v6
	v_ashrrev_i32_e32 v100, 4, v98
	s_lshl_b32 s7, s3, 6
	v_bfe_u32 v98, v6, 4, 2
	v_lshlrev_b32_e32 v101, 4, v98
	v_add_u32_e32 v98, s4, v100
	v_ashrrev_i32_e32 v100, 31, v98
	v_mov_b32_e32 v102, v98
	v_mov_b32_e32 v103, v100
	v_lshlrev_b64 v[110:111], 9, v[102:103]
	v_lshl_add_u64 v[102:103], v[104:105], 0, v[110:111]
	global_load_dwordx4 v[110:113], v[102:103], off
	v_add_u32_e32 v98, 0x200, v6
	v_ashrrev_i32_e32 v100, 4, v98
	v_add_u32_e32 v98, s4, v100
	v_ashrrev_i32_e32 v100, 31, v98
	v_mov_b32_e32 v102, v98
	v_mov_b32_e32 v103, v100
	v_lshlrev_b64 v[114:115], 9, v[102:103]
	v_lshl_add_u64 v[102:103], v[104:105], 0, v[114:115]
	global_load_dwordx4 v[114:117], v[102:103], off
	v_add_u32_e32 v98, 0x300, v6
	v_ashrrev_i32_e32 v100, 4, v98
	v_add_u32_e32 v98, s4, v100
	v_ashrrev_i32_e32 v100, 31, v98
	v_mov_b32_e32 v102, v98
	v_mov_b32_e32 v103, v100
	v_lshlrev_b64 v[118:119], 9, v[102:103]
	v_lshl_add_u64 v[102:103], v[104:105], 0, v[118:119]
	global_load_dwordx4 v[118:121], v[102:103], off
	v_add_u32_e32 v98, 0x400, v6
	v_ashrrev_i32_e32 v100, 4, v98
	v_add_u32_e32 v98, s4, v100
	v_ashrrev_i32_e32 v100, 31, v98
	v_mov_b32_e32 v102, v98
	v_mov_b32_e32 v103, v100
	v_lshlrev_b64 v[122:123], 9, v[102:103]
	v_lshl_add_u64 v[102:103], v[104:105], 0, v[122:123]
	global_load_dwordx4 v[122:125], v[102:103], off
	v_add_u32_e32 v98, 0x500, v6
	v_ashrrev_i32_e32 v100, 4, v98
	v_add_u32_e32 v98, s4, v100
	v_ashrrev_i32_e32 v100, 31, v98
	v_mov_b32_e32 v102, v98
	v_mov_b32_e32 v103, v100
	v_lshlrev_b64 v[126:127], 9, v[102:103]
	v_lshl_add_u64 v[102:103], v[104:105], 0, v[126:127]
	global_load_dwordx4 v[126:129], v[102:103], off
	v_add_u32_e32 v98, 0x600, v6
	v_ashrrev_i32_e32 v100, 4, v98
	v_add_u32_e32 v98, s4, v100
	v_ashrrev_i32_e32 v100, 31, v98
	v_mov_b32_e32 v102, v98
	v_mov_b32_e32 v103, v100
	v_lshlrev_b64 v[138:139], 9, v[102:103]
	v_lshl_add_u64 v[102:103], v[104:105], 0, v[138:139]
	global_load_dwordx4 v[138:141], v[102:103], off
	v_add_u32_e32 v98, 0x700, v6
	v_ashrrev_i32_e32 v100, 4, v98
	v_add_u32_e32 v98, s4, v100
	v_ashrrev_i32_e32 v100, 31, v98
	v_mov_b32_e32 v102, v98
	v_mov_b32_e32 v103, v100
	v_lshlrev_b64 v[142:143], 9, v[102:103]
	v_lshl_add_u64 v[102:103], v[104:105], 0, v[142:143]
	global_load_dwordx4 v[142:145], v[102:103], off
	v_readlane_b32 s18, v253, 37
	v_readlane_b32 s19, v253, 38
	v_ashrrev_i32_e32 v98, 2, v6
	v_and_b32_e32 v100, -16, v98
	v_ashrrev_i32_e32 v98, 31, v100
	v_mov_b32_e32 v102, v100
	v_mov_b32_e32 v103, v98
	s_mov_b32 s62, s7
	s_mov_b32 s63, s89
	v_lshl_add_u64 v[104:105], v[102:103], 0, s[62:63]
	v_or_b32_e32 v98, v104, v99
	v_mov_b32_e32 v102, v98
	v_mov_b32_e32 v103, v105
	v_lshlrev_b64 v[146:147], 8, v[102:103]
	v_lshl_add_u64 v[98:99], s[18:19], 0, v[146:147]
	v_mov_b32_e32 v102, v101
	v_mov_b32_e32 v103, v131
	v_lshl_add_u64 v[104:105], v[98:99], 0, v[102:103]
	global_load_dwordx4 v[98:101], v[104:105], off
	global_load_dwordx4 v[146:149], v[104:105], off offset:64
	global_load_dwordx4 v[150:153], v[104:105], off offset:128
	global_load_dwordx4 v[154:157], v[104:105], off offset:192
	s_lshl_b32 s0, s3, 5
	s_and_b32 s0, s0, 0x100
	v_readlane_b32 s1, v253, 61
	v_ashrrev_i32_e32 v5, 4, v6
	v_and_b32_e32 v74, 15, v6
	s_add_u32 s0, s1, s0
	v_readlane_b32 s1, v253, 62
	v_add_u32_e32 v8, s4, v5
	s_addc_u32 s1, s1, 0
	v_lshlrev_b32_e32 v130, 4, v74
	v_ashrrev_i32_e32 v9, 31, v8
	v_lshl_add_u64 v[2:3], s[0:1], 0, v[130:131]
	v_lshlrev_b64 v[8:9], 9, v[8:9]
	v_lshl_add_u64 v[8:9], v[2:3], 0, v[8:9]
	v_bitop3_b32 v4, v4, v6, 15 bitop3:0x78
	v_lshlrev_b32_e32 v4, 4, v4
	s_movk_i32 s0, 0x880
	v_mad_u32_u24 v4, v74, s0, v4
	v_lshlrev_b32_e32 v5, 1, v5
	v_add_u32_e32 v12, 0x100, v6
	v_and_or_b32 v4, v5, 14, v4
	v_ashrrev_i32_e32 v13, 4, v12
	s_lshl_b32 s88, s3, 6
	v_bfe_u32 v1, v6, 4, 2
	v_lshlrev_b32_e32 v130, 4, v1
	v_lshlrev_b32_e32 v82, 5, v1
	v_lshrrev_b32_e32 v7, 4, v6
	v_or_b32_e32 v83, 4, v1
	s_waitcnt vmcnt(0)
	ds_write_b16 v4, v106
	ds_write_b16_d16_hi v4, v106 offset:272
	ds_write_b16 v4, v107 offset:544
	ds_write_b16_d16_hi v4, v107 offset:816
	ds_write_b16 v4, v108 offset:1088
	ds_write_b16_d16_hi v4, v108 offset:1360
	ds_write_b16 v4, v109 offset:1632
	ds_write_b16_d16_hi v4, v109 offset:1904
	v_add_u32_e32 v4, s4, v13
	v_ashrrev_i32_e32 v5, 31, v4
	v_lshlrev_b64 v[4:5], 9, v[4:5]
	v_lshl_add_u64 v[4:5], v[2:3], 0, v[4:5]
	v_ashrrev_i32_e32 v4, 7, v12
	v_bitop3_b32 v4, v4, v6, 15 bitop3:0x78
	v_lshlrev_b32_e32 v4, 4, v4
	v_mad_u32_u24 v4, v74, s0, v4
	v_lshlrev_b32_e32 v5, 1, v13
	v_add_u32_e32 v12, 0x200, v6
	v_and_or_b32 v4, v5, 14, v4
	v_ashrrev_i32_e32 v13, 4, v12
	ds_write_b16 v4, v110
	ds_write_b16_d16_hi v4, v110 offset:272
	ds_write_b16 v4, v111 offset:544
	ds_write_b16_d16_hi v4, v111 offset:816
	ds_write_b16 v4, v112 offset:1088
	ds_write_b16_d16_hi v4, v112 offset:1360
	ds_write_b16 v4, v113 offset:1632
	ds_write_b16_d16_hi v4, v113 offset:1904
	v_add_u32_e32 v4, s4, v13
	v_ashrrev_i32_e32 v5, 31, v4
	v_lshlrev_b64 v[4:5], 9, v[4:5]
	v_lshl_add_u64 v[4:5], v[2:3], 0, v[4:5]
	v_ashrrev_i32_e32 v4, 7, v12
	v_bitop3_b32 v4, v4, v6, 15 bitop3:0x78
	v_lshlrev_b32_e32 v4, 4, v4
	v_mad_u32_u24 v4, v74, s0, v4
	v_lshlrev_b32_e32 v5, 1, v13
	v_add_u32_e32 v12, 0x300, v6
	v_and_or_b32 v4, v5, 14, v4
	v_ashrrev_i32_e32 v13, 4, v12
	ds_write_b16 v4, v114
	ds_write_b16_d16_hi v4, v114 offset:272
	ds_write_b16 v4, v115 offset:544
	ds_write_b16_d16_hi v4, v115 offset:816
	ds_write_b16 v4, v116 offset:1088
	ds_write_b16_d16_hi v4, v116 offset:1360
	ds_write_b16 v4, v117 offset:1632
	ds_write_b16_d16_hi v4, v117 offset:1904
	v_add_u32_e32 v4, s4, v13
	v_ashrrev_i32_e32 v5, 31, v4
	v_lshlrev_b64 v[4:5], 9, v[4:5]
	v_lshl_add_u64 v[4:5], v[2:3], 0, v[4:5]
	v_ashrrev_i32_e32 v4, 7, v12
	v_bitop3_b32 v4, v4, v6, 15 bitop3:0x78
	v_lshlrev_b32_e32 v4, 4, v4
	v_mad_u32_u24 v4, v74, s0, v4
	v_lshlrev_b32_e32 v5, 1, v13
	v_add_u32_e32 v12, 0x400, v6
	v_and_or_b32 v4, v5, 14, v4
	v_ashrrev_i32_e32 v13, 4, v12
	ds_write_b16 v4, v118
	ds_write_b16_d16_hi v4, v118 offset:272
	ds_write_b16 v4, v119 offset:544
	ds_write_b16_d16_hi v4, v119 offset:816
	ds_write_b16 v4, v120 offset:1088
	ds_write_b16_d16_hi v4, v120 offset:1360
	ds_write_b16 v4, v121 offset:1632
	ds_write_b16_d16_hi v4, v121 offset:1904
	v_add_u32_e32 v4, s4, v13
	v_ashrrev_i32_e32 v5, 31, v4
	v_lshlrev_b64 v[4:5], 9, v[4:5]
	v_lshl_add_u64 v[4:5], v[2:3], 0, v[4:5]
	v_ashrrev_i32_e32 v4, 7, v12
	v_bitop3_b32 v4, v4, v6, 15 bitop3:0x78
	v_lshlrev_b32_e32 v4, 4, v4
	v_mad_u32_u24 v4, v74, s0, v4
	v_lshlrev_b32_e32 v5, 1, v13
	v_add_u32_e32 v12, 0x500, v6
	v_and_or_b32 v4, v5, 14, v4
	v_ashrrev_i32_e32 v13, 4, v12
	ds_write_b16 v4, v122
	ds_write_b16_d16_hi v4, v122 offset:272
	ds_write_b16 v4, v123 offset:544
	ds_write_b16_d16_hi v4, v123 offset:816
	ds_write_b16 v4, v124 offset:1088
	ds_write_b16_d16_hi v4, v124 offset:1360
	ds_write_b16 v4, v125 offset:1632
	ds_write_b16_d16_hi v4, v125 offset:1904
	v_add_u32_e32 v4, s4, v13
	v_ashrrev_i32_e32 v5, 31, v4
	v_lshlrev_b64 v[4:5], 9, v[4:5]
	v_lshl_add_u64 v[4:5], v[2:3], 0, v[4:5]
	v_ashrrev_i32_e32 v4, 7, v12
	v_bitop3_b32 v4, v4, v6, 15 bitop3:0x78
	v_lshlrev_b32_e32 v4, 4, v4
	v_mad_u32_u24 v4, v74, s0, v4
	v_lshlrev_b32_e32 v5, 1, v13
	v_add_u32_e32 v12, 0x600, v6
	v_and_or_b32 v4, v5, 14, v4
	v_ashrrev_i32_e32 v13, 4, v12
	ds_write_b16 v4, v126
	ds_write_b16_d16_hi v4, v126 offset:272
	ds_write_b16 v4, v127 offset:544
	ds_write_b16_d16_hi v4, v127 offset:816
	ds_write_b16 v4, v128 offset:1088
	ds_write_b16_d16_hi v4, v128 offset:1360
	ds_write_b16 v4, v129 offset:1632
	ds_write_b16_d16_hi v4, v129 offset:1904
	v_add_u32_e32 v4, s4, v13
	v_ashrrev_i32_e32 v5, 31, v4
	v_lshlrev_b64 v[4:5], 9, v[4:5]
	v_lshl_add_u64 v[4:5], v[2:3], 0, v[4:5]
	v_ashrrev_i32_e32 v4, 7, v12
	v_bitop3_b32 v4, v4, v6, 15 bitop3:0x78
	v_lshlrev_b32_e32 v4, 4, v4
	v_mad_u32_u24 v4, v74, s0, v4
	v_lshlrev_b32_e32 v5, 1, v13
	v_and_or_b32 v4, v5, 14, v4
	ds_write_b16 v4, v138
	ds_write_b16_d16_hi v4, v138 offset:272
	ds_write_b16 v4, v139 offset:544
	ds_write_b16_d16_hi v4, v139 offset:816
	ds_write_b16 v4, v140 offset:1088
	ds_write_b16_d16_hi v4, v140 offset:1360
	ds_write_b16 v4, v141 offset:1632
	ds_write_b16_d16_hi v4, v141 offset:1904
	v_add_u32_e32 v8, 0x700, v6
	v_ashrrev_i32_e32 v9, 4, v8
	v_add_u32_e32 v4, s4, v9
	v_ashrrev_i32_e32 v5, 31, v4
	v_lshlrev_b64 v[4:5], 9, v[4:5]
	v_lshl_add_u64 v[2:3], v[2:3], 0, v[4:5]
	v_ashrrev_i32_e32 v8, 7, v8
	v_bitop3_b32 v8, v8, v6, 15 bitop3:0x78
	v_lshlrev_b32_e32 v8, 4, v8
	v_mad_u32_u24 v8, v74, s0, v8
	v_lshlrev_b32_e32 v9, 1, v9
	v_and_or_b32 v8, v9, 14, v8
	v_readlane_b32 s0, v253, 37
	v_readlane_b32 s1, v253, 38
	v_readlane_b32 s4, v254, 1
	v_readlane_b32 s5, v254, 2
	ds_write_b16 v8, v142
	ds_write_b16_d16_hi v8, v142 offset:272
	ds_write_b16 v8, v143 offset:544
	ds_write_b16_d16_hi v8, v143 offset:816
	ds_write_b16 v8, v144 offset:1088
	ds_write_b16_d16_hi v8, v144 offset:1360
	ds_write_b16 v8, v145 offset:1632
	ds_write_b16_d16_hi v8, v145 offset:1904
	v_ashrrev_i32_e32 v2, 2, v6
	v_and_b32_e32 v70, -16, v2
	v_ashrrev_i32_e32 v71, 31, v70
	v_lshl_add_u64 v[2:3], v[70:71], 0, s[88:89]
	v_or_b32_e32 v2, v2, v74
	v_lshlrev_b64 v[2:3], 8, v[2:3]
	v_lshl_add_u64 v[2:3], s[0:1], 0, v[2:3]
	v_lshl_add_u64 v[72:73], v[2:3], 0, v[130:131]
	s_waitcnt lgkmcnt(0)
	s_barrier
	v_bfe_u32 v71, v6, 3, 1
	v_bitop3_b32 v6, v71, v7, 3 bitop3:0x78
	v_lshlrev_b32_e32 v6, 4, v6
	s_movk_i32 s0, 0x110
	v_mad_u32_u24 v6, v74, s0, v6
	v_lshlrev_b32_e32 v130, 1, v74
	v_lshlrev_b32_e32 v16, 16, v98
	v_and_b32_e32 v17, 0xffff0000, v98
	v_lshlrev_b32_e32 v18, 16, v99
	v_and_b32_e32 v19, 0xffff0000, v99
	v_lshlrev_b32_e32 v20, 16, v100
	v_and_b32_e32 v21, 0xffff0000, v100
	v_lshlrev_b32_e32 v22, 16, v101
	v_and_b32_e32 v23, 0xffff0000, v101
	ds_read_b128 v[2:5], v82 offset:37888
	ds_read_b128 v[8:11], v82 offset:37904
	ds_read_b128 v[12:15], v82 offset:38400
	ds_read_b128 v[84:87], v82 offset:38528
	s_waitcnt lgkmcnt(3)
	v_pk_mul_f32 v[2:3], v[2:3], v[16:17]
	v_pk_mul_f32 v[4:5], v[4:5], v[18:19]
	s_waitcnt lgkmcnt(1)
	v_pk_mul_f32 v[12:13], v[12:13], v[16:17]
	v_cvt_pk_bf16_f32 v2, v2, v3
	v_cvt_pk_bf16_f32 v66, v12, v13
	v_cvt_pk_bf16_f32 v3, v4, v5
	v_pk_mul_f32 v[4:5], v[14:15], v[18:19]
	ds_read_b128 v[12:15], v82 offset:38416
	v_cvt_pk_bf16_f32 v67, v4, v5
	v_pk_mul_f32 v[4:5], v[8:9], v[20:21]
	s_waitcnt lgkmcnt(0)
	v_pk_mul_f32 v[8:9], v[12:13], v[20:21]
	s_nop 0
	v_cvt_pk_bf16_f32 v68, v8, v9
	v_pk_mul_f32 v[8:9], v[10:11], v[22:23]
	v_cvt_pk_bf16_f32 v4, v4, v5
	v_cvt_pk_bf16_f32 v5, v8, v9
	v_pk_mul_f32 v[8:9], v[14:15], v[22:23]
	s_nop 0
	v_cvt_pk_bf16_f32 v69, v8, v9
	ds_read_b128 v[6:9], v6
	s_waitcnt lgkmcnt(0)
	v_mfma_f32_16x16x32_bf16 v[58:61], v[2:5], v[6:9], 0
	v_mfma_f32_16x16x32_bf16 v[62:65], v[66:69], v[6:9], 0
	v_mov_b32_e32 v6, 0x1100
	v_mad_u32_u24 v81, v74, s0, v6
	v_bitop3_b32 v6, v71, v1, 2 bitop3:0x36
	v_lshl_add_u32 v6, v6, 4, v81
	ds_read_b128 v[6:9], v6
	s_waitcnt lgkmcnt(0)
	v_mfma_f32_16x16x32_bf16 v[50:53], v[2:5], v[6:9], 0
	v_mfma_f32_16x16x32_bf16 v[54:57], v[66:69], v[6:9], 0
	v_mov_b32_e32 v6, 0x2200
	v_mad_u32_u24 v80, v74, s0, v6
	v_bitop3_b32 v6, v71, v1, 4 bitop3:0x36
	v_lshl_add_u32 v6, v6, 4, v80
	ds_read_b128 v[6:9], v6
	s_waitcnt lgkmcnt(0)
	v_mfma_f32_16x16x32_bf16 v[42:45], v[2:5], v[6:9], 0
	v_mfma_f32_16x16x32_bf16 v[46:49], v[66:69], v[6:9], 0
	v_mov_b32_e32 v6, 0x3300
	v_mad_u32_u24 v79, v74, s0, v6
	v_bitop3_b32 v6, v71, v1, 6 bitop3:0x36
	v_lshl_add_u32 v6, v6, 4, v79
	ds_read_b128 v[6:9], v6
	s_waitcnt lgkmcnt(0)
	v_mfma_f32_16x16x32_bf16 v[34:37], v[2:5], v[6:9], 0
	v_mfma_f32_16x16x32_bf16 v[38:41], v[66:69], v[6:9], 0
	v_mov_b32_e32 v6, 0x4400
	v_mad_u32_u24 v78, v74, s0, v6
	v_bitop3_b32 v6, v71, v1, 8 bitop3:0x36
	v_lshl_add_u32 v6, v6, 4, v78
	ds_read_b128 v[6:9], v6
	s_waitcnt lgkmcnt(0)
	v_mfma_f32_16x16x32_bf16 v[26:29], v[2:5], v[6:9], 0
	v_mfma_f32_16x16x32_bf16 v[30:33], v[66:69], v[6:9], 0
	v_mov_b32_e32 v6, 0x5500
	v_mad_u32_u24 v77, v74, s0, v6
	v_bitop3_b32 v6, v71, v1, 10 bitop3:0x36
	v_lshl_add_u32 v6, v6, 4, v77
	ds_read_b128 v[6:9], v6
	s_waitcnt lgkmcnt(0)
	v_mfma_f32_16x16x32_bf16 v[18:21], v[2:5], v[6:9], 0
	v_mfma_f32_16x16x32_bf16 v[22:25], v[66:69], v[6:9], 0
	v_mov_b32_e32 v6, 0x6600
	v_mad_u32_u24 v76, v74, s0, v6
	v_bitop3_b32 v6, v71, v1, 12 bitop3:0x36
	v_lshl_add_u32 v6, v6, 4, v76
	ds_read_b128 v[6:9], v6
	s_waitcnt lgkmcnt(0)
	v_mfma_f32_16x16x32_bf16 v[10:13], v[2:5], v[6:9], 0
	v_mfma_f32_16x16x32_bf16 v[14:17], v[66:69], v[6:9], 0
	v_mov_b32_e32 v6, 0x7700
	v_mad_u32_u24 v75, v74, s0, v6
	v_bitop3_b32 v6, v71, v1, 14 bitop3:0x36
	v_lshl_add_u32 v6, v6, 4, v75
	ds_read_b128 v[6:9], v6
	s_waitcnt lgkmcnt(0)
	v_mfma_f32_16x16x32_bf16 v[2:5], v[2:5], v[6:9], 0
	v_mfma_f32_16x16x32_bf16 v[6:9], v[66:69], v[6:9], 0
	v_lshlrev_b32_e32 v88, 16, v146
	v_and_b32_e32 v89, 0xffff0000, v146
	v_lshlrev_b32_e32 v90, 16, v147
	v_and_b32_e32 v91, 0xffff0000, v147
	v_lshlrev_b32_e32 v94, 16, v148
	v_and_b32_e32 v95, 0xffff0000, v148
	v_lshlrev_b32_e32 v96, 16, v149
	v_and_b32_e32 v97, 0xffff0000, v149
	ds_read_b128 v[66:69], v82 offset:38016
	v_pk_mul_f32 v[84:85], v[84:85], v[88:89]
	s_waitcnt lgkmcnt(0)
	v_pk_mul_f32 v[66:67], v[66:67], v[88:89]
	v_pk_mul_f32 v[68:69], v[68:69], v[90:91]
	v_cvt_pk_bf16_f32 v66, v66, v67
	v_cvt_pk_bf16_f32 v67, v68, v69
	v_pk_mul_f32 v[68:69], v[86:87], v[90:91]
	ds_read_b128 v[86:89], v82 offset:38032
	ds_read_b128 v[90:93], v82 offset:38544
	v_cvt_pk_bf16_f32 v84, v84, v85
	v_cvt_pk_bf16_f32 v85, v68, v69
	s_waitcnt lgkmcnt(1)
	v_pk_mul_f32 v[68:69], v[86:87], v[94:95]
	v_pk_mul_f32 v[88:89], v[88:89], v[96:97]
	v_cvt_pk_bf16_f32 v68, v68, v69
	s_waitcnt lgkmcnt(0)
	v_pk_mul_f32 v[86:87], v[90:91], v[94:95]
	v_cvt_pk_bf16_f32 v69, v88, v89
	v_pk_mul_f32 v[88:89], v[92:93], v[96:97]
	v_cvt_pk_bf16_f32 v86, v86, v87
	v_cvt_pk_bf16_f32 v87, v88, v89
	v_bitop3_b32 v88, v1, v71, 4 bitop3:0x36
	v_lshlrev_b32_e32 v88, 4, v88
	v_mad_u32_u24 v88, v74, s0, v88
	ds_read_b128 v[88:91], v88
	s_waitcnt lgkmcnt(0)
	v_mfma_f32_16x16x32_bf16 v[58:61], v[66:69], v[88:91], v[58:61]
	v_mfma_f32_16x16x32_bf16 v[62:65], v[84:87], v[88:91], v[62:65]
	v_bitop3_b32 v88, v71, v83, 2 bitop3:0x36
	v_lshl_add_u32 v88, v88, 4, v81
	ds_read_b128 v[88:91], v88
	s_waitcnt lgkmcnt(0)
	v_mfma_f32_16x16x32_bf16 v[50:53], v[66:69], v[88:91], v[50:53]
	v_mfma_f32_16x16x32_bf16 v[54:57], v[84:87], v[88:91], v[54:57]
	v_bitop3_b32 v88, v71, v1, 4 bitop3:0x14
	v_lshl_add_u32 v88, v88, 4, v80
	ds_read_b128 v[88:91], v88
	s_waitcnt lgkmcnt(0)
	v_mfma_f32_16x16x32_bf16 v[42:45], v[66:69], v[88:91], v[42:45]
	v_mfma_f32_16x16x32_bf16 v[46:49], v[84:87], v[88:91], v[46:49]
	v_bitop3_b32 v88, v71, v83, 6 bitop3:0x36
	v_lshl_add_u32 v88, v88, 4, v79
	ds_read_b128 v[88:91], v88
	s_waitcnt lgkmcnt(0)
	v_mfma_f32_16x16x32_bf16 v[34:37], v[66:69], v[88:91], v[34:37]
	v_mfma_f32_16x16x32_bf16 v[38:41], v[84:87], v[88:91], v[38:41]
	v_bitop3_b32 v88, v71, v83, 8 bitop3:0x36
	v_lshl_add_u32 v88, v88, 4, v78
	ds_read_b128 v[88:91], v88
	s_waitcnt lgkmcnt(0)
	v_mfma_f32_16x16x32_bf16 v[26:29], v[66:69], v[88:91], v[26:29]
	v_mfma_f32_16x16x32_bf16 v[30:33], v[84:87], v[88:91], v[30:33]
	v_bitop3_b32 v88, v71, v83, 10 bitop3:0x36
	v_lshl_add_u32 v88, v88, 4, v77
	ds_read_b128 v[88:91], v88
	s_waitcnt lgkmcnt(0)
	v_mfma_f32_16x16x32_bf16 v[18:21], v[66:69], v[88:91], v[18:21]
	v_mfma_f32_16x16x32_bf16 v[22:25], v[84:87], v[88:91], v[22:25]
	v_bitop3_b32 v88, v71, v83, 12 bitop3:0x36
	v_lshl_add_u32 v88, v88, 4, v76
	ds_read_b128 v[88:91], v88
	v_bitop3_b32 v83, v71, v83, 14 bitop3:0x36
	v_lshl_add_u32 v83, v83, 4, v75
	s_waitcnt lgkmcnt(0)
	v_mfma_f32_16x16x32_bf16 v[10:13], v[66:69], v[88:91], v[10:13]
	v_mfma_f32_16x16x32_bf16 v[14:17], v[84:87], v[88:91], v[14:17]
	ds_read_b128 v[88:91], v83
	v_or_b32_e32 v83, 8, v1
	s_waitcnt lgkmcnt(0)
	v_mfma_f32_16x16x32_bf16 v[2:5], v[66:69], v[88:91], v[2:5]
	v_mfma_f32_16x16x32_bf16 v[66:69], v[84:87], v[88:91], v[6:9]
	ds_read_b128 v[84:87], v82 offset:38656
	s_nop 1
	v_lshlrev_b32_e32 v88, 16, v150
	v_and_b32_e32 v89, 0xffff0000, v150
	v_lshlrev_b32_e32 v90, 16, v151
	v_and_b32_e32 v91, 0xffff0000, v151
	v_lshlrev_b32_e32 v94, 16, v152
	v_and_b32_e32 v95, 0xffff0000, v152
	v_lshlrev_b32_e32 v96, 16, v153
	v_and_b32_e32 v97, 0xffff0000, v153
	ds_read_b128 v[6:9], v82 offset:38144
	s_waitcnt lgkmcnt(1)
	v_pk_mul_f32 v[84:85], v[84:85], v[88:89]
	s_waitcnt lgkmcnt(0)
	v_pk_mul_f32 v[6:7], v[6:7], v[88:89]
	v_pk_mul_f32 v[8:9], v[8:9], v[90:91]
	v_cvt_pk_bf16_f32 v6, v6, v7
	v_cvt_pk_bf16_f32 v7, v8, v9
	v_pk_mul_f32 v[8:9], v[86:87], v[90:91]
	ds_read_b128 v[86:89], v82 offset:38160
	ds_read_b128 v[90:93], v82 offset:38672
	v_cvt_pk_bf16_f32 v84, v84, v85
	v_cvt_pk_bf16_f32 v85, v8, v9
	s_waitcnt lgkmcnt(1)
	v_pk_mul_f32 v[8:9], v[86:87], v[94:95]
	v_pk_mul_f32 v[88:89], v[88:89], v[96:97]
	v_cvt_pk_bf16_f32 v8, v8, v9
	s_waitcnt lgkmcnt(0)
	v_pk_mul_f32 v[86:87], v[90:91], v[94:95]
	v_cvt_pk_bf16_f32 v9, v88, v89
	v_pk_mul_f32 v[88:89], v[92:93], v[96:97]
	v_cvt_pk_bf16_f32 v86, v86, v87
	v_cvt_pk_bf16_f32 v87, v88, v89
	v_bitop3_b32 v88, v1, v71, 8 bitop3:0x36
	v_lshlrev_b32_e32 v88, 4, v88
	v_mad_u32_u24 v88, v74, s0, v88
	ds_read_b128 v[88:91], v88
	s_waitcnt lgkmcnt(0)
	v_mfma_f32_16x16x32_bf16 v[58:61], v[6:9], v[88:91], v[58:61]
	v_mfma_f32_16x16x32_bf16 v[62:65], v[84:87], v[88:91], v[62:65]
	v_bitop3_b32 v88, v71, v83, 2 bitop3:0x36
	v_lshl_add_u32 v88, v88, 4, v81
	ds_read_b128 v[88:91], v88
	s_waitcnt lgkmcnt(0)
	v_mfma_f32_16x16x32_bf16 v[50:53], v[6:9], v[88:91], v[50:53]
	v_mfma_f32_16x16x32_bf16 v[54:57], v[84:87], v[88:91], v[54:57]
	v_bitop3_b32 v88, v71, v83, 4 bitop3:0x36
	v_lshl_add_u32 v88, v88, 4, v80
	ds_read_b128 v[88:91], v88
	s_waitcnt lgkmcnt(0)
	v_mfma_f32_16x16x32_bf16 v[42:45], v[6:9], v[88:91], v[42:45]
	v_mfma_f32_16x16x32_bf16 v[46:49], v[84:87], v[88:91], v[46:49]
	v_bitop3_b32 v88, v71, v83, 6 bitop3:0x36
	v_lshl_add_u32 v88, v88, 4, v79
	ds_read_b128 v[88:91], v88
	s_waitcnt lgkmcnt(0)
	v_mfma_f32_16x16x32_bf16 v[34:37], v[6:9], v[88:91], v[34:37]
	v_mfma_f32_16x16x32_bf16 v[38:41], v[84:87], v[88:91], v[38:41]
	v_bitop3_b32 v88, v71, v1, 8 bitop3:0x14
	v_lshl_add_u32 v88, v88, 4, v78
	ds_read_b128 v[88:91], v88
	s_waitcnt lgkmcnt(0)
	v_mfma_f32_16x16x32_bf16 v[26:29], v[6:9], v[88:91], v[26:29]
	v_mfma_f32_16x16x32_bf16 v[30:33], v[84:87], v[88:91], v[30:33]
	v_bitop3_b32 v88, v71, v83, 10 bitop3:0x36
	v_lshl_add_u32 v88, v88, 4, v77
	ds_read_b128 v[88:91], v88
	s_waitcnt lgkmcnt(0)
	v_mfma_f32_16x16x32_bf16 v[18:21], v[6:9], v[88:91], v[18:21]
	v_mfma_f32_16x16x32_bf16 v[22:25], v[84:87], v[88:91], v[22:25]
	v_bitop3_b32 v88, v71, v83, 12 bitop3:0x36
	v_lshl_add_u32 v88, v88, 4, v76
	ds_read_b128 v[88:91], v88
	v_bitop3_b32 v83, v71, v83, 14 bitop3:0x36
	v_lshl_add_u32 v83, v83, 4, v75
	s_waitcnt lgkmcnt(0)
	v_mfma_f32_16x16x32_bf16 v[10:13], v[6:9], v[88:91], v[10:13]
	v_mfma_f32_16x16x32_bf16 v[14:17], v[84:87], v[88:91], v[14:17]
	ds_read_b128 v[88:91], v83
	s_waitcnt lgkmcnt(0)
	v_mfma_f32_16x16x32_bf16 v[6:9], v[6:9], v[88:91], v[2:5]
	v_mfma_f32_16x16x32_bf16 v[2:5], v[84:87], v[88:91], v[66:69]
	ds_read_b128 v[84:87], v82 offset:38784
	ds_read_b128 v[90:93], v82 offset:38800
	s_nop 0
	v_lshlrev_b32_e32 v72, 16, v154
	v_and_b32_e32 v73, 0xffff0000, v154
	v_lshlrev_b32_e32 v88, 16, v155
	v_and_b32_e32 v89, 0xffff0000, v155
	v_lshlrev_b32_e32 v94, 16, v156
	v_and_b32_e32 v95, 0xffff0000, v156
	v_lshlrev_b32_e32 v96, 16, v157
	v_and_b32_e32 v97, 0xffff0000, v157
	ds_read_b128 v[66:69], v82 offset:38272
	s_waitcnt lgkmcnt(0)
	v_pk_mul_f32 v[66:67], v[66:67], v[72:73]
	v_pk_mul_f32 v[68:69], v[68:69], v[88:89]
	v_cvt_pk_bf16_f32 v66, v66, v67
	v_cvt_pk_bf16_f32 v67, v68, v69
	v_pk_mul_f32 v[68:69], v[86:87], v[88:89]
	ds_read_b128 v[86:89], v82 offset:38288
	v_pk_mul_f32 v[72:73], v[84:85], v[72:73]
	v_cvt_pk_bf16_f32 v85, v68, v69
	v_cvt_pk_bf16_f32 v84, v72, v73
	v_pk_mul_f32 v[72:73], v[90:91], v[94:95]
	s_waitcnt lgkmcnt(0)
	v_pk_mul_f32 v[68:69], v[86:87], v[94:95]
	v_cvt_pk_bf16_f32 v86, v72, v73
	v_pk_mul_f32 v[72:73], v[88:89], v[96:97]
	v_cvt_pk_bf16_f32 v68, v68, v69
	v_cvt_pk_bf16_f32 v69, v72, v73
	v_pk_mul_f32 v[72:73], v[92:93], v[96:97]
	s_nop 0
	v_cvt_pk_bf16_f32 v87, v72, v73
	v_bitop3_b32 v73, v1, v71, 12 bitop3:0x36
	v_lshlrev_b32_e32 v73, 4, v73
	v_mad_u32_u24 v73, v74, s0, v73
	ds_read_b128 v[88:91], v73
	v_or_b32_e32 v72, 12, v1
	v_bitop3_b32 v73, v71, v72, 2 bitop3:0x36
	v_lshl_add_u32 v73, v73, 4, v81
	s_waitcnt lgkmcnt(0)
	v_mfma_f32_16x16x32_bf16 v[58:61], v[66:69], v[88:91], v[58:61]
	s_lshl_b32 s0, s3, 15
	s_add_u32 s0, s4, s0
	s_addc_u32 s1, s5, 0
	v_mfma_f32_16x16x32_bf16 v[62:65], v[84:87], v[88:91], v[62:65]
	ds_read_b128 v[88:91], v73
	v_bitop3_b32 v73, v71, v72, 4 bitop3:0x36
	v_lshl_add_u32 v73, v73, 4, v80
	ds_read_b128 v[80:83], v73
	v_bitop3_b32 v73, v71, v72, 6 bitop3:0x36
	v_lshl_add_u32 v73, v73, 4, v79
	s_waitcnt lgkmcnt(0)
	v_mfma_f32_16x16x32_bf16 v[42:45], v[66:69], v[80:83], v[42:45]
	s_mov_b64 s[4:5], 0x4000
	v_mfma_f32_16x16x32_bf16 v[46:49], v[84:87], v[80:83], v[46:49]
	ds_read_b128 v[80:83], v73
	v_bitop3_b32 v73, v71, v72, 8 bitop3:0x36
	v_lshl_add_u32 v73, v73, 4, v78
	s_waitcnt lgkmcnt(0)
	v_mfma_f32_16x16x32_bf16 v[34:37], v[66:69], v[80:83], v[34:37]
	v_mfma_f32_16x16x32_bf16 v[38:41], v[84:87], v[80:83], v[38:41]
	ds_read_b128 v[78:81], v73
	v_bitop3_b32 v73, v71, v72, 10 bitop3:0x36
	v_lshl_add_u32 v73, v73, 4, v77
	s_waitcnt lgkmcnt(0)
	v_mfma_f32_16x16x32_bf16 v[26:29], v[66:69], v[78:81], v[26:29]
	v_mfma_f32_16x16x32_bf16 v[30:33], v[84:87], v[78:81], v[30:33]
	ds_read_b128 v[78:81], v73
	v_bitop3_b32 v73, v71, v1, 12 bitop3:0x14
	v_bitop3_b32 v71, v71, v72, 14 bitop3:0x36
	v_lshl_add_u32 v73, v73, 4, v76
	v_lshl_add_u32 v71, v71, 4, v75
	s_waitcnt lgkmcnt(0)
	v_mfma_f32_16x16x32_bf16 v[18:21], v[66:69], v[78:81], v[18:21]
	v_mfma_f32_16x16x32_bf16 v[22:25], v[84:87], v[78:81], v[22:25]
	ds_read_b128 v[76:79], v73
	ds_read_b128 v[72:75], v71
	v_mfma_f32_16x16x32_bf16 v[50:53], v[66:69], v[88:91], v[50:53]
	s_waitcnt lgkmcnt(1)
	v_mfma_f32_16x16x32_bf16 v[10:13], v[66:69], v[76:79], v[10:13]
	s_waitcnt lgkmcnt(0)
	v_mfma_f32_16x16x32_bf16 v[6:9], v[66:69], v[72:75], v[6:9]
	v_lshl_or_b32 v66, v1, 2, v70
	v_ashrrev_i32_e32 v67, 31, v66
	v_lshlrev_b64 v[68:69], 8, v[66:67]
	v_lshl_add_u64 v[68:69], s[0:1], 0, v[68:69]
	v_cvt_pk_bf16_f32 v1, v58, s0
	v_lshl_add_u64 v[70:71], v[68:69], 0, v[130:131]
	v_lshl_add_u64 v[68:69], v[68:69], 0, s[4:5]
	v_mfma_f32_16x16x32_bf16 v[2:5], v[84:87], v[72:75], v[2:5]
	global_store_short v[70:71], v1, off
	v_cvt_pk_bf16_f32 v1, v62, s0
	v_lshl_add_u64 v[72:73], v[68:69], 0, v[130:131]
	v_or_b32_e32 v58, 1, v66
	global_store_short v[72:73], v1, off
	v_cvt_pk_bf16_f32 v1, v59, s0
	v_ashrrev_i32_e32 v59, 31, v58
	v_lshlrev_b64 v[58:59], 8, v[58:59]
	v_lshl_add_u64 v[58:59], s[0:1], 0, v[58:59]
	v_lshl_add_u64 v[72:73], v[58:59], 0, v[130:131]
	v_lshl_add_u64 v[58:59], v[58:59], 0, s[4:5]
	global_store_short v[72:73], v1, off
	v_cvt_pk_bf16_f32 v1, v63, s0
	v_lshl_add_u64 v[62:63], v[58:59], 0, v[130:131]
	global_store_short v[62:63], v1, off
	v_or_b32_e32 v62, 2, v66
	v_ashrrev_i32_e32 v63, 31, v62
	v_lshlrev_b64 v[62:63], 8, v[62:63]
	v_lshl_add_u64 v[62:63], s[0:1], 0, v[62:63]
	v_cvt_pk_bf16_f32 v1, v60, s0
	v_lshl_add_u64 v[74:75], v[62:63], 0, v[130:131]
	v_lshl_add_u64 v[62:63], v[62:63], 0, s[4:5]
	v_mfma_f32_16x16x32_bf16 v[14:17], v[84:87], v[76:79], v[14:17]
	global_store_short v[74:75], v1, off
	v_cvt_pk_bf16_f32 v1, v64, s0
	v_lshl_add_u64 v[76:77], v[62:63], 0, v[130:131]
	v_or_b32_e32 v60, 3, v66
	global_store_short v[76:77], v1, off
	v_cvt_pk_bf16_f32 v1, v61, s0
	v_ashrrev_i32_e32 v61, 31, v60
	v_lshlrev_b64 v[60:61], 8, v[60:61]
	v_mfma_f32_16x16x32_bf16 v[54:57], v[84:87], v[88:91], v[54:57]
	v_lshl_add_u64 v[60:61], s[0:1], 0, v[60:61]
	v_lshl_add_u64 v[66:67], v[60:61], 0, v[130:131]
	v_lshl_add_u64 v[60:61], v[60:61], 0, s[4:5]
	global_store_short v[66:67], v1, off
	v_cvt_pk_bf16_f32 v1, v65, s0
	v_lshl_add_u64 v[64:65], v[60:61], 0, v[130:131]
	global_store_short v[64:65], v1, off
	v_cvt_pk_bf16_f32 v1, v50, s0
	v_or_b32_e32 v64, 32, v130
	v_mov_b32_e32 v65, v131
	global_store_short v[70:71], v1, off offset:32
	v_cvt_pk_bf16_f32 v1, v54, s0
	v_lshl_add_u64 v[76:77], v[68:69], 0, v[64:65]
	global_store_short v[76:77], v1, off
	v_cvt_pk_bf16_f32 v1, v51, s0
	global_store_short v[72:73], v1, off offset:32
	v_cvt_pk_bf16_f32 v1, v55, s0
	v_lshl_add_u64 v[50:51], v[58:59], 0, v[64:65]
	global_store_short v[50:51], v1, off
	v_cvt_pk_bf16_f32 v1, v52, s0
	global_store_short v[74:75], v1, off offset:32
	v_cvt_pk_bf16_f32 v1, v56, s0
	v_lshl_add_u64 v[50:51], v[62:63], 0, v[64:65]
	global_store_short v[50:51], v1, off
	v_cvt_pk_bf16_f32 v1, v53, s0
	global_store_short v[66:67], v1, off offset:32
	v_cvt_pk_bf16_f32 v1, v57, s0
	v_lshl_add_u64 v[50:51], v[60:61], 0, v[64:65]
	global_store_short v[50:51], v1, off
	v_cvt_pk_bf16_f32 v1, v42, s0
	v_or_b32_e32 v50, 64, v130
	v_mov_b32_e32 v51, v131
	global_store_short v[70:71], v1, off offset:64
	v_cvt_pk_bf16_f32 v1, v46, s0
	v_lshl_add_u64 v[52:53], v[68:69], 0, v[50:51]
	global_store_short v[52:53], v1, off
	v_cvt_pk_bf16_f32 v1, v43, s0
	global_store_short v[72:73], v1, off offset:64
	v_cvt_pk_bf16_f32 v1, v47, s0
	v_lshl_add_u64 v[42:43], v[58:59], 0, v[50:51]
	global_store_short v[42:43], v1, off
	v_cvt_pk_bf16_f32 v1, v44, s0
	global_store_short v[74:75], v1, off offset:64
	v_cvt_pk_bf16_f32 v1, v48, s0
	v_lshl_add_u64 v[42:43], v[62:63], 0, v[50:51]
	global_store_short v[42:43], v1, off
	v_cvt_pk_bf16_f32 v1, v45, s0
	global_store_short v[66:67], v1, off offset:64
	v_cvt_pk_bf16_f32 v1, v49, s0
	v_lshl_add_u64 v[42:43], v[60:61], 0, v[50:51]
	global_store_short v[42:43], v1, off
	v_cvt_pk_bf16_f32 v1, v34, s0
	v_or_b32_e32 v42, 0x60, v130
	v_mov_b32_e32 v43, v131
	global_store_short v[70:71], v1, off offset:96
	v_cvt_pk_bf16_f32 v1, v38, s0
	v_lshl_add_u64 v[44:45], v[68:69], 0, v[42:43]
	global_store_short v[44:45], v1, off
	v_cvt_pk_bf16_f32 v1, v35, s0
	global_store_short v[72:73], v1, off offset:96
	v_cvt_pk_bf16_f32 v1, v39, s0
	v_lshl_add_u64 v[34:35], v[58:59], 0, v[42:43]
	global_store_short v[34:35], v1, off
	v_cvt_pk_bf16_f32 v1, v36, s0
	global_store_short v[74:75], v1, off offset:96
	v_cvt_pk_bf16_f32 v1, v40, s0
	v_lshl_add_u64 v[34:35], v[62:63], 0, v[42:43]
	global_store_short v[34:35], v1, off
	v_cvt_pk_bf16_f32 v1, v37, s0
	global_store_short v[66:67], v1, off offset:96
	v_cvt_pk_bf16_f32 v1, v41, s0
	v_lshl_add_u64 v[34:35], v[60:61], 0, v[42:43]
	global_store_short v[34:35], v1, off
	v_cvt_pk_bf16_f32 v1, v26, s0
	v_or_b32_e32 v34, 0x80, v130
	v_mov_b32_e32 v35, v131
	global_store_short v[70:71], v1, off offset:128
	v_cvt_pk_bf16_f32 v1, v30, s0
	v_lshl_add_u64 v[36:37], v[68:69], 0, v[34:35]
	global_store_short v[36:37], v1, off
	v_cvt_pk_bf16_f32 v1, v27, s0
	global_store_short v[72:73], v1, off offset:128
	v_cvt_pk_bf16_f32 v1, v31, s0
	v_lshl_add_u64 v[26:27], v[58:59], 0, v[34:35]
	global_store_short v[26:27], v1, off
	v_cvt_pk_bf16_f32 v1, v28, s0
	global_store_short v[74:75], v1, off offset:128
	v_cvt_pk_bf16_f32 v1, v32, s0
	v_lshl_add_u64 v[26:27], v[62:63], 0, v[34:35]
	global_store_short v[26:27], v1, off
	v_cvt_pk_bf16_f32 v1, v29, s0
	global_store_short v[66:67], v1, off offset:128
	v_cvt_pk_bf16_f32 v1, v33, s0
	v_lshl_add_u64 v[26:27], v[60:61], 0, v[34:35]
	global_store_short v[26:27], v1, off
	v_cvt_pk_bf16_f32 v1, v18, s0
	v_or_b32_e32 v26, 0xa0, v130
	v_mov_b32_e32 v27, v131
	global_store_short v[70:71], v1, off offset:160
	v_cvt_pk_bf16_f32 v1, v22, s0
	v_lshl_add_u64 v[28:29], v[68:69], 0, v[26:27]
	global_store_short v[28:29], v1, off
	v_cvt_pk_bf16_f32 v1, v19, s0
	global_store_short v[72:73], v1, off offset:160
	v_cvt_pk_bf16_f32 v1, v23, s0
	v_lshl_add_u64 v[18:19], v[58:59], 0, v[26:27]
	global_store_short v[18:19], v1, off
	v_cvt_pk_bf16_f32 v1, v20, s0
	global_store_short v[74:75], v1, off offset:160
	v_cvt_pk_bf16_f32 v1, v24, s0
	v_lshl_add_u64 v[18:19], v[62:63], 0, v[26:27]
	global_store_short v[18:19], v1, off
	v_cvt_pk_bf16_f32 v1, v21, s0
	global_store_short v[66:67], v1, off offset:160
	v_cvt_pk_bf16_f32 v1, v25, s0
	v_lshl_add_u64 v[18:19], v[60:61], 0, v[26:27]
	global_store_short v[18:19], v1, off
	v_cvt_pk_bf16_f32 v1, v10, s0
	v_or_b32_e32 v18, 0xc0, v130
	v_mov_b32_e32 v19, v131
	global_store_short v[70:71], v1, off offset:192
	v_cvt_pk_bf16_f32 v1, v14, s0
	v_lshl_add_u64 v[20:21], v[68:69], 0, v[18:19]
	global_store_short v[20:21], v1, off
	v_cvt_pk_bf16_f32 v1, v11, s0
	global_store_short v[72:73], v1, off offset:192
	v_cvt_pk_bf16_f32 v1, v15, s0
	v_lshl_add_u64 v[10:11], v[58:59], 0, v[18:19]
	global_store_short v[10:11], v1, off
	v_cvt_pk_bf16_f32 v1, v12, s0
	global_store_short v[74:75], v1, off offset:192
	v_cvt_pk_bf16_f32 v1, v16, s0
	v_lshl_add_u64 v[10:11], v[62:63], 0, v[18:19]
	global_store_short v[10:11], v1, off
	v_cvt_pk_bf16_f32 v1, v13, s0
	global_store_short v[66:67], v1, off offset:192
	v_cvt_pk_bf16_f32 v1, v17, s0
	v_lshl_add_u64 v[10:11], v[60:61], 0, v[18:19]
	global_store_short v[10:11], v1, off
	v_cvt_pk_bf16_f32 v1, v6, s0
	v_or_b32_e32 v130, 0xe0, v130
	global_store_short v[70:71], v1, off offset:224
	v_cvt_pk_bf16_f32 v1, v2, s0
	v_lshl_add_u64 v[10:11], v[68:69], 0, v[130:131]
	global_store_short v[10:11], v1, off
	v_cvt_pk_bf16_f32 v1, v7, s0
	global_store_short v[72:73], v1, off offset:224
	v_cvt_pk_bf16_f32 v1, v3, s0
	v_lshl_add_u64 v[2:3], v[58:59], 0, v[130:131]
	global_store_short v[2:3], v1, off
	v_cvt_pk_bf16_f32 v1, v8, s0
	global_store_short v[74:75], v1, off offset:224
	v_cvt_pk_bf16_f32 v1, v4, s0
	v_lshl_add_u64 v[2:3], v[62:63], 0, v[130:131]
	global_store_short v[2:3], v1, off
	v_cvt_pk_bf16_f32 v1, v9, s0
	global_store_short v[66:67], v1, off offset:224
	v_cvt_pk_bf16_f32 v1, v5, s0
	v_lshl_add_u64 v[2:3], v[60:61], 0, v[130:131]
	global_store_short v[2:3], v1, off

.LBB0_537:
	v_lshl_add_u64 v[140:141], v[74:75], 0, s[2:3]
	v_add_co_u32_e32 v130, vcc, s5, v140
	v_lshl_add_u64 v[142:143], v[76:77], 0, s[2:3]
	s_nop 0
	v_addc_co_u32_e32 v134, vcc, 0, v141, vcc
	v_add_co_u32_e32 v137, vcc, s5, v142
	v_lshl_add_u64 v[140:141], v[78:79], 0, s[2:3]
	s_nop 0
	v_addc_co_u32_e32 v144, vcc, 0, v143, vcc
	v_add_co_u32_e32 v142, vcc, s5, v140
	v_lshl_add_u64 v[146:147], v[80:81], 0, s[2:3]
	s_nop 0
	v_addc_co_u32_e32 v143, vcc, 0, v141, vcc
	v_add_co_u32_e32 v140, vcc, s5, v146
	v_lshl_add_u64 v[148:149], v[72:73], 0, s[2:3]
	s_nop 0
	v_addc_co_u32_e32 v141, vcc, 0, v147, vcc
	v_add_co_u32_e32 v145, vcc, s6, v148
	v_lshl_add_u64 v[146:147], v[70:71], 0, s[2:3]
	s_nop 0
	v_addc_co_u32_e32 v150, vcc, 0, v149, vcc
	v_add_co_u32_e32 v148, vcc, s6, v146
	v_lshl_add_u64 v[152:153], v[68:69], 0, s[2:3]
	s_nop 0
	v_addc_co_u32_e32 v149, vcc, 0, v147, vcc
	v_add_co_u32_e32 v146, vcc, s6, v152
	v_lshl_add_u64 v[154:155], v[66:67], 0, s[2:3]
	s_nop 0
	v_addc_co_u32_e32 v147, vcc, 0, v153, vcc
	v_add_co_u32_e32 v151, vcc, s6, v154
	s_nop 1
	v_addc_co_u32_e32 v152, vcc, 0, v155, vcc
	v_mov_b32_e32 v154, v130
	v_mov_b32_e32 v155, v134
	global_load_dwordx4 v[156:159], v[154:155], off offset:320
	v_mov_b32_e32 v154, v137
	v_mov_b32_e32 v155, v144
	global_load_dwordx4 v[162:165], v[154:155], off offset:320
	global_load_dwordx4 v[168:171], v[142:143], off offset:320
	global_load_dwordx4 v[174:177], v[140:141], off offset:320
	v_mov_b32_e32 v140, v145
	v_mov_b32_e32 v141, v150
	global_load_dwordx4 v[180:183], v[140:141], off offset:320
	global_load_dwordx4 v[140:143], v[148:149], off offset:320
	global_load_dwordx4 v[184:187], v[146:147], off offset:320
	v_mov_b32_e32 v144, v151
	v_mov_b32_e32 v145, v152
	global_load_dwordx4 v[146:149], v[144:145], off offset:320
	v_lshl_add_u64 v[82:83], v[74:75], 0, s[2:3]
	v_add_co_u32_e32 v82, vcc, s5, v82
	v_lshl_add_u64 v[90:91], v[76:77], 0, s[2:3]
	s_nop 0
	v_addc_co_u32_e32 v83, vcc, 0, v83, vcc
	v_add_co_u32_e32 v118, vcc, s5, v90
	v_lshl_add_u64 v[94:95], v[78:79], 0, s[2:3]
	s_nop 0
	v_addc_co_u32_e32 v119, vcc, 0, v91, vcc
	v_add_co_u32_e32 v120, vcc, s5, v94
	v_lshl_add_u64 v[98:99], v[80:81], 0, s[2:3]
	s_nop 0
	v_addc_co_u32_e32 v121, vcc, 0, v95, vcc
	v_add_co_u32_e32 v122, vcc, s5, v98
	v_lshl_add_u64 v[102:103], v[72:73], 0, s[2:3]
	s_nop 0
	v_addc_co_u32_e32 v123, vcc, 0, v99, vcc
	v_add_co_u32_e32 v124, vcc, s6, v102
	v_lshl_add_u64 v[106:107], v[70:71], 0, s[2:3]
	s_nop 0
	v_addc_co_u32_e32 v125, vcc, 0, v103, vcc
	v_add_co_u32_e32 v126, vcc, s6, v106
	v_lshl_add_u64 v[110:111], v[68:69], 0, s[2:3]
	s_nop 0
	v_addc_co_u32_e32 v127, vcc, 0, v107, vcc
	global_load_dwordx4 v[86:89], v[82:83], off offset:256
	global_load_dwordx4 v[90:93], v[118:119], off offset:256
	global_load_dwordx4 v[94:97], v[120:121], off offset:256
	global_load_dwordx4 v[98:101], v[122:123], off offset:256
	v_add_co_u32_e32 v128, vcc, s6, v110
	v_lshl_add_u64 v[114:115], v[66:67], 0, s[2:3]
	s_nop 0
	v_addc_co_u32_e32 v129, vcc, 0, v111, vcc
	v_add_co_u32_e32 v138, vcc, s6, v114
	global_load_dwordx4 v[102:105], v[124:125], off offset:256
	global_load_dwordx4 v[106:109], v[126:127], off offset:256
	v_addc_co_u32_e32 v139, vcc, 0, v115, vcc
	global_load_dwordx4 v[110:113], v[128:129], off offset:256
	global_load_dwordx4 v[114:117], v[138:139], off offset:256
	s_add_u32 s2, s2, 0x80
	s_addc_u32 s3, s3, 0
	s_cmpk_lg_i32 s2, 0x200
	s_waitcnt vmcnt(3)
	v_mfma_f32_16x16x32_bf16 v[62:65], v[86:89], v[102:105], v[62:65]
	s_waitcnt vmcnt(2)
	v_mfma_f32_16x16x32_bf16 v[58:61], v[86:89], v[106:109], v[58:61]
	s_waitcnt vmcnt(1)
	v_mfma_f32_16x16x32_bf16 v[54:57], v[86:89], v[110:113], v[54:57]
	s_waitcnt vmcnt(0)
	v_mfma_f32_16x16x32_bf16 v[50:53], v[86:89], v[114:117], v[50:53]
	v_mfma_f32_16x16x32_bf16 v[38:41], v[90:93], v[102:105], v[38:41]
	v_mfma_f32_16x16x32_bf16 v[10:13], v[90:93], v[106:109], v[10:13]
	v_mfma_f32_16x16x32_bf16 v[6:9], v[90:93], v[110:113], v[6:9]
	v_mfma_f32_16x16x32_bf16 v[2:5], v[90:93], v[114:117], v[2:5]
	v_mfma_f32_16x16x32_bf16 v[46:49], v[94:97], v[102:105], v[46:49]
	v_mfma_f32_16x16x32_bf16 v[42:45], v[94:97], v[106:109], v[42:45]
	v_mfma_f32_16x16x32_bf16 v[34:37], v[94:97], v[110:113], v[34:37]
	v_mfma_f32_16x16x32_bf16 v[26:29], v[94:97], v[114:117], v[26:29]
	v_mfma_f32_16x16x32_bf16 v[30:33], v[98:101], v[102:105], v[30:33]
	v_mfma_f32_16x16x32_bf16 v[22:25], v[98:101], v[106:109], v[22:25]
	v_mfma_f32_16x16x32_bf16 v[18:21], v[98:101], v[110:113], v[18:21]
	v_mfma_f32_16x16x32_bf16 v[14:17], v[98:101], v[114:117], v[14:17]
	s_waitcnt vmcnt(0)
	v_mfma_f32_16x16x32_bf16 v[62:65], v[156:159], v[180:183], v[62:65]
	v_mfma_f32_16x16x32_bf16 v[58:61], v[156:159], v[140:143], v[58:61]
	v_mfma_f32_16x16x32_bf16 v[54:57], v[156:159], v[184:187], v[54:57]
	v_mfma_f32_16x16x32_bf16 v[50:53], v[156:159], v[146:149], v[50:53]
	v_mfma_f32_16x16x32_bf16 v[38:41], v[162:165], v[180:183], v[38:41]
	v_mfma_f32_16x16x32_bf16 v[10:13], v[162:165], v[140:143], v[10:13]
	v_mfma_f32_16x16x32_bf16 v[6:9], v[162:165], v[184:187], v[6:9]
	v_mfma_f32_16x16x32_bf16 v[2:5], v[162:165], v[146:149], v[2:5]
	v_mfma_f32_16x16x32_bf16 v[46:49], v[168:171], v[180:183], v[46:49]
	v_mfma_f32_16x16x32_bf16 v[42:45], v[168:171], v[140:143], v[42:45]
	v_mfma_f32_16x16x32_bf16 v[34:37], v[168:171], v[184:187], v[34:37]
	v_mfma_f32_16x16x32_bf16 v[26:29], v[168:171], v[146:149], v[26:29]
	v_mfma_f32_16x16x32_bf16 v[30:33], v[174:177], v[180:183], v[30:33]
	v_mfma_f32_16x16x32_bf16 v[22:25], v[174:177], v[140:143], v[22:25]
	v_mfma_f32_16x16x32_bf16 v[18:21], v[174:177], v[184:187], v[18:21]
	v_mfma_f32_16x16x32_bf16 v[14:17], v[174:177], v[146:149], v[14:17]
	s_cbranch_scc1 .LBB0_537
	v_and_b32_e32 v66, 3, v84
	v_and_b32_e32 v1, 0xffffffc0, v1
	s_lshl_b64 s[0:1], s[0:1], 9
	v_readlane_b32 s2, v254, 9
	v_lshl_or_b32 v66, v66, 2, v1
	v_lshl_or_b32 v68, s4, 6, v85
	v_readlane_b32 s3, v254, 10
	s_add_u32 s0, s2, s0
	s_addc_u32 s1, s3, s1
	v_ashrrev_i32_e32 v67, 31, v66
	v_ashrrev_i32_e32 v69, 31, v68
	v_lshl_add_u64 v[66:67], v[66:67], 1, s[0:1]
	v_cvt_pk_bf16_f32 v62, v62, v63
	v_cvt_pk_bf16_f32 v63, v64, v65
	v_lshlrev_b64 v[64:65], 14, v[68:69]
	v_lshl_add_u64 v[64:65], v[66:67], 0, v[64:65]
	global_store_dwordx2 v[64:65], v[62:63], off
	v_or_b32_e32 v62, 16, v68
	v_ashrrev_i32_e32 v63, 31, v62
	v_cvt_pk_bf16_f32 v58, v58, v59
	v_cvt_pk_bf16_f32 v59, v60, v61
	v_lshlrev_b64 v[60:61], 14, v[62:63]
	v_lshl_add_u64 v[60:61], v[66:67], 0, v[60:61]
	global_store_dwordx2 v[60:61], v[58:59], off
	v_or_b32_e32 v58, 32, v68
	v_ashrrev_i32_e32 v59, 31, v58
	v_cvt_pk_bf16_f32 v54, v54, v55
	v_cvt_pk_bf16_f32 v55, v56, v57
	v_lshlrev_b64 v[56:57], 14, v[58:59]
	v_lshl_add_u64 v[56:57], v[66:67], 0, v[56:57]
	global_store_dwordx2 v[56:57], v[54:55], off
	v_or_b32_e32 v54, 48, v68
	v_ashrrev_i32_e32 v55, 31, v54
	v_cvt_pk_bf16_f32 v50, v50, v51
	v_cvt_pk_bf16_f32 v51, v52, v53
	v_lshlrev_b64 v[52:53], 14, v[54:55]
	v_lshl_add_u64 v[52:53], v[66:67], 0, v[52:53]
	v_cvt_pk_bf16_f32 v2, v2, v3
	v_cvt_pk_bf16_f32 v3, v4, v5
	global_store_dwordx2 v[52:53], v[2:3], off offset:32
	v_cvt_pk_bf16_f32 v2, v46, v47
	v_cvt_pk_bf16_f32 v3, v48, v49
	global_store_dwordx2 v[64:65], v[2:3], off offset:64
	v_cvt_pk_bf16_f32 v2, v42, v43
	v_cvt_pk_bf16_f32 v3, v44, v45
	global_store_dwordx2 v[60:61], v[2:3], off offset:64
	v_cvt_pk_bf16_f32 v2, v34, v35
	v_cvt_pk_bf16_f32 v3, v36, v37
	global_store_dwordx2 v[56:57], v[2:3], off offset:64
	v_cvt_pk_bf16_f32 v2, v26, v27
	v_cvt_pk_bf16_f32 v3, v28, v29
	global_store_dwordx2 v[52:53], v[2:3], off offset:64
	v_cvt_pk_bf16_f32 v2, v30, v31
	v_cvt_pk_bf16_f32 v3, v32, v33
	global_store_dwordx2 v[64:65], v[2:3], off offset:96
	v_cvt_pk_bf16_f32 v2, v22, v23
	v_cvt_pk_bf16_f32 v3, v24, v25
	global_store_dwordx2 v[60:61], v[2:3], off offset:96
	v_cvt_pk_bf16_f32 v2, v18, v19
	v_cvt_pk_bf16_f32 v3, v20, v21
	v_cvt_pk_bf16_f32 v38, v38, v39
	v_cvt_pk_bf16_f32 v39, v40, v41
	v_cvt_pk_bf16_f32 v10, v10, v11
	v_cvt_pk_bf16_f32 v11, v12, v13
	v_cvt_pk_bf16_f32 v6, v6, v7
	v_cvt_pk_bf16_f32 v7, v8, v9
	global_store_dwordx2 v[56:57], v[2:3], off offset:96
	v_cvt_pk_bf16_f32 v2, v14, v15
	v_cvt_pk_bf16_f32 v3, v16, v17
	global_store_dwordx2 v[52:53], v[50:51], off
	global_store_dwordx2 v[64:65], v[38:39], off offset:32
	global_store_dwordx2 v[60:61], v[10:11], off offset:32
	global_store_dwordx2 v[56:57], v[6:7], off offset:32
	global_store_dwordx2 v[52:53], v[2:3], off offset:96

.LBB0_632:
	s_and_b32 s88, s29, 0x7fffff00
	s_add_i32 s4, s7, 0xffffb400
	s_and_b32 s20, s4, 0x7f0
	s_lshl_b64 s[18:19], s[88:89], 2
	v_mov_b32_e32 v16, v0
	s_add_u32 s18, s8, s18
	s_movk_i32 s4, 0x100
	v_ashrrev_i32_e32 v17, 31, v16
	s_addc_u32 s19, s9, s19
	v_cmp_gt_i32_e64 s[4:5], s4, v16
	v_lshl_add_u64 v[18:19], v[16:17], 2, s[18:19]
	s_waitcnt vmcnt(0)
	v_mov_b32_e32 v82, 1.0
	v_mov_b32_e32 v83, 1.0
	v_mov_b32_e32 v84, 1.0
	v_mov_b32_e32 v85, 1.0
	v_mov_b32_e32 v86, 1.0
	v_mov_b32_e32 v87, 1.0
	v_mov_b32_e32 v88, 1.0
	v_mov_b32_e32 v89, 1.0
	v_mov_b32_e32 v90, 1.0
	v_mov_b32_e32 v91, 1.0
	v_mov_b32_e32 v92, 1.0
	v_mov_b32_e32 v93, 1.0
	v_mov_b32_e32 v94, 1.0
	v_mov_b32_e32 v95, 1.0
	v_mov_b32_e32 v96, 1.0
	v_mov_b32_e32 v97, 1.0
	v_mov_b32_e32 v2, 0
	s_and_saveexec_b64 s[18:19], s[4:5]
	s_cbranch_execz .LBB0_634
	s_lshl_b32 vcc_lo, s20, 12
	s_mov_b32 vcc_hi, s89
	v_lshl_add_u64 v[2:3], v[18:19], 0, vcc
	global_load_dword v2, v[2:3], off
.LBB0_634:
	s_or_b64 exec, exec, s[18:19]
	s_cmpk_lt_u32 s20, 0x400
	s_cselect_b64 s[18:19], -1, 0
	s_and_b64 s[18:19], s[34:35], s[18:19]
	s_andn2_b64 vcc, exec, s[18:19]
	s_cbranch_vccnz .LBB0_636
	s_lshl_b32 s18, s20, 2
	v_mov_b32_e32 v1, s18
	global_load_dword v82, v1, s[10:11]

.LBB0_638:
	s_or_b64 exec, exec, s[18:19]
	s_cmpk_lt_u32 s20, 0x3ff
	s_cselect_b64 s[18:19], -1, 0
	s_and_b64 s[18:19], s[34:35], s[18:19]
	s_andn2_b64 vcc, exec, s[18:19]
	s_cbranch_vccnz .LBB0_640
	s_lshl_b32 s18, s20, 2
	v_mov_b32_e32 v1, s18
	global_load_dword v83, v1, s[10:11] offset:4

.LBB0_642:
	s_or_b64 exec, exec, s[18:19]
	s_cmpk_lt_u32 s20, 0x3fe
	s_cselect_b64 s[18:19], -1, 0
	s_and_b64 s[18:19], s[34:35], s[18:19]
	s_andn2_b64 vcc, exec, s[18:19]
	s_cbranch_vccnz .LBB0_644
	s_lshl_b32 s18, s20, 2
	v_mov_b32_e32 v1, s18
	global_load_dword v84, v1, s[10:11] offset:8

.LBB0_646:
	s_or_b64 exec, exec, s[18:19]
	s_cmpk_lt_u32 s20, 0x3fd
	s_cselect_b64 s[18:19], -1, 0
	s_and_b64 s[18:19], s[34:35], s[18:19]
	s_andn2_b64 vcc, exec, s[18:19]
	s_cbranch_vccnz .LBB0_648
	s_lshl_b32 s18, s20, 2
	v_mov_b32_e32 v1, s18
	global_load_dword v85, v1, s[10:11] offset:12

.LBB0_650:
	s_or_b64 exec, exec, s[18:19]
	s_cmpk_lt_u32 s20, 0x3fc
	s_cselect_b64 s[18:19], -1, 0
	s_and_b64 s[18:19], s[34:35], s[18:19]
	s_andn2_b64 vcc, exec, s[18:19]
	s_cbranch_vccnz .LBB0_652
	s_lshl_b32 s18, s20, 2
	v_mov_b32_e32 v1, s18
	global_load_dword v86, v1, s[10:11] offset:16

.LBB0_654:
	s_or_b64 exec, exec, s[18:19]
	s_cmpk_lt_u32 s20, 0x3fb
	s_cselect_b64 s[18:19], -1, 0
	s_and_b64 s[18:19], s[34:35], s[18:19]
	s_andn2_b64 vcc, exec, s[18:19]
	s_cbranch_vccnz .LBB0_656
	s_lshl_b32 s18, s20, 2
	v_mov_b32_e32 v1, s18
	global_load_dword v87, v1, s[10:11] offset:20

.LBB0_658:
	s_or_b64 exec, exec, s[18:19]
	s_cmpk_lt_u32 s20, 0x3fa
	s_cselect_b64 s[18:19], -1, 0
	s_and_b64 s[18:19], s[34:35], s[18:19]
	s_andn2_b64 vcc, exec, s[18:19]
	s_cbranch_vccnz .LBB0_660
	s_lshl_b32 s18, s20, 2
	v_mov_b32_e32 v1, s18
	global_load_dword v88, v1, s[10:11] offset:24

.LBB0_662:
	s_or_b64 exec, exec, s[18:19]
	s_cmpk_lt_u32 s20, 0x3f9
	s_cselect_b64 s[18:19], -1, 0
	s_and_b64 s[18:19], s[34:35], s[18:19]
	s_andn2_b64 vcc, exec, s[18:19]
	s_cbranch_vccnz .LBB0_664
	s_lshl_b32 s18, s20, 2
	v_mov_b32_e32 v1, s18
	global_load_dword v89, v1, s[10:11] offset:28

.LBB0_666:
	s_or_b64 exec, exec, s[18:19]
	s_cmpk_lt_u32 s20, 0x3f8
	s_cselect_b64 s[18:19], -1, 0
	s_and_b64 s[18:19], s[34:35], s[18:19]
	s_andn2_b64 vcc, exec, s[18:19]
	s_cbranch_vccnz .LBB0_668
	s_lshl_b32 s18, s20, 2
	v_mov_b32_e32 v1, s18
	global_load_dword v90, v1, s[10:11] offset:32

.LBB0_670:
	s_or_b64 exec, exec, s[18:19]
	s_cmpk_lt_u32 s20, 0x3f7
	s_cselect_b64 s[18:19], -1, 0
	s_and_b64 s[18:19], s[34:35], s[18:19]
	s_andn2_b64 vcc, exec, s[18:19]
	s_cbranch_vccnz .LBB0_672
	s_lshl_b32 s18, s20, 2
	v_mov_b32_e32 v1, s18
	global_load_dword v91, v1, s[10:11] offset:36

.LBB0_674:
	s_or_b64 exec, exec, s[18:19]
	s_cmpk_lt_u32 s20, 0x3f6
	s_cselect_b64 s[18:19], -1, 0
	s_and_b64 s[18:19], s[34:35], s[18:19]
	s_andn2_b64 vcc, exec, s[18:19]
	s_cbranch_vccnz .LBB0_676
	s_lshl_b32 s18, s20, 2
	v_mov_b32_e32 v1, s18
	global_load_dword v92, v1, s[10:11] offset:40

.LBB0_678:
	s_or_b64 exec, exec, s[18:19]
	s_cmpk_lt_u32 s20, 0x3f5
	s_cselect_b64 s[18:19], -1, 0
	s_and_b64 s[18:19], s[34:35], s[18:19]
	s_andn2_b64 vcc, exec, s[18:19]
	s_cbranch_vccnz .LBB0_680
	s_lshl_b32 s18, s20, 2
	v_mov_b32_e32 v1, s18
	global_load_dword v93, v1, s[10:11] offset:44

.LBB0_682:
	s_or_b64 exec, exec, s[18:19]
	s_cmpk_lt_u32 s20, 0x3f4
	s_cselect_b64 s[18:19], -1, 0
	s_and_b64 s[18:19], s[34:35], s[18:19]
	s_andn2_b64 vcc, exec, s[18:19]
	s_cbranch_vccnz .LBB0_684
	s_lshl_b32 s18, s20, 2
	v_mov_b32_e32 v1, s18
	global_load_dword v94, v1, s[10:11] offset:48

.LBB0_686:
	s_or_b64 exec, exec, s[18:19]
	s_cmpk_lt_u32 s20, 0x3f3
	s_cselect_b64 s[18:19], -1, 0
	s_and_b64 s[18:19], s[34:35], s[18:19]
	s_andn2_b64 vcc, exec, s[18:19]
	s_cbranch_vccnz .LBB0_688
	s_lshl_b32 s18, s20, 2
	v_mov_b32_e32 v1, s18
	global_load_dword v95, v1, s[10:11] offset:52

.LBB0_690:
	s_or_b64 exec, exec, s[18:19]
	s_cmpk_lt_u32 s20, 0x3f2
	s_cselect_b64 s[18:19], -1, 0
	s_and_b64 s[18:19], s[34:35], s[18:19]
	s_andn2_b64 vcc, exec, s[18:19]
	s_cbranch_vccnz .LBB0_692
	s_lshl_b32 s18, s20, 2
	v_mov_b32_e32 v1, s18
	global_load_dword v96, v1, s[10:11] offset:56

.LBB0_694:
	s_or_b64 exec, exec, s[18:19]
	s_cmpk_lt_u32 s20, 0x3f1
	s_cselect_b64 s[4:5], -1, 0
	s_and_b64 s[4:5], s[34:35], s[4:5]
	s_andn2_b64 vcc, exec, s[4:5]
	s_cbranch_vccnz .LBB0_696
	s_lshl_b32 s4, s20, 2
	v_mov_b32_e32 v1, s4
	global_load_dword v97, v1, s[10:11] offset:60
.LBB0_696:
	s_waitcnt vmcnt(0)
	v_mul_f32_e32 v2, v2, v82
	v_mul_f32_e32 v3, v3, v83
	v_mul_f32_e32 v4, v4, v84
	v_mul_f32_e32 v5, v5, v85
	v_mul_f32_e32 v6, v6, v86
	v_mul_f32_e32 v7, v7, v87
	v_mul_f32_e32 v8, v8, v88
	v_mul_f32_e32 v9, v9, v89
	v_mul_f32_e32 v10, v10, v90
	v_mul_f32_e32 v11, v11, v91
	v_mul_f32_e32 v12, v12, v92
	v_mul_f32_e32 v13, v13, v93
	v_mul_f32_e32 v14, v14, v94
	v_mul_f32_e32 v15, v15, v95
	v_mul_f32_e32 v20, v20, v96
	v_mul_f32_e32 v21, v21, v97
	v_add_u32_e32 v16, s88, v16
	s_movk_i32 s4, 0x400
	v_cmp_gt_i32_e32 vcc, s4, v16
	s_and_saveexec_b64 s[4:5], vcc
	s_xor_b64 s[4:5], exec, s[4:5]
	s_or_b64 s[14:15], s[14:15], exec
	s_or_b64 exec, exec, s[4:5]
	v_readlane_b32 s18, v253, 35
	s_mov_b64 s[4:5], 12
	v_readlane_b32 s19, v253, 36
	s_branch .LBB0_734

.LBB0_757:
	s_add_i32 s8, s8, 2
	v_lshl_add_u64 v[140:141], v[140:141], 0, s[92:93]
	v_lshl_add_u64 v[142:143], v[142:143], 0, s[92:93]
	v_lshl_add_u64 v[144:145], v[144:145], 0, s[92:93]
	v_lshl_add_u64 v[146:147], v[146:147], 0, s[92:93]
	v_lshl_add_u64 v[148:149], v[148:149], 0, s[92:93]
	s_and_b64 vcc, exec, s[4:5]
	s_cbranch_vccnz .LBB0_764

.LBB0_760:
	s_and_b64 vcc, exec, s[4:5]
	s_cbranch_vccnz .Lg0_h0_last
	ds_read_b128 v[174:177], v160 offset:32768
	ds_read_b128 v[180:183], v160 offset:34816
	ds_read_b128 v[184:187], v160 offset:36864
	ds_read_b128 v[188:191], v160 offset:38912
	ds_read_b128 v[168:171], v139
	ds_read_b128 v[192:195], v139 offset:2048
	ds_read_b128 v[234:237], v139 offset:4096
	s_waitcnt lgkmcnt(2)
	v_mfma_f32_16x16x32_bf16 v[62:65], v[168:171], v[174:177], v[62:65]
	v_mfma_f32_16x16x32_bf16 v[58:61], v[168:171], v[180:183], v[58:61]
	v_mfma_f32_16x16x32_bf16 v[54:57], v[168:171], v[184:187], v[54:57]
	v_mfma_f32_16x16x32_bf16 v[50:53], v[168:171], v[188:191], v[50:53]
	ds_read_b128 v[238:241], v139 offset:6144
	s_waitcnt lgkmcnt(2)
	v_mfma_f32_16x16x32_bf16 v[46:49], v[192:195], v[174:177], v[46:49]
	v_mfma_f32_16x16x32_bf16 v[42:45], v[192:195], v[180:183], v[42:45]
	v_mfma_f32_16x16x32_bf16 v[38:41], v[192:195], v[184:187], v[38:41]
	v_mfma_f32_16x16x32_bf16 v[34:37], v[192:195], v[188:191], v[34:37]
	ds_read_b128 v[218:221], v163 offset:32768
	ds_read_b128 v[222:225], v163 offset:34816
	s_waitcnt lgkmcnt(3)
	v_mfma_f32_16x16x32_bf16 v[30:33], v[234:237], v[174:177], v[30:33]
	v_mfma_f32_16x16x32_bf16 v[26:29], v[234:237], v[180:183], v[26:29]
	v_mfma_f32_16x16x32_bf16 v[22:25], v[234:237], v[184:187], v[22:25]
	v_mfma_f32_16x16x32_bf16 v[18:21], v[234:237], v[188:191], v[18:21]
	ds_read_b128 v[226:229], v163 offset:36864
	ds_read_b128 v[230:233], v163 offset:38912
	ds_read_b128 v[168:171], v162
	s_waitcnt lgkmcnt(5)
	v_mfma_f32_16x16x32_bf16 v[14:17], v[238:241], v[174:177], v[14:17]
	v_mfma_f32_16x16x32_bf16 v[10:13], v[238:241], v[180:183], v[10:13]
	v_mfma_f32_16x16x32_bf16 v[6:9], v[238:241], v[184:187], v[6:9]
	v_mfma_f32_16x16x32_bf16 v[2:5], v[238:241], v[188:191], v[2:5]
	ds_read_b128 v[192:195], v162 offset:2048
	s_waitcnt vmcnt(15)
	ds_write_b128 v137, v[98:101] offset:16384
	s_waitcnt vmcnt(13)
	ds_write_b128 v137, v[102:105] offset:20480
	s_waitcnt lgkmcnt(3)
	v_mfma_f32_16x16x32_bf16 v[62:65], v[168:171], v[218:221], v[62:65]
	v_mfma_f32_16x16x32_bf16 v[58:61], v[168:171], v[222:225], v[58:61]
	v_mfma_f32_16x16x32_bf16 v[54:57], v[168:171], v[226:229], v[54:57]
	v_mfma_f32_16x16x32_bf16 v[50:53], v[168:171], v[230:233], v[50:53]
	ds_read_b128 v[234:237], v162 offset:4096
	s_waitcnt vmcnt(12)
	ds_write_b128 v137, v[106:109] offset:24576
	s_waitcnt vmcnt(11)
	ds_write_b128 v137, v[110:113] offset:28672
	s_waitcnt vmcnt(11)
	ds_write_b128 v137, v[114:117] offset:49152
	s_waitcnt lgkmcnt(6)
	v_mfma_f32_16x16x32_bf16 v[46:49], v[192:195], v[218:221], v[46:49]
	v_mfma_f32_16x16x32_bf16 v[42:45], v[192:195], v[222:225], v[42:45]
	v_mfma_f32_16x16x32_bf16 v[38:41], v[192:195], v[226:229], v[38:41]
	v_mfma_f32_16x16x32_bf16 v[34:37], v[192:195], v[230:233], v[34:37]
	ds_read_b128 v[238:241], v162 offset:6144
	s_waitcnt vmcnt(10)
	ds_write_b128 v137, v[118:121] offset:53248
	s_waitcnt vmcnt(9)
	ds_write_b128 v137, v[122:125] offset:57344
	s_waitcnt vmcnt(8)
	ds_write_b128 v137, v[126:129] offset:61440
	s_waitcnt lgkmcnt(0)
	s_barrier
	v_mfma_f32_16x16x32_bf16 v[30:33], v[234:237], v[218:221], v[30:33]
	v_mfma_f32_16x16x32_bf16 v[26:29], v[234:237], v[222:225], v[26:29]
	v_mfma_f32_16x16x32_bf16 v[22:25], v[234:237], v[226:229], v[22:25]
	v_mfma_f32_16x16x32_bf16 v[18:21], v[234:237], v[230:233], v[18:21]
	v_mfma_f32_16x16x32_bf16 v[14:17], v[238:241], v[218:221], v[14:17]
	v_mfma_f32_16x16x32_bf16 v[10:13], v[238:241], v[222:225], v[10:13]
	v_mfma_f32_16x16x32_bf16 v[6:9], v[238:241], v[226:229], v[6:9]
	v_mfma_f32_16x16x32_bf16 v[2:5], v[238:241], v[230:233], v[2:5]
	s_branch .Lg0_h0_done
.Lg0_h0_last:
	ds_read_b128 v[174:177], v160 offset:32768
	ds_read_b128 v[180:183], v160 offset:34816
	ds_read_b128 v[184:187], v160 offset:36864
	ds_read_b128 v[188:191], v160 offset:38912
	ds_read_b128 v[168:171], v139
	ds_read_b128 v[192:195], v139 offset:2048
	ds_read_b128 v[234:237], v139 offset:4096
	s_waitcnt lgkmcnt(2)
	v_mfma_f32_16x16x32_bf16 v[62:65], v[168:171], v[174:177], v[62:65]
	v_mfma_f32_16x16x32_bf16 v[58:61], v[168:171], v[180:183], v[58:61]
	v_mfma_f32_16x16x32_bf16 v[54:57], v[168:171], v[184:187], v[54:57]
	v_mfma_f32_16x16x32_bf16 v[50:53], v[168:171], v[188:191], v[50:53]
	ds_read_b128 v[238:241], v139 offset:6144
	s_waitcnt lgkmcnt(2)
	v_mfma_f32_16x16x32_bf16 v[46:49], v[192:195], v[174:177], v[46:49]
	v_mfma_f32_16x16x32_bf16 v[42:45], v[192:195], v[180:183], v[42:45]
	v_mfma_f32_16x16x32_bf16 v[38:41], v[192:195], v[184:187], v[38:41]
	v_mfma_f32_16x16x32_bf16 v[34:37], v[192:195], v[188:191], v[34:37]
	ds_read_b128 v[218:221], v163 offset:32768
	ds_read_b128 v[222:225], v163 offset:34816
	s_waitcnt lgkmcnt(3)
	v_mfma_f32_16x16x32_bf16 v[30:33], v[234:237], v[174:177], v[30:33]
	v_mfma_f32_16x16x32_bf16 v[26:29], v[234:237], v[180:183], v[26:29]
	v_mfma_f32_16x16x32_bf16 v[22:25], v[234:237], v[184:187], v[22:25]
	v_mfma_f32_16x16x32_bf16 v[18:21], v[234:237], v[188:191], v[18:21]
	ds_read_b128 v[226:229], v163 offset:36864
	ds_read_b128 v[230:233], v163 offset:38912
	ds_read_b128 v[168:171], v162
	s_waitcnt lgkmcnt(5)
	v_mfma_f32_16x16x32_bf16 v[14:17], v[238:241], v[174:177], v[14:17]
	v_mfma_f32_16x16x32_bf16 v[10:13], v[238:241], v[180:183], v[10:13]
	v_mfma_f32_16x16x32_bf16 v[6:9], v[238:241], v[184:187], v[6:9]
	v_mfma_f32_16x16x32_bf16 v[2:5], v[238:241], v[188:191], v[2:5]
	ds_read_b128 v[192:195], v162 offset:2048
	s_waitcnt vmcnt(7)
	ds_write_b128 v137, v[98:101] offset:16384
	s_waitcnt vmcnt(5)
	ds_write_b128 v137, v[102:105] offset:20480
	s_waitcnt lgkmcnt(3)
	v_mfma_f32_16x16x32_bf16 v[62:65], v[168:171], v[218:221], v[62:65]
	v_mfma_f32_16x16x32_bf16 v[58:61], v[168:171], v[222:225], v[58:61]
	v_mfma_f32_16x16x32_bf16 v[54:57], v[168:171], v[226:229], v[54:57]
	v_mfma_f32_16x16x32_bf16 v[50:53], v[168:171], v[230:233], v[50:53]
	ds_read_b128 v[234:237], v162 offset:4096
	s_waitcnt vmcnt(4)
	ds_write_b128 v137, v[106:109] offset:24576
	s_waitcnt vmcnt(3)
	ds_write_b128 v137, v[110:113] offset:28672
	s_waitcnt vmcnt(3)
	ds_write_b128 v137, v[114:117] offset:49152
	s_waitcnt lgkmcnt(6)
	v_mfma_f32_16x16x32_bf16 v[46:49], v[192:195], v[218:221], v[46:49]
	v_mfma_f32_16x16x32_bf16 v[42:45], v[192:195], v[222:225], v[42:45]
	v_mfma_f32_16x16x32_bf16 v[38:41], v[192:195], v[226:229], v[38:41]
	v_mfma_f32_16x16x32_bf16 v[34:37], v[192:195], v[230:233], v[34:37]
	ds_read_b128 v[238:241], v162 offset:6144
	s_waitcnt vmcnt(2)
	ds_write_b128 v137, v[118:121] offset:53248
	s_waitcnt vmcnt(1)
	ds_write_b128 v137, v[122:125] offset:57344
	s_waitcnt vmcnt(0)
	ds_write_b128 v137, v[126:129] offset:61440
	s_waitcnt lgkmcnt(0)
	s_barrier
	v_mfma_f32_16x16x32_bf16 v[30:33], v[234:237], v[218:221], v[30:33]
	v_mfma_f32_16x16x32_bf16 v[26:29], v[234:237], v[222:225], v[26:29]
	v_mfma_f32_16x16x32_bf16 v[22:25], v[234:237], v[226:229], v[22:25]
	v_mfma_f32_16x16x32_bf16 v[18:21], v[234:237], v[230:233], v[18:21]
	v_mfma_f32_16x16x32_bf16 v[14:17], v[238:241], v[218:221], v[14:17]
	v_mfma_f32_16x16x32_bf16 v[10:13], v[238:241], v[222:225], v[10:13]
	v_mfma_f32_16x16x32_bf16 v[6:9], v[238:241], v[226:229], v[6:9]
	v_mfma_f32_16x16x32_bf16 v[2:5], v[238:241], v[230:233], v[2:5]
.Lg0_h0_done:
	s_cmp_gt_u32 s8, 12
	s_cbranch_scc1 .LBB0_762
	v_add_co_u32_e32 v98, vcc, 0xacb1000, v158
	s_nop 1
	v_addc_co_u32_e32 v99, vcc, 0, v159, vcc
	v_add_co_u32_e32 v102, vcc, 0xacb1000, v156
	global_load_dwordx4 v[98:101], v[98:99], off offset:640
	s_nop 0
	v_addc_co_u32_e32 v103, vcc, 0, v157, vcc
	v_add_co_u32_e32 v106, vcc, 0xacb1000, v154
	global_load_dwordx4 v[102:105], v[102:103], off offset:640
	s_nop 0
	v_addc_co_u32_e32 v107, vcc, 0, v155, vcc
	v_add_co_u32_e32 v110, vcc, 0xacb1000, v152
	global_load_dwordx4 v[106:109], v[106:107], off offset:640
	s_nop 0
	v_addc_co_u32_e32 v111, vcc, 0, v153, vcc
	v_add_co_u32_e32 v114, vcc, 0xa371000, v150
	global_load_dwordx4 v[110:113], v[110:111], off offset:640
	s_nop 0
	v_addc_co_u32_e32 v115, vcc, 0, v151, vcc
	v_add_co_u32_e32 v118, vcc, 0xa381000, v150
	s_nop 1
	v_addc_co_u32_e32 v119, vcc, 0, v151, vcc
	v_add_co_u32_e32 v122, vcc, 0xa391000, v150
	global_load_dwordx4 v[114:117], v[114:115], off offset:640
	s_nop 0
	global_load_dwordx4 v[118:121], v[118:119], off offset:640
	v_addc_co_u32_e32 v123, vcc, 0, v151, vcc
	v_add_co_u32_e32 v126, vcc, 0xa3a1000, v150
	s_nop 1
	v_addc_co_u32_e32 v127, vcc, 0, v151, vcc
	global_load_dwordx4 v[122:125], v[122:123], off offset:640
	s_nop 0
	global_load_dwordx4 v[126:129], v[126:127], off offset:640
.LBB0_762:
	s_andn2_b64 vcc, exec, s[6:7]
	s_cbranch_vccnz .Lg0_h1_nowrite
	ds_read_b128 v[174:177], v160 offset:49152
	ds_read_b128 v[180:183], v160 offset:51200
	ds_read_b128 v[184:187], v160 offset:53248
	ds_read_b128 v[188:191], v160 offset:55296
	ds_read_b128 v[168:171], v139 offset:16384
	ds_read_b128 v[192:195], v139 offset:18432
	ds_read_b128 v[234:237], v139 offset:20480
	s_waitcnt lgkmcnt(2)
	v_mfma_f32_16x16x32_bf16 v[62:65], v[168:171], v[174:177], v[62:65]
	v_mfma_f32_16x16x32_bf16 v[58:61], v[168:171], v[180:183], v[58:61]
	v_mfma_f32_16x16x32_bf16 v[54:57], v[168:171], v[184:187], v[54:57]
	v_mfma_f32_16x16x32_bf16 v[50:53], v[168:171], v[188:191], v[50:53]
	ds_read_b128 v[238:241], v139 offset:22528
	s_waitcnt lgkmcnt(2)
	v_mfma_f32_16x16x32_bf16 v[46:49], v[192:195], v[174:177], v[46:49]
	v_mfma_f32_16x16x32_bf16 v[42:45], v[192:195], v[180:183], v[42:45]
	v_mfma_f32_16x16x32_bf16 v[38:41], v[192:195], v[184:187], v[38:41]
	v_mfma_f32_16x16x32_bf16 v[34:37], v[192:195], v[188:191], v[34:37]
	ds_read_b128 v[218:221], v163 offset:49152
	ds_read_b128 v[222:225], v163 offset:51200
	s_waitcnt lgkmcnt(3)
	v_mfma_f32_16x16x32_bf16 v[30:33], v[234:237], v[174:177], v[30:33]
	v_mfma_f32_16x16x32_bf16 v[26:29], v[234:237], v[180:183], v[26:29]
	v_mfma_f32_16x16x32_bf16 v[22:25], v[234:237], v[184:187], v[22:25]
	v_mfma_f32_16x16x32_bf16 v[18:21], v[234:237], v[188:191], v[18:21]
	ds_read_b128 v[226:229], v163 offset:53248
	ds_read_b128 v[230:233], v163 offset:55296
	ds_read_b128 v[168:171], v162 offset:16384
	s_waitcnt lgkmcnt(5)
	v_mfma_f32_16x16x32_bf16 v[14:17], v[238:241], v[174:177], v[14:17]
	v_mfma_f32_16x16x32_bf16 v[10:13], v[238:241], v[180:183], v[10:13]
	v_mfma_f32_16x16x32_bf16 v[6:9], v[238:241], v[184:187], v[6:9]
	v_mfma_f32_16x16x32_bf16 v[2:5], v[238:241], v[188:191], v[2:5]
	ds_read_b128 v[192:195], v162 offset:18432
	s_waitcnt vmcnt(15)
	ds_write_b128 v137, v[66:69]
	s_waitcnt vmcnt(14)
	ds_write_b128 v137, v[70:73] offset:4096
	s_waitcnt lgkmcnt(3)
	v_mfma_f32_16x16x32_bf16 v[62:65], v[168:171], v[218:221], v[62:65]
	v_mfma_f32_16x16x32_bf16 v[58:61], v[168:171], v[222:225], v[58:61]
	v_mfma_f32_16x16x32_bf16 v[54:57], v[168:171], v[226:229], v[54:57]
	v_mfma_f32_16x16x32_bf16 v[50:53], v[168:171], v[230:233], v[50:53]
	ds_read_b128 v[234:237], v162 offset:20480
	s_waitcnt vmcnt(13)
	ds_write_b128 v137, v[74:77] offset:8192
	s_waitcnt vmcnt(12)
	ds_write_b128 v137, v[78:81] offset:12288
	s_waitcnt vmcnt(11)
	ds_write_b128 v137, v[82:85] offset:32768
	s_waitcnt lgkmcnt(6)
	v_mfma_f32_16x16x32_bf16 v[46:49], v[192:195], v[218:221], v[46:49]
	v_mfma_f32_16x16x32_bf16 v[42:45], v[192:195], v[222:225], v[42:45]
	v_mfma_f32_16x16x32_bf16 v[38:41], v[192:195], v[226:229], v[38:41]
	v_mfma_f32_16x16x32_bf16 v[34:37], v[192:195], v[230:233], v[34:37]
	ds_read_b128 v[238:241], v162 offset:22528
	s_waitcnt vmcnt(10)
	ds_write_b128 v137, v[86:89] offset:36864
	s_waitcnt vmcnt(9)
	ds_write_b128 v137, v[90:93] offset:40960
	s_waitcnt vmcnt(8)
	ds_write_b128 v137, v[94:97] offset:45056
	s_waitcnt lgkmcnt(0)
	s_barrier
	v_mfma_f32_16x16x32_bf16 v[30:33], v[234:237], v[218:221], v[30:33]
	v_mfma_f32_16x16x32_bf16 v[26:29], v[234:237], v[222:225], v[26:29]
	v_mfma_f32_16x16x32_bf16 v[22:25], v[234:237], v[226:229], v[22:25]
	v_mfma_f32_16x16x32_bf16 v[18:21], v[234:237], v[230:233], v[18:21]
	v_mfma_f32_16x16x32_bf16 v[14:17], v[238:241], v[218:221], v[14:17]
	v_mfma_f32_16x16x32_bf16 v[10:13], v[238:241], v[222:225], v[10:13]
	v_mfma_f32_16x16x32_bf16 v[6:9], v[238:241], v[226:229], v[6:9]
	v_mfma_f32_16x16x32_bf16 v[2:5], v[238:241], v[230:233], v[2:5]
	s_branch .LBB0_757
.Lg0_h1_nowrite:
	ds_read_b128 v[174:177], v160 offset:49152
	ds_read_b128 v[180:183], v160 offset:51200
	ds_read_b128 v[184:187], v160 offset:53248
	ds_read_b128 v[188:191], v160 offset:55296
	ds_read_b128 v[168:171], v139 offset:16384
	ds_read_b128 v[192:195], v139 offset:18432
	ds_read_b128 v[234:237], v139 offset:20480
	s_waitcnt lgkmcnt(2)
	v_mfma_f32_16x16x32_bf16 v[62:65], v[168:171], v[174:177], v[62:65]
	v_mfma_f32_16x16x32_bf16 v[58:61], v[168:171], v[180:183], v[58:61]
	v_mfma_f32_16x16x32_bf16 v[54:57], v[168:171], v[184:187], v[54:57]
	v_mfma_f32_16x16x32_bf16 v[50:53], v[168:171], v[188:191], v[50:53]
	ds_read_b128 v[238:241], v139 offset:22528
	s_waitcnt lgkmcnt(2)
	v_mfma_f32_16x16x32_bf16 v[46:49], v[192:195], v[174:177], v[46:49]
	v_mfma_f32_16x16x32_bf16 v[42:45], v[192:195], v[180:183], v[42:45]
	v_mfma_f32_16x16x32_bf16 v[38:41], v[192:195], v[184:187], v[38:41]
	v_mfma_f32_16x16x32_bf16 v[34:37], v[192:195], v[188:191], v[34:37]
	ds_read_b128 v[218:221], v163 offset:49152
	ds_read_b128 v[222:225], v163 offset:51200
	s_waitcnt lgkmcnt(3)
	v_mfma_f32_16x16x32_bf16 v[30:33], v[234:237], v[174:177], v[30:33]
	v_mfma_f32_16x16x32_bf16 v[26:29], v[234:237], v[180:183], v[26:29]
	v_mfma_f32_16x16x32_bf16 v[22:25], v[234:237], v[184:187], v[22:25]
	v_mfma_f32_16x16x32_bf16 v[18:21], v[234:237], v[188:191], v[18:21]
	ds_read_b128 v[226:229], v163 offset:53248
	ds_read_b128 v[230:233], v163 offset:55296
	ds_read_b128 v[168:171], v162 offset:16384
	s_waitcnt lgkmcnt(5)
	v_mfma_f32_16x16x32_bf16 v[14:17], v[238:241], v[174:177], v[14:17]
	v_mfma_f32_16x16x32_bf16 v[10:13], v[238:241], v[180:183], v[10:13]
	v_mfma_f32_16x16x32_bf16 v[6:9], v[238:241], v[184:187], v[6:9]
	v_mfma_f32_16x16x32_bf16 v[2:5], v[238:241], v[188:191], v[2:5]
	ds_read_b128 v[192:195], v162 offset:18432
	s_waitcnt lgkmcnt(1)
	v_mfma_f32_16x16x32_bf16 v[62:65], v[168:171], v[218:221], v[62:65]
	v_mfma_f32_16x16x32_bf16 v[58:61], v[168:171], v[222:225], v[58:61]
	v_mfma_f32_16x16x32_bf16 v[54:57], v[168:171], v[226:229], v[54:57]
	v_mfma_f32_16x16x32_bf16 v[50:53], v[168:171], v[230:233], v[50:53]
	ds_read_b128 v[234:237], v162 offset:20480
	s_waitcnt lgkmcnt(1)
	v_mfma_f32_16x16x32_bf16 v[46:49], v[192:195], v[218:221], v[46:49]
	v_mfma_f32_16x16x32_bf16 v[42:45], v[192:195], v[222:225], v[42:45]
	v_mfma_f32_16x16x32_bf16 v[38:41], v[192:195], v[226:229], v[38:41]
	v_mfma_f32_16x16x32_bf16 v[34:37], v[192:195], v[230:233], v[34:37]
	ds_read_b128 v[238:241], v162 offset:22528
	s_waitcnt lgkmcnt(0)
	s_barrier
	v_mfma_f32_16x16x32_bf16 v[30:33], v[234:237], v[218:221], v[30:33]
	v_mfma_f32_16x16x32_bf16 v[26:29], v[234:237], v[222:225], v[26:29]
	v_mfma_f32_16x16x32_bf16 v[22:25], v[234:237], v[226:229], v[22:25]
	v_mfma_f32_16x16x32_bf16 v[18:21], v[234:237], v[230:233], v[18:21]
	v_mfma_f32_16x16x32_bf16 v[14:17], v[238:241], v[218:221], v[14:17]
	v_mfma_f32_16x16x32_bf16 v[10:13], v[238:241], v[222:225], v[10:13]
	v_mfma_f32_16x16x32_bf16 v[6:9], v[238:241], v[226:229], v[6:9]
	v_mfma_f32_16x16x32_bf16 v[2:5], v[238:241], v[230:233], v[2:5]
	s_branch .LBB0_757

.LBB0_929:
	s_and_b32 s88, s27, 0x7fffff00
	s_add_i32 s2, s1, 0xffffb400
	v_readlane_b32 s52, v253, 4
	s_and_b32 s8, s2, 0x7f0
	s_lshl_b64 s[14:15], s[88:89], 2
	v_readlane_b32 s58, v253, 10
	v_mov_b32_e32 v16, v0
	v_readlane_b32 s59, v253, 11
	s_add_u32 s14, s58, s14
	s_movk_i32 s2, 0x100
	v_ashrrev_i32_e32 v17, 31, v16
	s_addc_u32 s15, s59, s15
	v_cmp_gt_i32_e64 s[2:3], s2, v16
	v_lshl_add_u64 v[18:19], v[16:17], 2, s[14:15]
	s_waitcnt vmcnt(0)
	v_mov_b32_e32 v82, 1.0
	v_mov_b32_e32 v83, 1.0
	v_mov_b32_e32 v84, 1.0
	v_mov_b32_e32 v85, 1.0
	v_mov_b32_e32 v86, 1.0
	v_mov_b32_e32 v87, 1.0
	v_mov_b32_e32 v88, 1.0
	v_mov_b32_e32 v89, 1.0
	v_mov_b32_e32 v90, 1.0
	v_mov_b32_e32 v91, 1.0
	v_mov_b32_e32 v92, 1.0
	v_mov_b32_e32 v93, 1.0
	v_mov_b32_e32 v94, 1.0
	v_mov_b32_e32 v95, 1.0
	v_mov_b32_e32 v96, 1.0
	v_mov_b32_e32 v97, 1.0
	v_mov_b32_e32 v2, 0
	v_readlane_b32 s53, v253, 5
	v_readlane_b32 s54, v253, 6
	v_readlane_b32 s55, v253, 7
	v_readlane_b32 s56, v253, 8
	v_readlane_b32 s57, v253, 9
	s_and_saveexec_b64 s[14:15], s[2:3]
	s_cbranch_execz .LBB0_931
	s_lshl_b32 s16, s8, 12
	s_mov_b32 s17, s89
	v_lshl_add_u64 v[2:3], v[18:19], 0, s[16:17]
	global_load_dword v2, v[2:3], off
.LBB0_931:
	s_or_b64 exec, exec, s[14:15]
	s_cmpk_lt_u32 s8, 0x400
	s_cselect_b64 s[14:15], -1, 0
	s_and_b64 s[14:15], s[34:35], s[14:15]
	v_readlane_b32 s52, v254, 21
	s_andn2_b64 vcc, exec, s[14:15]
	v_readlane_b32 s53, v254, 22
	v_readlane_b32 s54, v254, 23
	v_readlane_b32 s55, v254, 24
	v_readlane_b32 s56, v254, 25
	v_readlane_b32 s57, v254, 26
	v_readlane_b32 s58, v254, 27
	v_readlane_b32 s59, v254, 28
	v_readlane_b32 s60, v254, 29
	v_readlane_b32 s61, v254, 30
	v_readlane_b32 s64, v254, 33
	v_readlane_b32 s65, v254, 34
	v_readlane_b32 s66, v254, 35
	v_readlane_b32 s67, v254, 36
	v_readlane_b32 s62, v254, 31
	v_readlane_b32 s63, v254, 32
	s_cbranch_vccnz .LBB0_933
	s_lshl_b32 s9, s8, 2
	v_mov_b32_e32 v1, s9
	global_load_dword v82, v1, s[64:65]

.LBB0_935:
	s_or_b64 exec, exec, s[14:15]
	s_cmpk_lt_u32 s8, 0x3ff
	s_cselect_b64 s[14:15], -1, 0
	s_and_b64 s[14:15], s[34:35], s[14:15]
	s_andn2_b64 vcc, exec, s[14:15]
	s_cbranch_vccnz .LBB0_937
	s_lshl_b32 s9, s8, 2
	v_mov_b32_e32 v1, s9
	global_load_dword v83, v1, s[64:65] offset:4

.LBB0_939:
	s_or_b64 exec, exec, s[14:15]
	s_cmpk_lt_u32 s8, 0x3fe
	s_cselect_b64 s[14:15], -1, 0
	s_and_b64 s[14:15], s[34:35], s[14:15]
	s_andn2_b64 vcc, exec, s[14:15]
	s_cbranch_vccnz .LBB0_941
	s_lshl_b32 s9, s8, 2
	v_mov_b32_e32 v1, s9
	global_load_dword v84, v1, s[64:65] offset:8

.LBB0_943:
	s_or_b64 exec, exec, s[14:15]
	s_cmpk_lt_u32 s8, 0x3fd
	s_cselect_b64 s[14:15], -1, 0
	s_and_b64 s[14:15], s[34:35], s[14:15]
	s_andn2_b64 vcc, exec, s[14:15]
	s_cbranch_vccnz .LBB0_945
	s_lshl_b32 s9, s8, 2
	v_mov_b32_e32 v1, s9
	global_load_dword v85, v1, s[64:65] offset:12

.LBB0_947:
	s_or_b64 exec, exec, s[14:15]
	s_cmpk_lt_u32 s8, 0x3fc
	s_cselect_b64 s[14:15], -1, 0
	s_and_b64 s[14:15], s[34:35], s[14:15]
	s_andn2_b64 vcc, exec, s[14:15]
	s_cbranch_vccnz .LBB0_949
	s_lshl_b32 s9, s8, 2
	v_mov_b32_e32 v1, s9
	global_load_dword v86, v1, s[64:65] offset:16

.LBB0_951:
	s_or_b64 exec, exec, s[14:15]
	s_cmpk_lt_u32 s8, 0x3fb
	s_cselect_b64 s[14:15], -1, 0
	s_and_b64 s[14:15], s[34:35], s[14:15]
	s_andn2_b64 vcc, exec, s[14:15]
	s_cbranch_vccnz .LBB0_953
	s_lshl_b32 s9, s8, 2
	v_mov_b32_e32 v1, s9
	global_load_dword v87, v1, s[64:65] offset:20

.LBB0_955:
	s_or_b64 exec, exec, s[14:15]
	s_cmpk_lt_u32 s8, 0x3fa
	s_cselect_b64 s[14:15], -1, 0
	s_and_b64 s[14:15], s[34:35], s[14:15]
	s_andn2_b64 vcc, exec, s[14:15]
	s_cbranch_vccnz .LBB0_957
	s_lshl_b32 s9, s8, 2
	v_mov_b32_e32 v1, s9
	global_load_dword v88, v1, s[64:65] offset:24

.LBB0_959:
	s_or_b64 exec, exec, s[14:15]
	s_cmpk_lt_u32 s8, 0x3f9
	s_cselect_b64 s[14:15], -1, 0
	s_and_b64 s[14:15], s[34:35], s[14:15]
	s_andn2_b64 vcc, exec, s[14:15]
	s_cbranch_vccnz .LBB0_961
	s_lshl_b32 s9, s8, 2
	v_mov_b32_e32 v1, s9
	global_load_dword v89, v1, s[64:65] offset:28

.LBB0_963:
	s_or_b64 exec, exec, s[14:15]
	s_cmpk_lt_u32 s8, 0x3f8
	s_cselect_b64 s[14:15], -1, 0
	s_and_b64 s[14:15], s[34:35], s[14:15]
	s_andn2_b64 vcc, exec, s[14:15]
	s_cbranch_vccnz .LBB0_965
	s_lshl_b32 s9, s8, 2
	v_mov_b32_e32 v1, s9
	global_load_dword v90, v1, s[64:65] offset:32

.LBB0_967:
	s_or_b64 exec, exec, s[14:15]
	s_cmpk_lt_u32 s8, 0x3f7
	s_cselect_b64 s[14:15], -1, 0
	s_and_b64 s[14:15], s[34:35], s[14:15]
	s_andn2_b64 vcc, exec, s[14:15]
	s_cbranch_vccnz .LBB0_969
	s_lshl_b32 s9, s8, 2
	v_mov_b32_e32 v1, s9
	global_load_dword v91, v1, s[64:65] offset:36

.LBB0_971:
	s_or_b64 exec, exec, s[14:15]
	s_cmpk_lt_u32 s8, 0x3f6
	s_cselect_b64 s[14:15], -1, 0
	s_and_b64 s[14:15], s[34:35], s[14:15]
	s_andn2_b64 vcc, exec, s[14:15]
	s_cbranch_vccnz .LBB0_973
	s_lshl_b32 s9, s8, 2
	v_mov_b32_e32 v1, s9
	global_load_dword v92, v1, s[64:65] offset:40

.LBB0_975:
	s_or_b64 exec, exec, s[14:15]
	s_cmpk_lt_u32 s8, 0x3f5
	s_cselect_b64 s[14:15], -1, 0
	s_and_b64 s[14:15], s[34:35], s[14:15]
	s_andn2_b64 vcc, exec, s[14:15]
	s_cbranch_vccnz .LBB0_977
	s_lshl_b32 s9, s8, 2
	v_mov_b32_e32 v1, s9
	global_load_dword v93, v1, s[64:65] offset:44

.LBB0_979:
	s_or_b64 exec, exec, s[14:15]
	s_cmpk_lt_u32 s8, 0x3f4
	s_cselect_b64 s[14:15], -1, 0
	s_and_b64 s[14:15], s[34:35], s[14:15]
	s_andn2_b64 vcc, exec, s[14:15]
	s_cbranch_vccnz .LBB0_981
	s_lshl_b32 s9, s8, 2
	v_mov_b32_e32 v1, s9
	global_load_dword v94, v1, s[64:65] offset:48

.LBB0_983:
	s_or_b64 exec, exec, s[14:15]
	s_cmpk_lt_u32 s8, 0x3f3
	s_cselect_b64 s[14:15], -1, 0
	s_and_b64 s[14:15], s[34:35], s[14:15]
	s_andn2_b64 vcc, exec, s[14:15]
	s_cbranch_vccnz .LBB0_985
	s_lshl_b32 s9, s8, 2
	v_mov_b32_e32 v1, s9
	global_load_dword v95, v1, s[64:65] offset:52

.LBB0_987:
	s_or_b64 exec, exec, s[14:15]
	s_cmpk_lt_u32 s8, 0x3f2
	s_cselect_b64 s[14:15], -1, 0
	s_and_b64 s[14:15], s[34:35], s[14:15]
	s_andn2_b64 vcc, exec, s[14:15]
	s_cbranch_vccnz .LBB0_989
	s_lshl_b32 s9, s8, 2
	v_mov_b32_e32 v1, s9
	global_load_dword v96, v1, s[64:65] offset:56

.LBB0_991:
	s_or_b64 exec, exec, s[14:15]
	s_cmpk_lt_u32 s8, 0x3f1
	s_cselect_b64 s[2:3], -1, 0
	s_and_b64 s[2:3], s[34:35], s[2:3]
	s_andn2_b64 vcc, exec, s[2:3]
	s_cbranch_vccnz .LBB0_993
	s_lshl_b32 s2, s8, 2
	v_mov_b32_e32 v1, s2
	global_load_dword v97, v1, s[64:65] offset:60
.LBB0_993:
	s_waitcnt vmcnt(0)
	v_mul_f32_e32 v2, v2, v82
	v_mul_f32_e32 v3, v3, v83
	v_mul_f32_e32 v4, v4, v84
	v_mul_f32_e32 v5, v5, v85
	v_mul_f32_e32 v6, v6, v86
	v_mul_f32_e32 v7, v7, v87
	v_mul_f32_e32 v8, v8, v88
	v_mul_f32_e32 v9, v9, v89
	v_mul_f32_e32 v10, v10, v90
	v_mul_f32_e32 v11, v11, v91
	v_mul_f32_e32 v12, v12, v92
	v_mul_f32_e32 v13, v13, v93
	v_mul_f32_e32 v14, v14, v94
	v_mul_f32_e32 v15, v15, v95
	v_mul_f32_e32 v20, v20, v96
	v_mul_f32_e32 v21, v21, v97
	v_add_u32_e32 v16, s88, v16
	s_movk_i32 s2, 0x400
	v_cmp_gt_i32_e32 vcc, s2, v16
	s_and_saveexec_b64 s[2:3], vcc
	s_xor_b64 s[2:3], exec, s[2:3]
	s_or_b64 s[10:11], s[10:11], exec
	s_or_b64 exec, exec, s[2:3]
	v_readlane_b32 s14, v253, 35
	s_mov_b64 s[2:3], 12
	v_readlane_b32 s15, v253, 36
	s_branch .LBB0_1031
